# GEMM K-loops: dynamic priority with the memory-slot wave high (s_setprio 1 at each memory slot, 0 at each MFMA cluster) on top of static prio
# baseline (speedup 1.0000x reference)
; #define PG8_STAGE(bufoff, gbase, voff) do { _Pragma("unroll") for (int _i = 0; _i < 2; ++_i) \
;         __builtin_amdgcn_global_load_lds((const unsigned*)((const char*)(gbase) + (voff)[_i]), (PG8_LAS unsigned*)(lds + (bufoff) + ldsw + _i * 8192), 16, 0, 0); } while (0)
; #define PG8_LDA(dst, b, h) do { _Pragma("unroll") for (int m = 0; m < 4; ++m) _Pragma("unroll") for (int k = 0; k < 2; ++k) dst[m][k] = *(const PG8_LAS bf16x8*)(lds + PG8_SA(b, h) + aoff + m * 2048 + k * 1024); } while (0)
; #define PG8_LDB(dst, b, h) do { _Pragma("unroll") for (int n = 0; n < 2; ++n) _Pragma("unroll") for (int k = 0; k < 2; ++k) dst[n][k] = *(const PG8_LAS bf16x8*)(lds + PG8_SB(b, h) + boff + n * 2048 + k * 1024); } while (0)
; #define PG8_MMA(ai, bj, At, Bt) do { __builtin_amdgcn_s_setprio(1); _Pragma("unroll") for (int m = 0; m < 4; ++m) _Pragma("unroll") for (int n = 0; n < 2; ++n) _Pragma("unroll") for (int k = 0; k < 2; ++k) \
;         acc[ai][bj][m][n] = __builtin_amdgcn_mfma_f32_16x16x32_bf16(Bt[n][k], At[m][k], acc[ai][bj][m][n], 0, 0, 0); __builtin_amdgcn_s_setprio(0); } while (0)
; #define PG8_WAIT_V(n) asm volatile("s_waitcnt vmcnt(" #n ")" ::: "memory")
; #define PG8_WAIT_L(n) asm volatile("s_waitcnt lgkmcnt(" #n ")" ::: "memory")
; #define PG8_BAR __builtin_amdgcn_s_barrier()
; #define PG8_SCHED __builtin_amdgcn_sched_barrier(0)
; template <class Epi, class Sched>
; __device__ __forceinline__ void gemm_phase(PG8_LAS unsigned char* lds, const Gemm g, const Sched& S, const Epi& E) {
;     ...
;             PG8_LDB(B0, 0, 0); PG8_SCHED; PG8_LDA(At, 0, 0); PG8_STAGE(PG8_SA(1, 1), a1 + hstep, voffA);
;             PG8_WAIT_L(8); PG8_BAR; PG8_WAIT_L(0); PG8_MMA(0, 0, At, B0); PG8_BAR; PG8_SCHED;
;             PG8_LDB(B1, 0, 1); PG8_STAGE(PG8_SB(0, 0), b2, voffB);
;             PG8_BAR; PG8_WAIT_L(0); PG8_MMA(0, 1, At, B1); PG8_BAR;
;             PG8_LDA(At, 0, 1); PG8_STAGE(PG8_SA(0, 0), a2, voffA);
;             PG8_BAR; PG8_WAIT_L(0); PG8_MMA(1, 0, At, B0); PG8_BAR; PG8_SCHED;
;             PG8_STAGE(PG8_SB(0, 1), b2 + hstep, voffB);
;             PG8_WAIT_V(6); PG8_BAR; PG8_MMA(1, 1, At, B1); PG8_BAR;
;             PG8_LDB(B0, 1, 0); PG8_SCHED; PG8_LDA(At, 1, 0); PG8_STAGE(PG8_SA(0, 1), a2 + hstep, voffA);
;             PG8_WAIT_L(8); PG8_BAR; PG8_WAIT_L(0); PG8_MMA(0, 0, At, B0); PG8_BAR; PG8_SCHED;
.Lgp_1873:
.LBB0_47:
	s_setprio 1
	s_add_u32 s52, s50, 0x100
	s_addc_u32 s53, s51, 0
	s_add_i32 s42, 0, 0x10000
	v_add_u32_e32 v134, s42, v225
	ds_read_b128 v[118:121], v134
	ds_read_b128 v[126:129], v134 offset:1024
	ds_read_b128 v[130:133], v134 offset:2048
	ds_read_b128 v[134:137], v134 offset:3072
	s_cmp_eq_u32 s94, 60
	s_cselect_b32 s1, s41, s53
	s_cselect_b32 s0, s68, s52
	s_cselect_b32 vcc_hi, s39, s71
	s_cselect_b32 vcc_lo, s69, s70
	v_lshl_add_u64 v[178:179], s[50:51], 0, v[210:211]
	s_add_i32 m0, s49, 0xc000
	ds_read_b128 v[146:149], v240
	ds_read_b128 v[150:153], v240 offset:1024
	ds_read_b128 v[154:157], v240 offset:2048
	ds_read_b128 v[158:161], v240 offset:3072
	ds_read_b128 v[162:165], v240 offset:4096
	ds_read_b128 v[166:169], v240 offset:5120
	ds_read_b128 v[170:173], v240 offset:6144
	ds_read_b128 v[174:177], v240 offset:7168
	global_load_lds_dwordx4 v[178:179], off
	v_lshl_add_u64 v[178:179], s[50:51], 0, v[212:213]
	s_add_i32 m0, s49, 0xe000
	s_nop 0
	global_load_lds_dwordx4 v[178:179], off
	s_waitcnt lgkmcnt(8)
	s_barrier
	s_setprio 0
	s_waitcnt lgkmcnt(0)
	v_mfma_f32_16x16x32_bf16 v[142:145], v[118:121], v[146:149], v[142:145]
	v_mfma_f32_16x16x32_bf16 v[138:141], v[130:133], v[146:149], v[138:141]
	v_mfma_f32_16x16x32_bf16 v[114:117], v[118:121], v[154:157], v[114:117]
	v_mfma_f32_16x16x32_bf16 v[106:109], v[130:133], v[154:157], v[106:109]
	v_mfma_f32_16x16x32_bf16 v[102:105], v[118:121], v[162:165], v[102:105]
	v_mfma_f32_16x16x32_bf16 v[92:95], v[130:133], v[162:165], v[92:95]
	v_mfma_f32_16x16x32_bf16 v[84:87], v[118:121], v[170:173], v[84:87]
	v_mfma_f32_16x16x32_bf16 v[76:79], v[130:133], v[170:173], v[76:79]
	v_mfma_f32_16x16x32_bf16 v[142:145], v[126:129], v[150:153], v[142:145]
	v_mfma_f32_16x16x32_bf16 v[138:141], v[134:137], v[150:153], v[138:141]
	v_mfma_f32_16x16x32_bf16 v[114:117], v[126:129], v[158:161], v[114:117]
	v_mfma_f32_16x16x32_bf16 v[106:109], v[134:137], v[158:161], v[106:109]
	v_mfma_f32_16x16x32_bf16 v[102:105], v[126:129], v[166:169], v[102:105]
	v_mfma_f32_16x16x32_bf16 v[92:95], v[134:137], v[166:169], v[92:95]
	v_mfma_f32_16x16x32_bf16 v[84:87], v[126:129], v[174:177], v[84:87]
	v_mfma_f32_16x16x32_bf16 v[76:79], v[134:137], v[174:177], v[76:79]
	s_barrier
	s_setprio 1
	s_add_i32 s43, 0, 0x14000
	s_add_i32 s42, s42, s58
	v_add_u32_e32 v190, s43, v225
	v_lshl_add_u64 v[194:195], vcc, 0, v[96:97]
	s_mov_b32 m0, s42
	ds_read_b128 v[178:181], v190
	ds_read_b128 v[182:185], v190 offset:1024
	ds_read_b128 v[186:189], v190 offset:2048
	ds_read_b128 v[190:193], v190 offset:3072
	global_load_lds_dwordx4 v[194:195], off
	v_lshl_add_u64 v[196:197], vcc, 0, v[208:209]
	s_add_i32 m0, s42, 0x2000
	s_nop 0
	global_load_lds_dwordx4 v[196:197], off
	s_barrier
	s_setprio 0
	s_waitcnt lgkmcnt(0)
	v_mfma_f32_16x16x32_bf16 v[122:125], v[178:181], v[146:149], v[122:125]
	v_mfma_f32_16x16x32_bf16 v[110:113], v[186:189], v[146:149], v[110:113]
	v_mfma_f32_16x16x32_bf16 v[98:101], v[178:181], v[154:157], v[98:101]
	v_mfma_f32_16x16x32_bf16 v[88:91], v[186:189], v[154:157], v[88:91]
	v_mfma_f32_16x16x32_bf16 v[80:83], v[178:181], v[162:165], v[80:83]
	v_mfma_f32_16x16x32_bf16 v[72:75], v[186:189], v[162:165], v[72:75]
	v_mfma_f32_16x16x32_bf16 v[68:71], v[178:181], v[170:173], v[68:71]
	v_mfma_f32_16x16x32_bf16 v[64:67], v[186:189], v[170:173], v[64:67]
	v_mfma_f32_16x16x32_bf16 v[122:125], v[182:185], v[150:153], v[122:125]
	v_mfma_f32_16x16x32_bf16 v[110:113], v[190:193], v[150:153], v[110:113]
	v_mfma_f32_16x16x32_bf16 v[98:101], v[182:185], v[158:161], v[98:101]
	v_mfma_f32_16x16x32_bf16 v[88:91], v[190:193], v[158:161], v[88:91]
	v_mfma_f32_16x16x32_bf16 v[80:83], v[182:185], v[166:169], v[80:83]
	v_mfma_f32_16x16x32_bf16 v[72:75], v[190:193], v[166:169], v[72:75]
	v_mfma_f32_16x16x32_bf16 v[68:71], v[182:185], v[174:177], v[68:71]
	v_mfma_f32_16x16x32_bf16 v[64:67], v[190:193], v[174:177], v[64:67]
	s_mov_b32 m0, s49
	v_lshl_add_u64 v[198:199], s[0:1], 0, v[96:97]
	s_barrier
	s_setprio 1
	ds_read_b128 v[146:149], v240 offset:16384
	ds_read_b128 v[150:153], v240 offset:17408
	ds_read_b128 v[154:157], v240 offset:18432
	ds_read_b128 v[158:161], v240 offset:19456
	ds_read_b128 v[162:165], v240 offset:20480
	ds_read_b128 v[166:169], v240 offset:21504
	ds_read_b128 v[170:173], v240 offset:22528
	ds_read_b128 v[174:177], v240 offset:23552
	global_load_lds_dwordx4 v[198:199], off
	v_lshl_add_u64 v[200:201], s[0:1], 0, v[208:209]
	s_mov_b32 m0, s61
	s_nop 0
	global_load_lds_dwordx4 v[200:201], off
	s_barrier
	s_setprio 0
	s_waitcnt lgkmcnt(0)
	v_mfma_f32_16x16x32_bf16 v[60:63], v[118:121], v[146:149], v[60:63]
	v_mfma_f32_16x16x32_bf16 v[56:59], v[130:133], v[146:149], v[56:59]
	v_mfma_f32_16x16x32_bf16 v[52:55], v[118:121], v[154:157], v[52:55]
	v_mfma_f32_16x16x32_bf16 v[44:47], v[130:133], v[154:157], v[44:47]
	v_mfma_f32_16x16x32_bf16 v[36:39], v[118:121], v[162:165], v[36:39]
	v_mfma_f32_16x16x32_bf16 v[28:31], v[130:133], v[162:165], v[28:31]
	v_mfma_f32_16x16x32_bf16 v[20:23], v[118:121], v[170:173], v[20:23]
	v_mfma_f32_16x16x32_bf16 v[12:15], v[130:133], v[170:173], v[12:15]
	v_mfma_f32_16x16x32_bf16 v[60:63], v[126:129], v[150:153], v[60:63]
	v_mfma_f32_16x16x32_bf16 v[56:59], v[134:137], v[150:153], v[56:59]
	v_mfma_f32_16x16x32_bf16 v[52:55], v[126:129], v[158:161], v[52:55]
	v_mfma_f32_16x16x32_bf16 v[44:47], v[134:137], v[158:161], v[44:47]
	v_mfma_f32_16x16x32_bf16 v[36:39], v[126:129], v[166:169], v[36:39]
	v_mfma_f32_16x16x32_bf16 v[28:31], v[134:137], v[166:169], v[28:31]
	v_mfma_f32_16x16x32_bf16 v[20:23], v[126:129], v[174:177], v[20:23]
	v_mfma_f32_16x16x32_bf16 v[12:15], v[134:137], v[174:177], v[12:15]
	s_barrier
; #define PG8_STAGE(bufoff, gbase, voff) do { _Pragma("unroll") for (int _i = 0; _i < 2; ++_i) \
;         __builtin_amdgcn_global_load_lds((const unsigned*)((const char*)(gbase) + (voff)[_i]), (PG8_LAS unsigned*)(lds + (bufoff) + ldsw + _i * 8192), 16, 0, 0); } while (0)
; #define PG8_LDA(dst, b, h) do { _Pragma("unroll") for (int m = 0; m < 4; ++m) _Pragma("unroll") for (int k = 0; k < 2; ++k) dst[m][k] = *(const PG8_LAS bf16x8*)(lds + PG8_SA(b, h) + aoff + m * 2048 + k * 1024); } while (0)
; #define PG8_LDB(dst, b, h) do { _Pragma("unroll") for (int n = 0; n < 2; ++n) _Pragma("unroll") for (int k = 0; k < 2; ++k) dst[n][k] = *(const PG8_LAS bf16x8*)(lds + PG8_SB(b, h) + boff + n * 2048 + k * 1024); } while (0)
; #define PG8_MMA(ai, bj, At, Bt) do { __builtin_amdgcn_s_setprio(1); _Pragma("unroll") for (int m = 0; m < 4; ++m) _Pragma("unroll") for (int n = 0; n < 2; ++n) _Pragma("unroll") for (int k = 0; k < 2; ++k) \
;         acc[ai][bj][m][n] = __builtin_amdgcn_mfma_f32_16x16x32_bf16(Bt[n][k], At[m][k], acc[ai][bj][m][n], 0, 0, 0); __builtin_amdgcn_s_setprio(0); } while (0)
; #define PG8_WAIT_V(n) asm volatile("s_waitcnt vmcnt(" #n ")" ::: "memory")
; #define PG8_WAIT_L(n) asm volatile("s_waitcnt lgkmcnt(" #n ")" ::: "memory")
; #define PG8_BAR __builtin_amdgcn_s_barrier()
; #define PG8_SCHED __builtin_amdgcn_sched_barrier(0)
; template <class Epi, class Sched>
; __device__ __forceinline__ void gemm_phase(PG8_LAS unsigned char* lds, const Gemm g, const Sched& S, const Epi& E) {
;     ...
;             PG8_STAGE(PG8_SB(0, 1), b2 + hstep, voffB);
;             PG8_WAIT_V(6); PG8_BAR; PG8_MMA(1, 1, At, B1); PG8_BAR;
;             PG8_LDB(B0, 1, 0); PG8_SCHED; PG8_LDA(At, 1, 0); PG8_STAGE(PG8_SA(0, 1), a2 + hstep, voffA);
;             PG8_WAIT_L(8); PG8_BAR; PG8_WAIT_L(0); PG8_MMA(0, 0, At, B0); PG8_BAR; PG8_SCHED;
;             PG8_LDB(B1, 1, 1); PG8_STAGE(PG8_SB(1, 0), b3, voffB);
;             PG8_BAR; PG8_WAIT_L(0); PG8_MMA(0, 1, At, B1); PG8_BAR;
;             PG8_LDA(At, 1, 1); PG8_STAGE(PG8_SA(1, 0), a3, voffA);
;             PG8_BAR; PG8_WAIT_L(0); PG8_MMA(1, 0, At, B0); PG8_BAR; PG8_SCHED;
	s_setprio 1
	s_add_u32 s50, vcc_lo, 0x100000
	s_addc_u32 s51, vcc_hi, 0
	s_add_i32 s42, s43, s58
	v_lshl_add_u64 v[118:119], s[50:51], 0, v[96:97]
	s_mov_b32 m0, s42
	s_nop 0
	global_load_lds_dwordx4 v[118:119], off
	v_lshl_add_u64 v[118:119], s[50:51], 0, v[208:209]
	s_add_i32 m0, s42, 0x2000
	s_nop 0
	global_load_lds_dwordx4 v[118:119], off
	s_waitcnt vmcnt(6)
	s_barrier
	s_setprio 0
	v_mfma_f32_16x16x32_bf16 v[48:51], v[178:181], v[146:149], v[48:51]
	v_mfma_f32_16x16x32_bf16 v[40:43], v[186:189], v[146:149], v[40:43]
	v_mfma_f32_16x16x32_bf16 v[32:35], v[178:181], v[154:157], v[32:35]
	v_mfma_f32_16x16x32_bf16 v[24:27], v[186:189], v[154:157], v[24:27]
	v_mfma_f32_16x16x32_bf16 v[16:19], v[178:181], v[162:165], v[16:19]
	v_mfma_f32_16x16x32_bf16 v[8:11], v[186:189], v[162:165], v[8:11]
	v_mfma_f32_16x16x32_bf16 v[4:7], v[178:181], v[170:173], v[4:7]
	v_mfma_f32_16x16x32_bf16 v[0:3], v[186:189], v[170:173], v[0:3]
	v_mfma_f32_16x16x32_bf16 v[48:51], v[182:185], v[150:153], v[48:51]
	v_mfma_f32_16x16x32_bf16 v[40:43], v[190:193], v[150:153], v[40:43]
	v_mfma_f32_16x16x32_bf16 v[32:35], v[182:185], v[158:161], v[32:35]
	v_mfma_f32_16x16x32_bf16 v[24:27], v[190:193], v[158:161], v[24:27]
	v_mfma_f32_16x16x32_bf16 v[16:19], v[182:185], v[166:169], v[16:19]
	v_mfma_f32_16x16x32_bf16 v[8:11], v[190:193], v[166:169], v[8:11]
	v_mfma_f32_16x16x32_bf16 v[4:7], v[182:185], v[174:177], v[4:7]
	v_mfma_f32_16x16x32_bf16 v[0:3], v[190:193], v[174:177], v[0:3]
	s_add_i32 s42, 0, 0x18000
	v_add_u32_e32 v134, s42, v225
	s_barrier
	s_setprio 1
	ds_read_b128 v[118:121], v134
	ds_read_b128 v[126:129], v134 offset:1024
	ds_read_b128 v[130:133], v134 offset:2048
	ds_read_b128 v[134:137], v134 offset:3072
	s_add_u32 s0, s0, 0x100000
	s_addc_u32 s1, s1, 0
	s_mov_b32 m0, s62
	v_lshl_add_u64 v[178:179], s[0:1], 0, v[96:97]
	ds_read_b128 v[146:149], v240 offset:32768
	ds_read_b128 v[150:153], v240 offset:33792
	ds_read_b128 v[154:157], v240 offset:34816
	ds_read_b128 v[158:161], v240 offset:35840
	ds_read_b128 v[162:165], v240 offset:36864
	ds_read_b128 v[166:169], v240 offset:37888
	ds_read_b128 v[170:173], v240 offset:38912
	ds_read_b128 v[174:177], v240 offset:39936
	global_load_lds_dwordx4 v[178:179], off
	v_lshl_add_u64 v[178:179], s[0:1], 0, v[208:209]
	s_mov_b32 m0, s63
	s_nop 0
	global_load_lds_dwordx4 v[178:179], off
	s_waitcnt lgkmcnt(8)
	s_barrier
	s_setprio 0
	s_waitcnt lgkmcnt(0)
	v_mfma_f32_16x16x32_bf16 v[142:145], v[118:121], v[146:149], v[142:145]
	v_mfma_f32_16x16x32_bf16 v[138:141], v[130:133], v[146:149], v[138:141]
	v_mfma_f32_16x16x32_bf16 v[114:117], v[118:121], v[154:157], v[114:117]
	v_mfma_f32_16x16x32_bf16 v[106:109], v[130:133], v[154:157], v[106:109]
	v_mfma_f32_16x16x32_bf16 v[102:105], v[118:121], v[162:165], v[102:105]
	v_mfma_f32_16x16x32_bf16 v[92:95], v[130:133], v[162:165], v[92:95]
	v_mfma_f32_16x16x32_bf16 v[84:87], v[118:121], v[170:173], v[84:87]
	v_mfma_f32_16x16x32_bf16 v[76:79], v[130:133], v[170:173], v[76:79]
	v_mfma_f32_16x16x32_bf16 v[142:145], v[126:129], v[150:153], v[142:145]
	v_mfma_f32_16x16x32_bf16 v[138:141], v[134:137], v[150:153], v[138:141]
	v_mfma_f32_16x16x32_bf16 v[114:117], v[126:129], v[158:161], v[114:117]
	v_mfma_f32_16x16x32_bf16 v[106:109], v[134:137], v[158:161], v[106:109]
	v_mfma_f32_16x16x32_bf16 v[102:105], v[126:129], v[166:169], v[102:105]
	v_mfma_f32_16x16x32_bf16 v[92:95], v[134:137], v[166:169], v[92:95]
	v_mfma_f32_16x16x32_bf16 v[84:87], v[126:129], v[174:177], v[84:87]
	v_mfma_f32_16x16x32_bf16 v[76:79], v[134:137], v[174:177], v[76:79]
	s_barrier
	s_setprio 1
	s_add_i32 s43, 0, 0x1c000
	s_add_i32 s0, s42, s58
	v_add_u32_e32 v190, s43, v225
	v_lshl_add_u64 v[194:195], v[194:195], 0, s[2:3]
	s_mov_b32 m0, s0
	ds_read_b128 v[178:181], v190
	ds_read_b128 v[182:185], v190 offset:1024
	ds_read_b128 v[186:189], v190 offset:2048
	ds_read_b128 v[190:193], v190 offset:3072
	global_load_lds_dwordx4 v[194:195], off
	v_lshl_add_u64 v[194:195], v[196:197], 0, s[2:3]
	s_add_i32 m0, s0, 0x2000
	s_nop 0
	global_load_lds_dwordx4 v[194:195], off
	s_barrier
	s_setprio 0
	s_waitcnt lgkmcnt(0)
	v_mfma_f32_16x16x32_bf16 v[122:125], v[178:181], v[146:149], v[122:125]
	v_mfma_f32_16x16x32_bf16 v[110:113], v[186:189], v[146:149], v[110:113]
	v_mfma_f32_16x16x32_bf16 v[98:101], v[178:181], v[154:157], v[98:101]
	v_mfma_f32_16x16x32_bf16 v[88:91], v[186:189], v[154:157], v[88:91]
	v_mfma_f32_16x16x32_bf16 v[80:83], v[178:181], v[162:165], v[80:83]
	v_mfma_f32_16x16x32_bf16 v[72:75], v[186:189], v[162:165], v[72:75]
	v_mfma_f32_16x16x32_bf16 v[68:71], v[178:181], v[170:173], v[68:71]
	v_mfma_f32_16x16x32_bf16 v[64:67], v[186:189], v[170:173], v[64:67]
	v_mfma_f32_16x16x32_bf16 v[122:125], v[182:185], v[150:153], v[122:125]
	v_mfma_f32_16x16x32_bf16 v[110:113], v[190:193], v[150:153], v[110:113]
	v_mfma_f32_16x16x32_bf16 v[98:101], v[182:185], v[158:161], v[98:101]
	v_mfma_f32_16x16x32_bf16 v[88:91], v[190:193], v[158:161], v[88:91]
	v_mfma_f32_16x16x32_bf16 v[80:83], v[182:185], v[166:169], v[80:83]
	v_mfma_f32_16x16x32_bf16 v[72:75], v[190:193], v[166:169], v[72:75]
	v_mfma_f32_16x16x32_bf16 v[68:71], v[182:185], v[174:177], v[68:71]
	v_mfma_f32_16x16x32_bf16 v[64:67], v[190:193], v[174:177], v[64:67]
	s_mov_b32 m0, s64
	v_lshl_add_u64 v[194:195], v[198:199], 0, s[2:3]
	s_barrier
	s_setprio 1
	ds_read_b128 v[146:149], v240 offset:49152
	ds_read_b128 v[150:153], v240 offset:50176
	ds_read_b128 v[154:157], v240 offset:51200
	ds_read_b128 v[158:161], v240 offset:52224
	ds_read_b128 v[162:165], v240 offset:53248
	ds_read_b128 v[166:169], v240 offset:54272
	ds_read_b128 v[170:173], v240 offset:55296
	ds_read_b128 v[174:177], v240 offset:56320
	global_load_lds_dwordx4 v[194:195], off
	v_lshl_add_u64 v[194:195], v[200:201], 0, s[2:3]
	s_mov_b32 m0, s65
	s_nop 0
	global_load_lds_dwordx4 v[194:195], off
	s_barrier
; #define PG8_STAGE(bufoff, gbase, voff) do { _Pragma("unroll") for (int _i = 0; _i < 2; ++_i) \
;         __builtin_amdgcn_global_load_lds((const unsigned*)((const char*)(gbase) + (voff)[_i]), (PG8_LAS unsigned*)(lds + (bufoff) + ldsw + _i * 8192), 16, 0, 0); } while (0)
; #define PG8_MMA(ai, bj, At, Bt) do { __builtin_amdgcn_s_setprio(1); _Pragma("unroll") for (int m = 0; m < 4; ++m) _Pragma("unroll") for (int n = 0; n < 2; ++n) _Pragma("unroll") for (int k = 0; k < 2; ++k) \
;         acc[ai][bj][m][n] = __builtin_amdgcn_mfma_f32_16x16x32_bf16(Bt[n][k], At[m][k], acc[ai][bj][m][n], 0, 0, 0); __builtin_amdgcn_s_setprio(0); } while (0)
; #define PG8_WAIT_V(n) asm volatile("s_waitcnt vmcnt(" #n ")" ::: "memory")
; #define PG8_BAR __builtin_amdgcn_s_barrier()
; template <class Epi, class Sched>
; __device__ __forceinline__ void gemm_phase(PG8_LAS unsigned char* lds, const Gemm g, const Sched& S, const Epi& E) {
;     ...
;             PG8_STAGE(PG8_SB(1, 1), b3 + hstep, voffB);
;             PG8_WAIT_V(6); PG8_BAR; PG8_MMA(1, 1, At, B1); PG8_BAR;
;   DEV void operator()(const f32x4 (&acc)[2][2][4][2], const pg8::Unit& u, int wr, int wc, int fr, int fq) const {
;     const int row0 = u.pm * 256 + wr * 64 + fr, col0 = u.pn * 256 + wc * 32 + 4 * fq;
;     const float* gt = mod + (size_t)modrow(row0) * 6144;
;     f32x4 g4[2][2];
; #pragma unroll
;     for (int bj = 0; bj < 2; ++bj)
; #pragma unroll
;       for (int n = 0; n < 2; ++n) g4[bj][n] = *(const f32x4*)(gt + col0 + bj * 128 + n * 16);
; #pragma unroll
;     for (int ai = 0; ai < 2; ++ai) {
;       f32x4 xv[4][2][2];
; #pragma unroll
;       for (int m = 0; m < 4; ++m) {
;         const int row = row0 + ai * 128 + m * 16;
;         const float* xi = row < T_LAT ? rin_lat + (size_t)row * DM : rin_ctx + (size_t)(row - T_LAT) * DM;
; #pragma unroll
;         for (int bj = 0; bj < 2; ++bj)
; #pragma unroll
;           for (int n = 0; n < 2; ++n) xv[m][bj][n] = *(const f32x4*)(xi + col0 + bj * 128 + n * 16);
	s_setprio 0
	s_waitcnt lgkmcnt(0)
	v_mfma_f32_16x16x32_bf16 v[60:63], v[118:121], v[146:149], v[60:63]
	v_mfma_f32_16x16x32_bf16 v[56:59], v[130:133], v[146:149], v[56:59]
	v_mfma_f32_16x16x32_bf16 v[52:55], v[118:121], v[154:157], v[52:55]
	v_mfma_f32_16x16x32_bf16 v[44:47], v[130:133], v[154:157], v[44:47]
	v_mfma_f32_16x16x32_bf16 v[36:39], v[118:121], v[162:165], v[36:39]
	v_mfma_f32_16x16x32_bf16 v[28:31], v[130:133], v[162:165], v[28:31]
	v_mfma_f32_16x16x32_bf16 v[20:23], v[118:121], v[170:173], v[20:23]
	v_mfma_f32_16x16x32_bf16 v[12:15], v[130:133], v[170:173], v[12:15]
	v_mfma_f32_16x16x32_bf16 v[60:63], v[126:129], v[150:153], v[60:63]
	v_mfma_f32_16x16x32_bf16 v[56:59], v[134:137], v[150:153], v[56:59]
	v_mfma_f32_16x16x32_bf16 v[52:55], v[126:129], v[158:161], v[52:55]
	v_mfma_f32_16x16x32_bf16 v[44:47], v[134:137], v[158:161], v[44:47]
	v_mfma_f32_16x16x32_bf16 v[36:39], v[126:129], v[166:169], v[36:39]
	v_mfma_f32_16x16x32_bf16 v[28:31], v[134:137], v[166:169], v[28:31]
	v_mfma_f32_16x16x32_bf16 v[20:23], v[126:129], v[174:177], v[20:23]
	v_mfma_f32_16x16x32_bf16 v[12:15], v[134:137], v[174:177], v[12:15]
	s_barrier
	s_setprio 1
	s_add_u32 s0, vcc_lo, 0x100080
	s_addc_u32 s1, vcc_hi, 0
	s_add_i32 s42, s43, s58
	v_lshl_add_u64 v[118:119], s[0:1], 0, v[96:97]
	s_mov_b32 m0, s42
	s_nop 0
	global_load_lds_dwordx4 v[118:119], off
	v_lshl_add_u64 v[118:119], s[0:1], 0, v[208:209]
	s_add_i32 m0, s42, 0x2000
	s_nop 0
	global_load_lds_dwordx4 v[118:119], off
	s_waitcnt vmcnt(6)
	s_barrier
	s_setprio 0
	v_mfma_f32_16x16x32_bf16 v[48:51], v[178:181], v[146:149], v[48:51]
	v_mfma_f32_16x16x32_bf16 v[40:43], v[186:189], v[146:149], v[40:43]
	v_mfma_f32_16x16x32_bf16 v[32:35], v[178:181], v[154:157], v[32:35]
	v_mfma_f32_16x16x32_bf16 v[24:27], v[186:189], v[154:157], v[24:27]
	v_mfma_f32_16x16x32_bf16 v[16:19], v[178:181], v[162:165], v[16:19]
	v_mfma_f32_16x16x32_bf16 v[8:11], v[186:189], v[162:165], v[8:11]
	v_mfma_f32_16x16x32_bf16 v[4:7], v[178:181], v[170:173], v[4:7]
	v_mfma_f32_16x16x32_bf16 v[0:3], v[186:189], v[170:173], v[0:3]
	v_mfma_f32_16x16x32_bf16 v[48:51], v[182:185], v[150:153], v[48:51]
	v_mfma_f32_16x16x32_bf16 v[40:43], v[190:193], v[150:153], v[40:43]
	v_mfma_f32_16x16x32_bf16 v[32:35], v[182:185], v[158:161], v[32:35]
	v_mfma_f32_16x16x32_bf16 v[24:27], v[190:193], v[158:161], v[24:27]
	v_mfma_f32_16x16x32_bf16 v[16:19], v[182:185], v[166:169], v[16:19]
	v_mfma_f32_16x16x32_bf16 v[8:11], v[190:193], v[166:169], v[8:11]
	v_mfma_f32_16x16x32_bf16 v[4:7], v[182:185], v[174:177], v[4:7]
	v_mfma_f32_16x16x32_bf16 v[0:3], v[190:193], v[174:177], v[0:3]
	s_add_i32 s94, s94, 2
	s_add_u32 s70, s70, 0x100
	s_addc_u32 s71, s71, 0
	s_cmp_gt_u32 s94, 61
	s_mov_b64 s[50:51], s[52:53]
	s_barrier
	s_cbranch_scc0 .LBB0_47
	v_lshl_add_u32 v238, s48, 8, v224
	s_mov_b32 s71, 0x8000
	v_readlane_b32 s0, v251, 52
	v_min_i32_e32 v119, 0x8000, v238
	v_cmp_gt_i32_e32 vcc, s71, v238
	v_add_u32_e32 v146, 0xffff8000, v238
	v_ashrrev_i32_e32 v147, 31, v238
	v_mov_b32_e32 v241, s0
	v_readlane_b32 s0, v251, 51
	v_lshl_or_b32 v118, s67, 8, v239
	v_ashrrev_i32_e32 v119, 12, v119
	v_cndmask_b32_e32 v147, 0, v147, vcc
	v_cndmask_b32_e32 v146, v146, v238, vcc
	v_mov_b32_e32 v242, s73
	v_mov_b32_e32 v243, s0
	v_mov_b32_e32 v244, s72
	v_mul_hi_i32_i24_e32 v121, 0x6000, v119
	v_mul_i32_i24_e32 v120, 0x6000, v119
	v_ashrrev_i32_e32 v119, 31, v118
	v_cndmask_b32_e32 v149, v241, v242, vcc
	v_cndmask_b32_e32 v148, v243, v244, vcc
	v_lshlrev_b64 v[146:147], 12, v[146:147]
	v_lshlrev_b64 v[214:215], 2, v[118:119]
	v_lshl_add_u64 v[146:147], v[148:149], 0, v[146:147]
	v_lshl_add_u64 v[222:223], v[146:147], 0, v[214:215]
	v_or_b32_e32 v146, 16, v238
	v_cmp_gt_i32_e32 vcc, s71, v146
	v_ashrrev_i32_e32 v147, 31, v146
	v_add_u32_e32 v148, 0xffff8010, v238
	v_cndmask_b32_e32 v147, 0, v147, vcc
	v_cndmask_b32_e32 v146, v148, v146, vcc
	v_cndmask_b32_e32 v149, v241, v242, vcc
	v_cndmask_b32_e32 v148, v243, v244, vcc
	v_lshlrev_b64 v[146:147], 12, v[146:147]
	v_lshl_add_u64 v[146:147], v[148:149], 0, v[146:147]
	v_lshl_add_u64 v[220:221], v[146:147], 0, v[214:215]
	v_or_b32_e32 v146, 32, v238
	v_cmp_gt_i32_e32 vcc, s71, v146
	v_ashrrev_i32_e32 v147, 31, v146
	v_add_u32_e32 v148, 0xffff8020, v238
	v_cndmask_b32_e32 v147, 0, v147, vcc
	v_cndmask_b32_e32 v146, v148, v146, vcc
	v_cndmask_b32_e32 v149, v241, v242, vcc
	v_cndmask_b32_e32 v148, v243, v244, vcc
	v_lshlrev_b64 v[146:147], 12, v[146:147]
	v_lshl_add_u64 v[146:147], v[148:149], 0, v[146:147]
	v_lshl_add_u64 v[218:219], v[146:147], 0, v[214:215]
	v_or_b32_e32 v146, 48, v238
	v_cmp_gt_i32_e32 vcc, s71, v146
	v_ashrrev_i32_e32 v147, 31, v146
	v_add_u32_e32 v148, 0xffff8030, v238
	v_cndmask_b32_e32 v147, 0, v147, vcc
	v_cndmask_b32_e32 v146, v148, v146, vcc
	v_cndmask_b32_e32 v149, v241, v242, vcc
	v_cndmask_b32_e32 v148, v243, v244, vcc
	v_lshlrev_b64 v[146:147], 12, v[146:147]
	v_lshl_add_u64 v[120:121], s[30:31], 0, v[120:121]
	v_lshl_add_u64 v[146:147], v[148:149], 0, v[146:147]
	v_lshl_add_u64 v[118:119], v[120:121], 0, v[214:215]
	v_lshl_add_u64 v[216:217], v[146:147], 0, v[214:215]
	global_load_dwordx4 v[134:137], v[118:119], off
	global_load_dwordx4 v[130:133], v[118:119], off offset:64
	global_load_dwordx4 v[126:129], v[118:119], off offset:512
	s_nop 0
	global_load_dwordx4 v[118:121], v[118:119], off offset:576
	s_nop 0
	global_load_dwordx4 v[202:205], v[222:223], off offset:64
	global_load_dwordx4 v[198:201], v[222:223], off offset:512
	global_load_dwordx4 v[194:197], v[222:223], off offset:576
	global_load_dwordx4 v[190:193], v[220:221], off
	global_load_dwordx4 v[186:189], v[220:221], off offset:64
	global_load_dwordx4 v[182:185], v[220:221], off offset:512
	global_load_dwordx4 v[174:177], v[220:221], off offset:576
	global_load_dwordx4 v[178:181], v[218:219], off
	global_load_dwordx4 v[170:173], v[218:219], off offset:64
	global_load_dwordx4 v[166:169], v[218:219], off offset:512
	global_load_dwordx4 v[158:161], v[218:219], off offset:576
	global_load_dwordx4 v[162:165], v[216:217], off
	global_load_dwordx4 v[154:157], v[216:217], off offset:64
	global_load_dwordx4 v[150:153], v[216:217], off offset:512
	global_load_dwordx4 v[146:149], v[216:217], off offset:576
	global_load_dwordx4 v[228:231], v[222:223], off
	s_movk_i32 s0, 0x7f80
	v_cmp_gt_i32_e32 vcc, s0, v238
	s_movk_i32 s0, 0x7f70
	s_mov_b32 s67, s38
	s_mov_b32 s48, s40
	s_mov_b64 s[52:53], s[46:47]
	s_mov_b64 s[50:51], s[44:45]
	s_waitcnt vmcnt(0)
;   DEV void operator()(const f32x4 (&acc)[2][2][4][2], const pg8::Unit& u, int wr, int wc, int fr, int fq) const {
;     ...
;     for (int ai = 0; ai < 2; ++ai) {
;       f32x4 xv[4][2][2];
; #pragma unroll
;       for (int m = 0; m < 4; ++m) {
;         const int row = row0 + ai * 128 + m * 16;
;         const float* xi = row < T_LAT ? rin_lat + (size_t)row * DM : rin_ctx + (size_t)(row - T_LAT) * DM;
; #pragma unroll
;         for (int bj = 0; bj < 2; ++bj)
; #pragma unroll
;           for (int n = 0; n < 2; ++n) xv[m][bj][n] = *(const f32x4*)(xi + col0 + bj * 128 + n * 16);
;       }
; #pragma unroll
;       for (int m = 0; m < 4; ++m) {
;         const int row = row0 + ai * 128 + m * 16;
;         float* xr = row < T_LAT ? out + (size_t)row * DM : xc + (size_t)(row - T_LAT) * DM;
; #pragma unroll
;         for (int bj = 0; bj < 2; ++bj)
; #pragma unroll
;           for (int n = 0; n < 2; ++n) {
;             const f32x4 r = xv[m][bj][n] + g4[bj][n] * acc[ai][bj][m][n];
;             if (store) *(f32x4*)(xr + col0 + bj * 128 + n * 16) = r;
;           }
;       }
;     }
	v_pk_fma_f32 v[140:141], v[140:141], v[132:133], v[204:205]
	v_pk_fma_f32 v[138:139], v[138:139], v[130:131], v[202:203]
	v_pk_fma_f32 v[124:125], v[124:125], v[128:129], v[200:201]
	v_pk_fma_f32 v[122:123], v[122:123], v[126:127], v[198:199]
	v_pk_fma_f32 v[112:113], v[112:113], v[120:121], v[196:197]
	v_pk_fma_f32 v[144:145], v[144:145], v[136:137], v[230:231]
	v_pk_fma_f32 v[142:143], v[142:143], v[134:135], v[228:229]
	v_pk_fma_f32 v[110:111], v[110:111], v[118:119], v[194:195]
	v_pk_fma_f32 v[90:91], v[90:91], v[120:121], v[176:177]
	v_pk_fma_f32 v[88:89], v[88:89], v[118:119], v[174:175]
	global_store_dwordx4 v[222:223], v[142:145], off
	global_store_dwordx4 v[222:223], v[138:141], off offset:64
	global_store_dwordx4 v[222:223], v[122:125], off offset:512
	global_store_dwordx4 v[222:223], v[110:113], off offset:576
	v_pk_fma_f32 v[108:109], v[108:109], v[132:133], v[188:189]
	v_pk_fma_f32 v[106:107], v[106:107], v[130:131], v[186:187]
	v_pk_fma_f32 v[112:113], v[116:117], v[136:137], v[192:193]
	v_pk_fma_f32 v[110:111], v[114:115], v[134:135], v[190:191]
	v_pk_fma_f32 v[100:101], v[100:101], v[128:129], v[184:185]
	v_pk_fma_f32 v[98:99], v[98:99], v[126:127], v[182:183]
	global_store_dwordx4 v[220:221], v[88:91], off offset:576
	global_store_dwordx4 v[220:221], v[110:113], off
	global_store_dwordx4 v[220:221], v[106:109], off offset:64
	v_pk_fma_f32 v[90:91], v[104:105], v[136:137], v[180:181]
	v_pk_fma_f32 v[88:89], v[102:103], v[134:135], v[178:179]
	global_store_dwordx4 v[220:221], v[98:101], off offset:512
	global_store_dwordx4 v[218:219], v[88:91], off
	v_pk_fma_f32 v[82:83], v[82:83], v[128:129], v[168:169]
	v_pk_fma_f32 v[80:81], v[80:81], v[126:127], v[166:167]
	v_pk_fma_f32 v[90:91], v[94:95], v[132:133], v[172:173]
	v_pk_fma_f32 v[88:89], v[92:93], v[130:131], v[170:171]
	v_pk_fma_f32 v[74:75], v[74:75], v[120:121], v[160:161]
	v_pk_fma_f32 v[72:73], v[72:73], v[118:119], v[158:159]
	v_pk_fma_f32 v[66:67], v[66:67], v[120:121], v[148:149]
	v_pk_fma_f32 v[64:65], v[64:65], v[118:119], v[146:147]
	global_store_dwordx4 v[218:219], v[88:91], off offset:64
	global_store_dwordx4 v[218:219], v[80:83], off offset:512
	global_store_dwordx4 v[218:219], v[72:75], off offset:576
	global_store_dwordx4 v[216:217], v[64:67], off offset:576
	v_pk_fma_f32 v[70:71], v[70:71], v[128:129], v[152:153]
	v_pk_fma_f32 v[74:75], v[86:87], v[136:137], v[164:165]
	v_add_u32_e32 v64, 0x80, v238
	v_ashrrev_i32_e32 v65, 31, v64
	v_add_u32_e32 v66, 0xffff8080, v238
	v_cndmask_b32_e32 v65, 0, v65, vcc
	v_cndmask_b32_e32 v64, v66, v64, vcc
	v_cndmask_b32_e32 v67, v241, v242, vcc
	v_cndmask_b32_e32 v66, v243, v244, vcc
	v_lshlrev_b64 v[64:65], 12, v[64:65]
	v_lshl_add_u64 v[64:65], v[66:67], 0, v[64:65]
	v_lshl_add_u64 v[148:149], v[64:65], 0, v[214:215]
	v_add_u32_e32 v64, 0x90, v238
	v_cmp_gt_i32_e32 vcc, s0, v238
	v_ashrrev_i32_e32 v65, 31, v64
	v_add_u32_e32 v66, 0xffff8090, v238
	v_cndmask_b32_e32 v65, 0, v65, vcc
	v_cndmask_b32_e32 v64, v66, v64, vcc
	v_cndmask_b32_e32 v67, v241, v242, vcc
	v_cndmask_b32_e32 v66, v243, v244, vcc
	v_lshlrev_b64 v[64:65], 12, v[64:65]
	v_lshl_add_u64 v[64:65], v[66:67], 0, v[64:65]
	v_lshl_add_u64 v[146:147], v[64:65], 0, v[214:215]
	v_add_u32_e32 v64, 0xa0, v238
	s_movk_i32 s0, 0x7f60
	v_cmp_gt_i32_e32 vcc, s0, v238
	v_ashrrev_i32_e32 v65, 31, v64
	v_add_u32_e32 v66, 0xffff80a0, v238
	v_cndmask_b32_e32 v65, 0, v65, vcc
	v_cndmask_b32_e32 v64, v66, v64, vcc
	v_cndmask_b32_e32 v67, v241, v242, vcc
	v_cndmask_b32_e32 v66, v243, v244, vcc
	v_lshlrev_b64 v[64:65], 12, v[64:65]
	v_lshl_add_u64 v[64:65], v[66:67], 0, v[64:65]
	v_lshl_add_u64 v[144:145], v[64:65], 0, v[214:215]
	v_add_u32_e32 v64, 0xb0, v238
	s_movk_i32 s0, 0x7f50
	v_cmp_gt_i32_e32 vcc, s0, v238
	v_ashrrev_i32_e32 v65, 31, v64
	v_add_u32_e32 v66, 0xffff80b0, v238
	v_pk_fma_f32 v[72:73], v[84:85], v[134:135], v[162:163]
	v_cndmask_b32_e32 v65, 0, v65, vcc
	v_cndmask_b32_e32 v64, v66, v64, vcc
	global_store_dwordx4 v[216:217], v[72:75], off
	v_pk_fma_f32 v[68:69], v[68:69], v[126:127], v[150:151]
	v_cndmask_b32_e32 v67, v241, v242, vcc
	v_pk_fma_f32 v[74:75], v[78:79], v[132:133], v[156:157]
	v_pk_fma_f32 v[72:73], v[76:77], v[130:131], v[154:155]
	v_cndmask_b32_e32 v66, v243, v244, vcc
	v_lshlrev_b64 v[64:65], 12, v[64:65]
	global_store_dwordx4 v[216:217], v[72:75], off offset:64
	global_store_dwordx4 v[216:217], v[68:71], off offset:512
	v_lshl_add_u64 v[64:65], v[66:67], 0, v[64:65]
	global_load_dwordx4 v[138:141], v[148:149], off offset:64
	global_load_dwordx4 v[122:125], v[148:149], off offset:512
	global_load_dwordx4 v[110:113], v[148:149], off offset:576
	v_lshl_add_u64 v[142:143], v[64:65], 0, v[214:215]
	global_load_dwordx4 v[114:117], v[146:147], off
	global_load_dwordx4 v[106:109], v[146:147], off offset:64
	global_load_dwordx4 v[102:105], v[146:147], off offset:512
	global_load_dwordx4 v[92:95], v[146:147], off offset:576
	global_load_dwordx4 v[98:101], v[144:145], off
	global_load_dwordx4 v[88:91], v[144:145], off offset:64
	global_load_dwordx4 v[84:87], v[144:145], off offset:512
	global_load_dwordx4 v[76:79], v[144:145], off offset:576
	global_load_dwordx4 v[80:83], v[142:143], off
	global_load_dwordx4 v[72:75], v[142:143], off offset:64
	global_load_dwordx4 v[68:71], v[142:143], off offset:512
	global_load_dwordx4 v[64:67], v[142:143], off offset:576
	global_load_dwordx4 v[150:153], v[148:149], off
	s_and_b64 vcc, exec, s[36:37]
	s_waitcnt vmcnt(0)
;   DEV void operator()(const f32x4 (&acc)[2][2][4][2], const pg8::Unit& u, int wr, int wc, int fr, int fq) const {
;     ...
;       for (int m = 0; m < 4; ++m) {
;         const int row = row0 + ai * 128 + m * 16;
;         float* xr = row < T_LAT ? out + (size_t)row * DM : xc + (size_t)(row - T_LAT) * DM;
; #pragma unroll
;         for (int bj = 0; bj < 2; ++bj)
; #pragma unroll
;           for (int n = 0; n < 2; ++n) {
;             const f32x4 r = xv[m][bj][n] + g4[bj][n] * acc[ai][bj][m][n];
;             if (store) *(f32x4*)(xr + col0 + bj * 128 + n * 16) = r;
;           }
;       }
;     }
	v_pk_fma_f32 v[58:59], v[58:59], v[132:133], v[140:141]
	v_pk_fma_f32 v[56:57], v[56:57], v[130:131], v[138:139]
	v_pk_fma_f32 v[42:43], v[42:43], v[120:121], v[112:113]
	v_pk_fma_f32 v[40:41], v[40:41], v[118:119], v[110:111]
	v_pk_fma_f32 v[50:51], v[50:51], v[128:129], v[124:125]
	v_pk_fma_f32 v[48:49], v[48:49], v[126:127], v[122:123]
	v_pk_fma_f32 v[62:63], v[62:63], v[136:137], v[152:153]
	v_pk_fma_f32 v[60:61], v[60:61], v[134:135], v[150:151]
	global_store_dwordx4 v[148:149], v[40:43], off offset:576
	v_pk_fma_f32 v[26:27], v[26:27], v[120:121], v[94:95]
	v_pk_fma_f32 v[24:25], v[24:25], v[118:119], v[92:93]
	v_pk_fma_f32 v[42:43], v[54:55], v[136:137], v[116:117]
	v_pk_fma_f32 v[40:41], v[52:53], v[134:135], v[114:115]
	global_store_dwordx4 v[148:149], v[60:63], off
	global_store_dwordx4 v[148:149], v[56:59], off offset:64
	global_store_dwordx4 v[148:149], v[48:51], off offset:512
	global_store_dwordx4 v[146:147], v[40:43], off
	v_pk_fma_f32 v[34:35], v[34:35], v[128:129], v[104:105]
	v_pk_fma_f32 v[32:33], v[32:33], v[126:127], v[102:103]
	v_pk_fma_f32 v[42:43], v[46:47], v[132:133], v[108:109]
	v_pk_fma_f32 v[40:41], v[44:45], v[130:131], v[106:107]
	global_store_dwordx4 v[146:147], v[24:27], off offset:576
	v_pk_fma_f32 v[10:11], v[10:11], v[120:121], v[78:79]
	v_pk_fma_f32 v[8:9], v[8:9], v[118:119], v[76:77]
	v_pk_fma_f32 v[26:27], v[38:39], v[136:137], v[100:101]
	v_pk_fma_f32 v[24:25], v[36:37], v[134:135], v[98:99]
	global_store_dwordx4 v[146:147], v[40:43], off offset:64
	global_store_dwordx4 v[146:147], v[32:35], off offset:512
	global_store_dwordx4 v[144:145], v[24:27], off
	v_pk_fma_f32 v[18:19], v[18:19], v[128:129], v[86:87]
	v_pk_fma_f32 v[16:17], v[16:17], v[126:127], v[84:85]
	v_pk_fma_f32 v[26:27], v[30:31], v[132:133], v[90:91]
	v_pk_fma_f32 v[24:25], v[28:29], v[130:131], v[88:89]
	global_store_dwordx4 v[144:145], v[8:11], off offset:576
	global_store_dwordx4 v[144:145], v[24:27], off offset:64
	global_store_dwordx4 v[144:145], v[16:19], off offset:512
	v_pk_fma_f32 v[10:11], v[22:23], v[136:137], v[82:83]
	v_pk_fma_f32 v[8:9], v[20:21], v[134:135], v[80:81]
	global_store_dwordx4 v[142:143], v[8:11], off
	v_pk_fma_f32 v[6:7], v[6:7], v[128:129], v[70:71]
	v_pk_fma_f32 v[4:5], v[4:5], v[126:127], v[68:69]
	v_pk_fma_f32 v[10:11], v[14:15], v[132:133], v[74:75]
	v_pk_fma_f32 v[8:9], v[12:13], v[130:131], v[72:73]
	v_pk_fma_f32 v[2:3], v[2:3], v[120:121], v[66:67]
	v_pk_fma_f32 v[0:1], v[0:1], v[118:119], v[64:65]
	global_store_dwordx4 v[142:143], v[8:11], off offset:64
	global_store_dwordx4 v[142:143], v[4:7], off offset:512
	global_store_dwordx4 v[142:143], v[0:3], off offset:576
	s_cbranch_vccz .LBB0_44
	s_waitcnt vmcnt(0)
	v_readlane_b32 s66, v255, 34
	v_readlane_b32 s64, v255, 38
	s_cmpk_gt_u32 s56, 0xff
	v_readlane_b32 s67, v255, 35
	v_readlane_b32 s65, v255, 39
	s_cbranch_scc1 .LBB0_51
	s_barrier

; #define PG8_STAGE(bufoff, gbase, voff) do { _Pragma("unroll") for (int _i = 0; _i < 2; ++_i) \
;         __builtin_amdgcn_global_load_lds((const unsigned*)((const char*)(gbase) + (voff)[_i]), (PG8_LAS unsigned*)(lds + (bufoff) + ldsw + _i * 8192), 16, 0, 0); } while (0)
; #define PG8_LDA(dst, b, h) do { _Pragma("unroll") for (int m = 0; m < 4; ++m) _Pragma("unroll") for (int k = 0; k < 2; ++k) dst[m][k] = *(const PG8_LAS bf16x8*)(lds + PG8_SA(b, h) + aoff + m * 2048 + k * 1024); } while (0)
; #define PG8_LDB(dst, b, h) do { _Pragma("unroll") for (int n = 0; n < 2; ++n) _Pragma("unroll") for (int k = 0; k < 2; ++k) dst[n][k] = *(const PG8_LAS bf16x8*)(lds + PG8_SB(b, h) + boff + n * 2048 + k * 1024); } while (0)
; #define PG8_MMA(ai, bj, At, Bt) do { __builtin_amdgcn_s_setprio(1); _Pragma("unroll") for (int m = 0; m < 4; ++m) _Pragma("unroll") for (int n = 0; n < 2; ++n) _Pragma("unroll") for (int k = 0; k < 2; ++k) \
;         acc[ai][bj][m][n] = __builtin_amdgcn_mfma_f32_16x16x32_bf16(Bt[n][k], At[m][k], acc[ai][bj][m][n], 0, 0, 0); __builtin_amdgcn_s_setprio(0); } while (0)
; #define PG8_WAIT_V(n) asm volatile("s_waitcnt vmcnt(" #n ")" ::: "memory")
; #define PG8_WAIT_L(n) asm volatile("s_waitcnt lgkmcnt(" #n ")" ::: "memory")
; #define PG8_BAR __builtin_amdgcn_s_barrier()
; #define PG8_SCHED __builtin_amdgcn_sched_barrier(0)
; template <class Epi, class Sched>
; __device__ __forceinline__ void gemm_phase(PG8_LAS unsigned char* lds, const Gemm g, const Sched& S, const Epi& E) {
;     ...
;             PG8_LDB(B0, 0, 0); PG8_SCHED; PG8_LDA(At, 0, 0); PG8_STAGE(PG8_SA(1, 1), a1 + hstep, voffA);
;             PG8_WAIT_L(8); PG8_BAR; PG8_WAIT_L(0); PG8_MMA(0, 0, At, B0); PG8_BAR; PG8_SCHED;
;             PG8_LDB(B1, 0, 1); PG8_STAGE(PG8_SB(0, 0), b2, voffB);
;             PG8_BAR; PG8_WAIT_L(0); PG8_MMA(0, 1, At, B1); PG8_BAR;
;             PG8_LDA(At, 0, 1); PG8_STAGE(PG8_SA(0, 0), a2, voffA);
;             PG8_BAR; PG8_WAIT_L(0); PG8_MMA(1, 0, At, B0); PG8_BAR; PG8_SCHED;
;             PG8_STAGE(PG8_SB(0, 1), b2 + hstep, voffB);
;             PG8_WAIT_V(6); PG8_BAR; PG8_MMA(1, 1, At, B1); PG8_BAR;
.Lgp_2972:
.LBB0_65:
	s_setprio 1
	s_add_u32 s42, s46, 0xfffc0080
	s_addc_u32 s43, s47, -1
	s_add_i32 s71, 0, 0x10000
	v_add_u32_e32 v156, s71, v141
	ds_read_b128 v[144:147], v156
	ds_read_b128 v[148:151], v156 offset:1024
	ds_read_b128 v[152:155], v156 offset:2048
	ds_read_b128 v[156:159], v156 offset:3072
	s_cmp_eq_u32 s70, 12
	s_cselect_b32 s51, s31, s43
	s_cselect_b32 s50, s66, s42
	s_cselect_b32 s49, s1, s69
	s_cselect_b32 s48, s67, s68
	v_lshl_add_u64 v[192:193], s[46:47], 0, v[136:137]
	s_add_i32 m0, s45, 0xc000
	ds_read_b128 v[160:163], v143
	ds_read_b128 v[164:167], v143 offset:1024
	ds_read_b128 v[168:171], v143 offset:2048
	ds_read_b128 v[172:175], v143 offset:3072
	ds_read_b128 v[176:179], v143 offset:4096
	ds_read_b128 v[180:183], v143 offset:5120
	ds_read_b128 v[184:187], v143 offset:6144
	ds_read_b128 v[188:191], v143 offset:7168
	global_load_lds_dwordx4 v[192:193], off
	v_lshl_add_u64 v[192:193], s[46:47], 0, v[138:139]
	s_add_i32 m0, s45, 0xe000
	s_nop 0
	global_load_lds_dwordx4 v[192:193], off
	s_waitcnt lgkmcnt(8)
	s_barrier
	s_setprio 0
	s_waitcnt lgkmcnt(0)
	v_mfma_f32_16x16x32_bf16 v[126:129], v[144:147], v[160:163], v[126:129]
	v_mfma_f32_16x16x32_bf16 v[122:125], v[152:155], v[160:163], v[122:125]
	v_mfma_f32_16x16x32_bf16 v[110:113], v[144:147], v[168:171], v[110:113]
	v_mfma_f32_16x16x32_bf16 v[106:109], v[152:155], v[168:171], v[106:109]
	v_mfma_f32_16x16x32_bf16 v[92:95], v[144:147], v[176:179], v[92:95]
	v_mfma_f32_16x16x32_bf16 v[88:91], v[152:155], v[176:179], v[88:91]
	v_mfma_f32_16x16x32_bf16 v[76:79], v[144:147], v[184:187], v[76:79]
	v_mfma_f32_16x16x32_bf16 v[72:75], v[152:155], v[184:187], v[72:75]
	v_mfma_f32_16x16x32_bf16 v[126:129], v[148:151], v[164:167], v[126:129]
	v_mfma_f32_16x16x32_bf16 v[122:125], v[156:159], v[164:167], v[122:125]
	v_mfma_f32_16x16x32_bf16 v[110:113], v[148:151], v[172:175], v[110:113]
	v_mfma_f32_16x16x32_bf16 v[106:109], v[156:159], v[172:175], v[106:109]
	v_mfma_f32_16x16x32_bf16 v[92:95], v[148:151], v[180:183], v[92:95]
	v_mfma_f32_16x16x32_bf16 v[88:91], v[156:159], v[180:183], v[88:91]
	v_mfma_f32_16x16x32_bf16 v[76:79], v[148:151], v[188:191], v[76:79]
	v_mfma_f32_16x16x32_bf16 v[72:75], v[156:159], v[188:191], v[72:75]
	s_barrier
	s_setprio 1
	s_add_i32 s42, 0, 0x14000
	v_add_u32_e32 v204, s42, v141
	s_add_i32 s43, s71, s56
	ds_read_b128 v[192:195], v204
	ds_read_b128 v[196:199], v204 offset:1024
	ds_read_b128 v[200:203], v204 offset:2048
	ds_read_b128 v[208:211], v204 offset:3072
	v_lshl_add_u64 v[204:205], s[48:49], 0, v[96:97]
	s_mov_b32 m0, s43
	v_lshl_add_u64 v[212:213], s[48:49], 0, v[130:131]
	global_load_lds_dwordx4 v[204:205], off
	s_add_i32 m0, s43, 0x2000
	s_nop 0
	global_load_lds_dwordx4 v[212:213], off
	s_barrier
	s_setprio 0
	s_waitcnt lgkmcnt(0)
	v_mfma_f32_16x16x32_bf16 v[118:121], v[192:195], v[160:163], v[118:121]
	v_mfma_f32_16x16x32_bf16 v[114:117], v[200:203], v[160:163], v[114:117]
	v_mfma_f32_16x16x32_bf16 v[102:105], v[192:195], v[168:171], v[102:105]
	v_mfma_f32_16x16x32_bf16 v[98:101], v[200:203], v[168:171], v[98:101]
	v_mfma_f32_16x16x32_bf16 v[84:87], v[192:195], v[176:179], v[84:87]
	v_mfma_f32_16x16x32_bf16 v[80:83], v[200:203], v[176:179], v[80:83]
	v_mfma_f32_16x16x32_bf16 v[68:71], v[192:195], v[184:187], v[68:71]
	v_mfma_f32_16x16x32_bf16 v[64:67], v[200:203], v[184:187], v[64:67]
	v_mfma_f32_16x16x32_bf16 v[118:121], v[196:199], v[164:167], v[118:121]
	v_mfma_f32_16x16x32_bf16 v[114:117], v[208:211], v[164:167], v[114:117]
	v_mfma_f32_16x16x32_bf16 v[102:105], v[196:199], v[172:175], v[102:105]
	v_mfma_f32_16x16x32_bf16 v[98:101], v[208:211], v[172:175], v[98:101]
	v_mfma_f32_16x16x32_bf16 v[84:87], v[196:199], v[180:183], v[84:87]
	v_mfma_f32_16x16x32_bf16 v[80:83], v[208:211], v[180:183], v[80:83]
	v_mfma_f32_16x16x32_bf16 v[68:71], v[196:199], v[188:191], v[68:71]
	v_mfma_f32_16x16x32_bf16 v[64:67], v[208:211], v[188:191], v[64:67]
	s_mov_b32 m0, s45
	v_lshl_add_u64 v[214:215], s[50:51], 0, v[134:135]
	s_barrier
	s_setprio 1
	ds_read_b128 v[160:163], v143 offset:16384
	ds_read_b128 v[164:167], v143 offset:17408
	ds_read_b128 v[168:171], v143 offset:18432
	ds_read_b128 v[172:175], v143 offset:19456
	ds_read_b128 v[176:179], v143 offset:20480
	ds_read_b128 v[180:183], v143 offset:21504
	ds_read_b128 v[184:187], v143 offset:22528
	ds_read_b128 v[188:191], v143 offset:23552
	global_load_lds_dwordx4 v[214:215], off
	v_lshl_add_u64 v[216:217], s[50:51], 0, v[132:133]
	s_mov_b32 m0, s59
	s_nop 0
	global_load_lds_dwordx4 v[216:217], off
	s_barrier
	s_setprio 0
	s_waitcnt lgkmcnt(0)
	v_mfma_f32_16x16x32_bf16 v[60:63], v[144:147], v[160:163], v[60:63]
	v_mfma_f32_16x16x32_bf16 v[56:59], v[152:155], v[160:163], v[56:59]
	v_mfma_f32_16x16x32_bf16 v[44:47], v[144:147], v[168:171], v[44:47]
	v_mfma_f32_16x16x32_bf16 v[40:43], v[152:155], v[168:171], v[40:43]
	v_mfma_f32_16x16x32_bf16 v[28:31], v[144:147], v[176:179], v[28:31]
	v_mfma_f32_16x16x32_bf16 v[24:27], v[152:155], v[176:179], v[24:27]
	v_mfma_f32_16x16x32_bf16 v[12:15], v[144:147], v[184:187], v[12:15]
	v_mfma_f32_16x16x32_bf16 v[8:11], v[152:155], v[184:187], v[8:11]
	v_mfma_f32_16x16x32_bf16 v[60:63], v[148:151], v[164:167], v[60:63]
	v_mfma_f32_16x16x32_bf16 v[56:59], v[156:159], v[164:167], v[56:59]
	v_mfma_f32_16x16x32_bf16 v[44:47], v[148:151], v[172:175], v[44:47]
	v_mfma_f32_16x16x32_bf16 v[40:43], v[156:159], v[172:175], v[40:43]
	v_mfma_f32_16x16x32_bf16 v[28:31], v[148:151], v[180:183], v[28:31]
	v_mfma_f32_16x16x32_bf16 v[24:27], v[156:159], v[180:183], v[24:27]
	v_mfma_f32_16x16x32_bf16 v[12:15], v[148:151], v[188:191], v[12:15]
	v_mfma_f32_16x16x32_bf16 v[8:11], v[156:159], v[188:191], v[8:11]
	s_barrier
; #define PG8_STAGE(bufoff, gbase, voff) do { _Pragma("unroll") for (int _i = 0; _i < 2; ++_i) \
;         __builtin_amdgcn_global_load_lds((const unsigned*)((const char*)(gbase) + (voff)[_i]), (PG8_LAS unsigned*)(lds + (bufoff) + ldsw + _i * 8192), 16, 0, 0); } while (0)
; #define PG8_LDA(dst, b, h) do { _Pragma("unroll") for (int m = 0; m < 4; ++m) _Pragma("unroll") for (int k = 0; k < 2; ++k) dst[m][k] = *(const PG8_LAS bf16x8*)(lds + PG8_SA(b, h) + aoff + m * 2048 + k * 1024); } while (0)
; #define PG8_LDB(dst, b, h) do { _Pragma("unroll") for (int n = 0; n < 2; ++n) _Pragma("unroll") for (int k = 0; k < 2; ++k) dst[n][k] = *(const PG8_LAS bf16x8*)(lds + PG8_SB(b, h) + boff + n * 2048 + k * 1024); } while (0)
; #define PG8_MMA(ai, bj, At, Bt) do { __builtin_amdgcn_s_setprio(1); _Pragma("unroll") for (int m = 0; m < 4; ++m) _Pragma("unroll") for (int n = 0; n < 2; ++n) _Pragma("unroll") for (int k = 0; k < 2; ++k) \
;         acc[ai][bj][m][n] = __builtin_amdgcn_mfma_f32_16x16x32_bf16(Bt[n][k], At[m][k], acc[ai][bj][m][n], 0, 0, 0); __builtin_amdgcn_s_setprio(0); } while (0)
; #define PG8_WAIT_V(n) asm volatile("s_waitcnt vmcnt(" #n ")" ::: "memory")
; #define PG8_WAIT_L(n) asm volatile("s_waitcnt lgkmcnt(" #n ")" ::: "memory")
; #define PG8_BAR __builtin_amdgcn_s_barrier()
; #define PG8_SCHED __builtin_amdgcn_sched_barrier(0)
; template <class Epi, class Sched>
; __device__ __forceinline__ void gemm_phase(PG8_LAS unsigned char* lds, const Gemm g, const Sched& S, const Epi& E) {
;     ...
;             PG8_STAGE(PG8_SB(0, 1), b2 + hstep, voffB);
;             PG8_WAIT_V(6); PG8_BAR; PG8_MMA(1, 1, At, B1); PG8_BAR;
;             PG8_LDB(B0, 1, 0); PG8_SCHED; PG8_LDA(At, 1, 0); PG8_STAGE(PG8_SA(0, 1), a2 + hstep, voffA);
;             PG8_WAIT_L(8); PG8_BAR; PG8_WAIT_L(0); PG8_MMA(0, 0, At, B0); PG8_BAR; PG8_SCHED;
;             PG8_LDB(B1, 1, 1); PG8_STAGE(PG8_SB(1, 0), b3, voffB);
;             PG8_BAR; PG8_WAIT_L(0); PG8_MMA(0, 1, At, B1); PG8_BAR;
;             PG8_LDA(At, 1, 1); PG8_STAGE(PG8_SA(1, 0), a3, voffA);
;             PG8_BAR; PG8_WAIT_L(0); PG8_MMA(1, 0, At, B0); PG8_BAR; PG8_SCHED;
	s_setprio 1
	s_add_u32 vcc_lo, s48, 0x40000
	s_addc_u32 vcc_hi, s49, 0
	s_add_i32 s42, s42, s56
	v_lshl_add_u64 v[144:145], vcc, 0, v[96:97]
	s_mov_b32 m0, s42
	s_nop 0
	global_load_lds_dwordx4 v[144:145], off
	v_lshl_add_u64 v[144:145], vcc, 0, v[130:131]
	s_add_i32 m0, s42, 0x2000
	s_nop 0
	global_load_lds_dwordx4 v[144:145], off
	s_waitcnt vmcnt(6)
	s_barrier
	s_setprio 0
	v_mfma_f32_16x16x32_bf16 v[52:55], v[192:195], v[160:163], v[52:55]
	v_mfma_f32_16x16x32_bf16 v[48:51], v[200:203], v[160:163], v[48:51]
	v_mfma_f32_16x16x32_bf16 v[36:39], v[192:195], v[168:171], v[36:39]
	v_mfma_f32_16x16x32_bf16 v[32:35], v[200:203], v[168:171], v[32:35]
	v_mfma_f32_16x16x32_bf16 v[20:23], v[192:195], v[176:179], v[20:23]
	v_mfma_f32_16x16x32_bf16 v[16:19], v[200:203], v[176:179], v[16:19]
	v_mfma_f32_16x16x32_bf16 v[4:7], v[192:195], v[184:187], v[4:7]
	v_mfma_f32_16x16x32_bf16 v[0:3], v[200:203], v[184:187], v[0:3]
	v_mfma_f32_16x16x32_bf16 v[52:55], v[196:199], v[164:167], v[52:55]
	v_mfma_f32_16x16x32_bf16 v[48:51], v[208:211], v[164:167], v[48:51]
	v_mfma_f32_16x16x32_bf16 v[36:39], v[196:199], v[172:175], v[36:39]
	v_mfma_f32_16x16x32_bf16 v[32:35], v[208:211], v[172:175], v[32:35]
	v_mfma_f32_16x16x32_bf16 v[20:23], v[196:199], v[180:183], v[20:23]
	v_mfma_f32_16x16x32_bf16 v[16:19], v[208:211], v[180:183], v[16:19]
	v_mfma_f32_16x16x32_bf16 v[4:7], v[196:199], v[188:191], v[4:7]
	v_mfma_f32_16x16x32_bf16 v[0:3], v[208:211], v[188:191], v[0:3]
	s_add_i32 s42, 0, 0x18000
	v_add_u32_e32 v156, s42, v141
	s_barrier
	s_setprio 1
	ds_read_b128 v[144:147], v156
	ds_read_b128 v[148:151], v156 offset:1024
	ds_read_b128 v[152:155], v156 offset:2048
	ds_read_b128 v[156:159], v156 offset:3072
	s_add_u32 s50, s50, 0x40000
	s_addc_u32 s51, s51, 0
	s_mov_b32 m0, s60
	v_lshl_add_u64 v[192:193], s[50:51], 0, v[134:135]
	ds_read_b128 v[160:163], v143 offset:32768
	ds_read_b128 v[164:167], v143 offset:33792
	ds_read_b128 v[168:171], v143 offset:34816
	ds_read_b128 v[172:175], v143 offset:35840
	ds_read_b128 v[176:179], v143 offset:36864
	ds_read_b128 v[180:183], v143 offset:37888
	ds_read_b128 v[184:187], v143 offset:38912
	ds_read_b128 v[188:191], v143 offset:39936
	global_load_lds_dwordx4 v[192:193], off
	v_lshl_add_u64 v[192:193], s[50:51], 0, v[132:133]
	s_mov_b32 m0, s61
	s_nop 0
	global_load_lds_dwordx4 v[192:193], off
	s_waitcnt lgkmcnt(8)
	s_barrier
	s_setprio 0
	s_waitcnt lgkmcnt(0)
	v_mfma_f32_16x16x32_bf16 v[126:129], v[144:147], v[160:163], v[126:129]
	v_mfma_f32_16x16x32_bf16 v[122:125], v[152:155], v[160:163], v[122:125]
	v_mfma_f32_16x16x32_bf16 v[110:113], v[144:147], v[168:171], v[110:113]
	v_mfma_f32_16x16x32_bf16 v[106:109], v[152:155], v[168:171], v[106:109]
	v_mfma_f32_16x16x32_bf16 v[92:95], v[144:147], v[176:179], v[92:95]
	v_mfma_f32_16x16x32_bf16 v[88:91], v[152:155], v[176:179], v[88:91]
	v_mfma_f32_16x16x32_bf16 v[76:79], v[144:147], v[184:187], v[76:79]
	v_mfma_f32_16x16x32_bf16 v[72:75], v[152:155], v[184:187], v[72:75]
	v_mfma_f32_16x16x32_bf16 v[126:129], v[148:151], v[164:167], v[126:129]
	v_mfma_f32_16x16x32_bf16 v[122:125], v[156:159], v[164:167], v[122:125]
	v_mfma_f32_16x16x32_bf16 v[110:113], v[148:151], v[172:175], v[110:113]
	v_mfma_f32_16x16x32_bf16 v[106:109], v[156:159], v[172:175], v[106:109]
	v_mfma_f32_16x16x32_bf16 v[92:95], v[148:151], v[180:183], v[92:95]
	v_mfma_f32_16x16x32_bf16 v[88:91], v[156:159], v[180:183], v[88:91]
	v_mfma_f32_16x16x32_bf16 v[76:79], v[148:151], v[188:191], v[76:79]
	v_mfma_f32_16x16x32_bf16 v[72:75], v[156:159], v[188:191], v[72:75]
	s_barrier
	s_setprio 1
	s_add_i32 s43, 0, 0x1c000
	s_add_i32 s42, s42, s56
	v_add_u32_e32 v208, s43, v141
	v_lshl_add_u64 v[204:205], v[204:205], 0, s[2:3]
	s_mov_b32 m0, s42
	ds_read_b128 v[192:195], v208
	ds_read_b128 v[196:199], v208 offset:1024
	ds_read_b128 v[200:203], v208 offset:2048
	ds_read_b128 v[208:211], v208 offset:3072
	global_load_lds_dwordx4 v[204:205], off
	v_lshl_add_u64 v[204:205], v[212:213], 0, s[2:3]
	s_add_i32 m0, s42, 0x2000
	s_nop 0
	global_load_lds_dwordx4 v[204:205], off
	s_barrier
	s_setprio 0
	s_waitcnt lgkmcnt(0)
	v_mfma_f32_16x16x32_bf16 v[118:121], v[192:195], v[160:163], v[118:121]
	v_mfma_f32_16x16x32_bf16 v[114:117], v[200:203], v[160:163], v[114:117]
	v_mfma_f32_16x16x32_bf16 v[102:105], v[192:195], v[168:171], v[102:105]
	v_mfma_f32_16x16x32_bf16 v[98:101], v[200:203], v[168:171], v[98:101]
	v_mfma_f32_16x16x32_bf16 v[84:87], v[192:195], v[176:179], v[84:87]
	v_mfma_f32_16x16x32_bf16 v[80:83], v[200:203], v[176:179], v[80:83]
	v_mfma_f32_16x16x32_bf16 v[68:71], v[192:195], v[184:187], v[68:71]
	v_mfma_f32_16x16x32_bf16 v[64:67], v[200:203], v[184:187], v[64:67]
	v_mfma_f32_16x16x32_bf16 v[118:121], v[196:199], v[164:167], v[118:121]
	v_mfma_f32_16x16x32_bf16 v[114:117], v[208:211], v[164:167], v[114:117]
	v_mfma_f32_16x16x32_bf16 v[102:105], v[196:199], v[172:175], v[102:105]
	v_mfma_f32_16x16x32_bf16 v[98:101], v[208:211], v[172:175], v[98:101]
	v_mfma_f32_16x16x32_bf16 v[84:87], v[196:199], v[180:183], v[84:87]
	v_mfma_f32_16x16x32_bf16 v[80:83], v[208:211], v[180:183], v[80:83]
	v_mfma_f32_16x16x32_bf16 v[68:71], v[196:199], v[188:191], v[68:71]
	v_mfma_f32_16x16x32_bf16 v[64:67], v[208:211], v[188:191], v[64:67]
	s_mov_b32 m0, s62
	v_lshl_add_u64 v[204:205], v[214:215], 0, s[2:3]
	s_barrier
	s_setprio 1
	ds_read_b128 v[160:163], v143 offset:49152
	ds_read_b128 v[164:167], v143 offset:50176
	ds_read_b128 v[168:171], v143 offset:51200
	ds_read_b128 v[172:175], v143 offset:52224
	ds_read_b128 v[176:179], v143 offset:53248
	ds_read_b128 v[180:183], v143 offset:54272
	ds_read_b128 v[184:187], v143 offset:55296
	ds_read_b128 v[188:191], v143 offset:56320
	global_load_lds_dwordx4 v[204:205], off
	v_lshl_add_u64 v[204:205], v[216:217], 0, s[2:3]
	s_mov_b32 m0, s63
	s_nop 0
	global_load_lds_dwordx4 v[204:205], off
	s_barrier
; #define PG8_STAGE(bufoff, gbase, voff) do { _Pragma("unroll") for (int _i = 0; _i < 2; ++_i) \
;         __builtin_amdgcn_global_load_lds((const unsigned*)((const char*)(gbase) + (voff)[_i]), (PG8_LAS unsigned*)(lds + (bufoff) + ldsw + _i * 8192), 16, 0, 0); } while (0)
; #define PG8_LDA(dst, b, h) do { _Pragma("unroll") for (int m = 0; m < 4; ++m) _Pragma("unroll") for (int k = 0; k < 2; ++k) dst[m][k] = *(const PG8_LAS bf16x8*)(lds + PG8_SA(b, h) + aoff + m * 2048 + k * 1024); } while (0)
; #define PG8_MMA(ai, bj, At, Bt) do { __builtin_amdgcn_s_setprio(1); _Pragma("unroll") for (int m = 0; m < 4; ++m) _Pragma("unroll") for (int n = 0; n < 2; ++n) _Pragma("unroll") for (int k = 0; k < 2; ++k) \
;         acc[ai][bj][m][n] = __builtin_amdgcn_mfma_f32_16x16x32_bf16(Bt[n][k], At[m][k], acc[ai][bj][m][n], 0, 0, 0); __builtin_amdgcn_s_setprio(0); } while (0)
; #define PG8_WAIT_V(n) asm volatile("s_waitcnt vmcnt(" #n ")" ::: "memory")
; #define PG8_WAIT_L(n) asm volatile("s_waitcnt lgkmcnt(" #n ")" ::: "memory")
; #define PG8_BAR __builtin_amdgcn_s_barrier()
; template <class Epi, class Sched>
; __device__ __forceinline__ void gemm_phase(PG8_LAS unsigned char* lds, const Gemm g, const Sched& S, const Epi& E) {
;     ...
;             PG8_LDA(At, 1, 1); PG8_STAGE(PG8_SA(1, 0), a3, voffA);
;             PG8_BAR; PG8_WAIT_L(0); PG8_MMA(1, 0, At, B0); PG8_BAR; PG8_SCHED;
;             PG8_STAGE(PG8_SB(1, 1), b3 + hstep, voffB);
;             PG8_WAIT_V(6); PG8_BAR; PG8_MMA(1, 1, At, B1); PG8_BAR;
;   DEV void operator()(const f32x4 (&acc)[2][2][4][2], const pg8::Unit& u, int wr, int wc, int fr, int fq) const {
;     const int row0 = u.pm * 256 + wr * 64 + fr, col0 = u.pn * 256 + wc * 32 + 8 * fq;
; #pragma unroll
;     for (int ai = 0; ai < 2; ++ai)
; #pragma unroll
;       for (int m = 0; m < 4; ++m) {
;         const int row = row0 + ai * 128 + m * 16;
; #pragma unroll
;         for (int bj = 0; bj < 2; ++bj) {
;           float v[8];
; #pragma unroll
;           for (int j = 0; j < 4; ++j) {
;             const float r0 = fmaxf(acc[ai][bj][m][0][j], 0.f), r1 = fmaxf(acc[ai][bj][m][1][j], 0.f);
;             v[j] = r0 * r0; v[4 + j] = r1 * r1;
;           }
;           u32x4 o;
;           o[0] = pk2(v[0], v[1]); o[1] = pk2(v[2], v[3]); o[2] = pk2(v[4], v[5]); o[3] = pk2(v[6], v[7]);
;           *(u32x4*)(HID + (size_t)row * 4096 + col0 + bj * 128) = o;
	s_setprio 0
	s_waitcnt lgkmcnt(0)
	v_mfma_f32_16x16x32_bf16 v[60:63], v[144:147], v[160:163], v[60:63]
	v_mfma_f32_16x16x32_bf16 v[56:59], v[152:155], v[160:163], v[56:59]
	v_mfma_f32_16x16x32_bf16 v[44:47], v[144:147], v[168:171], v[44:47]
	v_mfma_f32_16x16x32_bf16 v[40:43], v[152:155], v[168:171], v[40:43]
	v_mfma_f32_16x16x32_bf16 v[28:31], v[144:147], v[176:179], v[28:31]
	v_mfma_f32_16x16x32_bf16 v[24:27], v[152:155], v[176:179], v[24:27]
	v_mfma_f32_16x16x32_bf16 v[12:15], v[144:147], v[184:187], v[12:15]
	v_mfma_f32_16x16x32_bf16 v[8:11], v[152:155], v[184:187], v[8:11]
	v_mfma_f32_16x16x32_bf16 v[60:63], v[148:151], v[164:167], v[60:63]
	v_mfma_f32_16x16x32_bf16 v[56:59], v[156:159], v[164:167], v[56:59]
	v_mfma_f32_16x16x32_bf16 v[44:47], v[148:151], v[172:175], v[44:47]
	v_mfma_f32_16x16x32_bf16 v[40:43], v[156:159], v[172:175], v[40:43]
	v_mfma_f32_16x16x32_bf16 v[28:31], v[148:151], v[180:183], v[28:31]
	v_mfma_f32_16x16x32_bf16 v[24:27], v[156:159], v[180:183], v[24:27]
	v_mfma_f32_16x16x32_bf16 v[12:15], v[148:151], v[188:191], v[12:15]
	v_mfma_f32_16x16x32_bf16 v[8:11], v[156:159], v[188:191], v[8:11]
	s_barrier
	s_setprio 1
	s_add_u32 s48, s48, 0x40080
	s_addc_u32 s49, s49, 0
	s_add_i32 s42, s43, s56
	v_lshl_add_u64 v[144:145], s[48:49], 0, v[96:97]
	s_mov_b32 m0, s42
	s_nop 0
	global_load_lds_dwordx4 v[144:145], off
	v_lshl_add_u64 v[144:145], s[48:49], 0, v[130:131]
	s_add_i32 m0, s42, 0x2000
	s_nop 0
	global_load_lds_dwordx4 v[144:145], off
	s_waitcnt vmcnt(6)
	s_barrier
	s_setprio 0
	v_mfma_f32_16x16x32_bf16 v[52:55], v[192:195], v[160:163], v[52:55]
	v_mfma_f32_16x16x32_bf16 v[48:51], v[200:203], v[160:163], v[48:51]
	v_mfma_f32_16x16x32_bf16 v[36:39], v[192:195], v[168:171], v[36:39]
	v_mfma_f32_16x16x32_bf16 v[32:35], v[200:203], v[168:171], v[32:35]
	v_mfma_f32_16x16x32_bf16 v[20:23], v[192:195], v[176:179], v[20:23]
	v_mfma_f32_16x16x32_bf16 v[16:19], v[200:203], v[176:179], v[16:19]
	v_mfma_f32_16x16x32_bf16 v[4:7], v[192:195], v[184:187], v[4:7]
	v_mfma_f32_16x16x32_bf16 v[0:3], v[200:203], v[184:187], v[0:3]
	v_mfma_f32_16x16x32_bf16 v[52:55], v[196:199], v[164:167], v[52:55]
	v_mfma_f32_16x16x32_bf16 v[48:51], v[208:211], v[164:167], v[48:51]
	v_mfma_f32_16x16x32_bf16 v[36:39], v[196:199], v[172:175], v[36:39]
	v_mfma_f32_16x16x32_bf16 v[32:35], v[208:211], v[172:175], v[32:35]
	v_mfma_f32_16x16x32_bf16 v[20:23], v[196:199], v[180:183], v[20:23]
	v_mfma_f32_16x16x32_bf16 v[16:19], v[208:211], v[180:183], v[16:19]
	v_mfma_f32_16x16x32_bf16 v[4:7], v[196:199], v[188:191], v[4:7]
	v_mfma_f32_16x16x32_bf16 v[0:3], v[208:211], v[188:191], v[0:3]
	s_add_i32 s70, s70, 2
	s_add_u32 s46, s46, 0x100
	s_addc_u32 s47, s47, 0
	s_add_u32 s68, s68, 0x100
	s_addc_u32 s69, s69, 0
	s_cmp_gt_u32 s70, 13
	s_barrier
	s_cbranch_scc0 .LBB0_65
	v_lshl_add_u32 v144, s44, 8, v140
	v_max_f32_e32 v126, v126, v126
	v_max_f32_e32 v122, v122, v122
	v_max_f32_e32 v127, v127, v127
	v_max_f32_e32 v123, v123, v123
	v_max_f32_e32 v128, v128, v128
	v_max_f32_e32 v129, v129, v129
	v_lshl_or_b32 v146, s65, 8, v142
	v_ashrrev_i32_e32 v145, 31, v144
	v_max_f32_e32 v126, 0, v126
	v_max_f32_e32 v122, 0, v122
	v_max_f32_e32 v127, 0, v127
	v_max_f32_e32 v123, 0, v123
	v_max_f32_e32 v128, 0, v128
	v_max_f32_e32 v124, v124, v124
	v_max_f32_e32 v129, 0, v129
	v_max_f32_e32 v125, v125, v125
	v_readlane_b32 s42, v251, 49
	v_ashrrev_i32_e32 v147, 31, v146
	v_lshlrev_b64 v[148:149], 13, v[144:145]
	v_pk_mul_f32 v[126:127], v[126:127], v[126:127]
	v_pk_mul_f32 v[122:123], v[122:123], v[122:123]
	v_max_f32_e32 v124, 0, v124
	v_max_f32_e32 v125, 0, v125
	v_pk_mul_f32 v[128:129], v[128:129], v[128:129]
	v_readlane_b32 s43, v251, 50
	v_pk_mul_f32 v[150:151], v[124:125], v[124:125]
	v_cvt_pk_bf16_f32 v124, v126, v127
	v_cvt_pk_bf16_f32 v125, v128, v129
	v_cvt_pk_bf16_f32 v126, v122, v123
	v_lshl_add_u64 v[122:123], s[42:43], 0, v[148:149]
	v_lshlrev_b64 v[128:129], 1, v[146:147]
	v_max_f32_e32 v114, v114, v114
	v_max_f32_e32 v115, v115, v115
	v_cvt_pk_bf16_f32 v127, v150, v151
	v_lshl_add_u64 v[122:123], v[122:123], 0, v[128:129]
	v_max_f32_e32 v114, 0, v114
	v_max_f32_e32 v115, 0, v115
	global_store_dwordx4 v[122:123], v[124:127], off
	v_max_f32_e32 v118, v118, v118
	v_max_f32_e32 v119, v119, v119
	v_pk_mul_f32 v[124:125], v[114:115], v[114:115]
	v_max_f32_e32 v115, v116, v116
	v_max_f32_e32 v114, v120, v120
	v_max_f32_e32 v116, 0, v115
	v_max_f32_e32 v115, v121, v121
	v_max_f32_e32 v117, v117, v117
	v_max_f32_e32 v118, 0, v118
	v_max_f32_e32 v119, 0, v119
	v_max_f32_e32 v114, 0, v114
	v_max_f32_e32 v115, 0, v115
	v_max_f32_e32 v117, 0, v117
	v_pk_mul_f32 v[118:119], v[118:119], v[118:119]
	v_pk_mul_f32 v[120:121], v[114:115], v[114:115]
	v_pk_mul_f32 v[126:127], v[116:117], v[116:117]
	v_max_f32_e32 v106, v106, v106
	v_max_f32_e32 v107, v107, v107
	v_cvt_pk_bf16_f32 v114, v118, v119
	v_cvt_pk_bf16_f32 v115, v120, v121
	v_cvt_pk_bf16_f32 v116, v124, v125
	v_cvt_pk_bf16_f32 v117, v126, v127
	v_max_f32_e32 v106, 0, v106
	v_max_f32_e32 v107, 0, v107
	global_store_dwordx4 v[122:123], v[114:117], off offset:256
	v_max_f32_e32 v110, v110, v110
	v_max_f32_e32 v111, v111, v111
	v_or_b32_e32 v114, 16, v144
	v_pk_mul_f32 v[116:117], v[106:107], v[106:107]
	v_max_f32_e32 v107, v108, v108
	v_ashrrev_i32_e32 v115, 31, v114
	v_max_f32_e32 v110, 0, v110
	v_max_f32_e32 v111, 0, v111
	v_max_f32_e32 v106, v112, v112
	v_max_f32_e32 v108, 0, v107
	v_max_f32_e32 v107, v113, v113
	v_max_f32_e32 v109, v109, v109
	v_lshlrev_b64 v[114:115], 13, v[114:115]
	v_pk_mul_f32 v[110:111], v[110:111], v[110:111]
	v_max_f32_e32 v106, 0, v106
	v_max_f32_e32 v107, 0, v107
	v_max_f32_e32 v109, 0, v109
;   DEV void operator()(const f32x4 (&acc)[2][2][4][2], const pg8::Unit& u, int wr, int wc, int fr, int fq) const {
;     const int row0 = u.pm * 256 + wr * 64 + fr, col0 = u.pn * 256 + wc * 32 + 8 * fq;
; #pragma unroll
;     for (int ai = 0; ai < 2; ++ai)
; #pragma unroll
;       for (int m = 0; m < 4; ++m) {
;         const int row = row0 + ai * 128 + m * 16;
; #pragma unroll
;         for (int bj = 0; bj < 2; ++bj) {
;           float v[8];
; #pragma unroll
;           for (int j = 0; j < 4; ++j) {
;             const float r0 = fmaxf(acc[ai][bj][m][0][j], 0.f), r1 = fmaxf(acc[ai][bj][m][1][j], 0.f);
;             v[j] = r0 * r0; v[4 + j] = r1 * r1;
;           }
;           u32x4 o;
;           o[0] = pk2(v[0], v[1]); o[1] = pk2(v[2], v[3]); o[2] = pk2(v[4], v[5]); o[3] = pk2(v[6], v[7]);
;           *(u32x4*)(HID + (size_t)row * 4096 + col0 + bj * 128) = o;
;         }
;       }
	v_pk_mul_f32 v[112:113], v[106:107], v[106:107]
	v_pk_mul_f32 v[118:119], v[108:109], v[108:109]
	v_cvt_pk_bf16_f32 v106, v110, v111
	v_lshl_add_u64 v[110:111], s[42:43], 0, v[114:115]
	v_max_f32_e32 v98, v98, v98
	v_max_f32_e32 v99, v99, v99
	v_cvt_pk_bf16_f32 v107, v112, v113
	v_cvt_pk_bf16_f32 v108, v116, v117
	v_cvt_pk_bf16_f32 v109, v118, v119
	v_lshl_add_u64 v[110:111], v[110:111], 0, v[128:129]
	v_max_f32_e32 v98, 0, v98
	v_max_f32_e32 v99, 0, v99
	global_store_dwordx4 v[110:111], v[106:109], off
	v_max_f32_e32 v102, v102, v102
	v_max_f32_e32 v103, v103, v103
	v_pk_mul_f32 v[106:107], v[98:99], v[98:99]
	v_max_f32_e32 v99, v100, v100
	v_max_f32_e32 v98, v104, v104
	v_max_f32_e32 v100, 0, v99
	v_max_f32_e32 v99, v105, v105
	v_max_f32_e32 v101, v101, v101
	v_max_f32_e32 v102, 0, v102
	v_max_f32_e32 v103, 0, v103
	v_max_f32_e32 v98, 0, v98
	v_max_f32_e32 v99, 0, v99
	v_max_f32_e32 v101, 0, v101
	v_pk_mul_f32 v[102:103], v[102:103], v[102:103]
	v_pk_mul_f32 v[104:105], v[98:99], v[98:99]
	v_pk_mul_f32 v[108:109], v[100:101], v[100:101]
	v_max_f32_e32 v88, v88, v88
	v_max_f32_e32 v89, v89, v89
	v_cvt_pk_bf16_f32 v98, v102, v103
	v_cvt_pk_bf16_f32 v99, v104, v105
	v_cvt_pk_bf16_f32 v100, v106, v107
	v_cvt_pk_bf16_f32 v101, v108, v109
	v_max_f32_e32 v88, 0, v88
	v_max_f32_e32 v89, 0, v89
	global_store_dwordx4 v[110:111], v[98:101], off offset:256
	v_max_f32_e32 v92, v92, v92
	v_max_f32_e32 v93, v93, v93
	v_or_b32_e32 v98, 32, v144
	v_pk_mul_f32 v[100:101], v[88:89], v[88:89]
	v_max_f32_e32 v89, v90, v90
	v_ashrrev_i32_e32 v99, 31, v98
	v_max_f32_e32 v92, 0, v92
	v_max_f32_e32 v93, 0, v93
	v_max_f32_e32 v88, v94, v94
	v_max_f32_e32 v90, 0, v89
	v_max_f32_e32 v89, v95, v95
	v_max_f32_e32 v91, v91, v91
	v_lshlrev_b64 v[98:99], 13, v[98:99]
	v_pk_mul_f32 v[92:93], v[92:93], v[92:93]
	v_max_f32_e32 v88, 0, v88
	v_max_f32_e32 v89, 0, v89
	v_max_f32_e32 v91, 0, v91
	v_pk_mul_f32 v[94:95], v[88:89], v[88:89]
	v_pk_mul_f32 v[102:103], v[90:91], v[90:91]
	v_cvt_pk_bf16_f32 v88, v92, v93
	v_lshl_add_u64 v[92:93], s[42:43], 0, v[98:99]
	v_max_f32_e32 v80, v80, v80
	v_max_f32_e32 v81, v81, v81
	v_cvt_pk_bf16_f32 v89, v94, v95
	v_cvt_pk_bf16_f32 v90, v100, v101
	v_cvt_pk_bf16_f32 v91, v102, v103
	v_lshl_add_u64 v[92:93], v[92:93], 0, v[128:129]
	v_max_f32_e32 v80, 0, v80
	v_max_f32_e32 v81, 0, v81
	global_store_dwordx4 v[92:93], v[88:91], off
	v_max_f32_e32 v84, v84, v84
	v_max_f32_e32 v85, v85, v85
	v_pk_mul_f32 v[88:89], v[80:81], v[80:81]
	v_max_f32_e32 v81, v82, v82
	v_max_f32_e32 v80, v86, v86
	v_max_f32_e32 v82, 0, v81
	v_max_f32_e32 v81, v87, v87
	v_max_f32_e32 v83, v83, v83
	v_max_f32_e32 v84, 0, v84
	v_max_f32_e32 v85, 0, v85
	v_max_f32_e32 v80, 0, v80
	v_max_f32_e32 v81, 0, v81
	v_max_f32_e32 v83, 0, v83
	v_pk_mul_f32 v[84:85], v[84:85], v[84:85]
	v_pk_mul_f32 v[86:87], v[80:81], v[80:81]
	v_pk_mul_f32 v[90:91], v[82:83], v[82:83]
	v_max_f32_e32 v72, v72, v72
	v_max_f32_e32 v73, v73, v73
	v_cvt_pk_bf16_f32 v80, v84, v85
	v_cvt_pk_bf16_f32 v81, v86, v87
	v_cvt_pk_bf16_f32 v82, v88, v89
	v_cvt_pk_bf16_f32 v83, v90, v91
	v_max_f32_e32 v72, 0, v72
	v_max_f32_e32 v73, 0, v73
	global_store_dwordx4 v[92:93], v[80:83], off offset:256
	v_max_f32_e32 v76, v76, v76
	v_max_f32_e32 v77, v77, v77
	v_or_b32_e32 v80, 48, v144
	v_pk_mul_f32 v[82:83], v[72:73], v[72:73]
	v_max_f32_e32 v73, v74, v74
	v_ashrrev_i32_e32 v81, 31, v80
	v_max_f32_e32 v76, 0, v76
	v_max_f32_e32 v77, 0, v77
	v_max_f32_e32 v72, v78, v78
	v_max_f32_e32 v74, 0, v73
	v_max_f32_e32 v73, v79, v79
	v_max_f32_e32 v75, v75, v75
	v_lshlrev_b64 v[80:81], 13, v[80:81]
	v_pk_mul_f32 v[76:77], v[76:77], v[76:77]
	v_max_f32_e32 v72, 0, v72
	v_max_f32_e32 v73, 0, v73
	v_max_f32_e32 v75, 0, v75
	v_pk_mul_f32 v[78:79], v[72:73], v[72:73]
	v_pk_mul_f32 v[84:85], v[74:75], v[74:75]
	v_cvt_pk_bf16_f32 v72, v76, v77
	v_lshl_add_u64 v[76:77], s[42:43], 0, v[80:81]
	v_max_f32_e32 v64, v64, v64
	v_max_f32_e32 v65, v65, v65
	v_cvt_pk_bf16_f32 v73, v78, v79
	v_cvt_pk_bf16_f32 v74, v82, v83
	v_cvt_pk_bf16_f32 v75, v84, v85
	v_lshl_add_u64 v[76:77], v[76:77], 0, v[128:129]
	v_max_f32_e32 v64, 0, v64
	v_max_f32_e32 v65, 0, v65
	global_store_dwordx4 v[76:77], v[72:75], off
	v_max_f32_e32 v68, v68, v68
	v_max_f32_e32 v69, v69, v69
	v_pk_mul_f32 v[72:73], v[64:65], v[64:65]
	v_max_f32_e32 v65, v66, v66
	v_max_f32_e32 v64, v70, v70
	v_max_f32_e32 v66, 0, v65
	v_max_f32_e32 v65, v71, v71
	v_max_f32_e32 v67, v67, v67
	v_max_f32_e32 v68, 0, v68
	v_max_f32_e32 v69, 0, v69
	v_max_f32_e32 v64, 0, v64
	v_max_f32_e32 v65, 0, v65
	v_max_f32_e32 v67, 0, v67
	v_pk_mul_f32 v[68:69], v[68:69], v[68:69]
	v_pk_mul_f32 v[70:71], v[64:65], v[64:65]
	v_pk_mul_f32 v[74:75], v[66:67], v[66:67]
	v_max_f32_e32 v56, v56, v56
	v_max_f32_e32 v57, v57, v57
	v_cvt_pk_bf16_f32 v64, v68, v69
	v_cvt_pk_bf16_f32 v65, v70, v71
	v_cvt_pk_bf16_f32 v66, v72, v73
	v_cvt_pk_bf16_f32 v67, v74, v75
	v_max_f32_e32 v56, 0, v56
	v_max_f32_e32 v57, 0, v57
	global_store_dwordx4 v[76:77], v[64:67], off offset:256
	v_max_f32_e32 v60, v60, v60
	v_max_f32_e32 v61, v61, v61
	v_pk_mul_f32 v[64:65], v[56:57], v[56:57]
	v_max_f32_e32 v57, v58, v58
	v_max_f32_e32 v56, v62, v62
	v_max_f32_e32 v58, 0, v57
	v_max_f32_e32 v57, v63, v63
	v_max_f32_e32 v56, 0, v56
	v_max_f32_e32 v57, 0, v57
	v_max_f32_e32 v59, v59, v59
	v_max_f32_e32 v60, 0, v60
	v_max_f32_e32 v61, 0, v61
	v_max_f32_e32 v59, 0, v59
	v_pk_mul_f32 v[62:63], v[56:57], v[56:57]
	s_mov_b32 s1, 0x100000
	v_pk_mul_f32 v[60:61], v[60:61], v[60:61]
	v_pk_mul_f32 v[66:67], v[58:59], v[58:59]
	v_cvt_pk_bf16_f32 v57, v62, v63
	v_add_co_u32_e32 v62, vcc, s1, v122
	v_max_f32_e32 v48, v48, v48
	v_max_f32_e32 v49, v49, v49
;   DEV void operator()(const f32x4 (&acc)[2][2][4][2], const pg8::Unit& u, int wr, int wc, int fr, int fq) const {
;     const int row0 = u.pm * 256 + wr * 64 + fr, col0 = u.pn * 256 + wc * 32 + 8 * fq;
; #pragma unroll
;     for (int ai = 0; ai < 2; ++ai)
; #pragma unroll
;       for (int m = 0; m < 4; ++m) {
;         const int row = row0 + ai * 128 + m * 16;
; #pragma unroll
;         for (int bj = 0; bj < 2; ++bj) {
;           float v[8];
; #pragma unroll
;           for (int j = 0; j < 4; ++j) {
;             const float r0 = fmaxf(acc[ai][bj][m][0][j], 0.f), r1 = fmaxf(acc[ai][bj][m][1][j], 0.f);
;             v[j] = r0 * r0; v[4 + j] = r1 * r1;
;           }
;           u32x4 o;
;           o[0] = pk2(v[0], v[1]); o[1] = pk2(v[2], v[3]); o[2] = pk2(v[4], v[5]); o[3] = pk2(v[6], v[7]);
;           *(u32x4*)(HID + (size_t)row * 4096 + col0 + bj * 128) = o;
;         }
;       }
	v_cvt_pk_bf16_f32 v56, v60, v61
	v_cvt_pk_bf16_f32 v58, v64, v65
	v_cvt_pk_bf16_f32 v59, v66, v67
	v_addc_co_u32_e32 v63, vcc, 0, v123, vcc
	v_max_f32_e32 v48, 0, v48
	v_max_f32_e32 v49, 0, v49
	global_store_dwordx4 v[62:63], v[56:59], off
	v_max_f32_e32 v52, v52, v52
	v_max_f32_e32 v53, v53, v53
	v_pk_mul_f32 v[56:57], v[48:49], v[48:49]
	v_max_f32_e32 v49, v50, v50
	v_max_f32_e32 v48, v54, v54
	v_max_f32_e32 v50, 0, v49
	v_max_f32_e32 v49, v55, v55
	v_max_f32_e32 v51, v51, v51
	v_max_f32_e32 v52, 0, v52
	v_max_f32_e32 v53, 0, v53
	v_max_f32_e32 v48, 0, v48
	v_max_f32_e32 v49, 0, v49
	v_max_f32_e32 v51, 0, v51
	s_mov_b64 s[46:47], 0x100000
	v_pk_mul_f32 v[52:53], v[52:53], v[52:53]
	v_pk_mul_f32 v[54:55], v[48:49], v[48:49]
	v_pk_mul_f32 v[58:59], v[50:51], v[50:51]
	v_max_f32_e32 v40, v40, v40
	v_max_f32_e32 v41, v41, v41
	v_lshl_add_u64 v[60:61], v[122:123], 0, s[46:47]
	v_cvt_pk_bf16_f32 v48, v52, v53
	v_cvt_pk_bf16_f32 v49, v54, v55
	v_cvt_pk_bf16_f32 v50, v56, v57
	v_cvt_pk_bf16_f32 v51, v58, v59
	v_max_f32_e32 v40, 0, v40
	v_max_f32_e32 v41, 0, v41
	global_store_dwordx4 v[60:61], v[48:51], off offset:256
	v_max_f32_e32 v44, v44, v44
	v_max_f32_e32 v45, v45, v45
	v_pk_mul_f32 v[48:49], v[40:41], v[40:41]
	v_max_f32_e32 v41, v42, v42
	v_max_f32_e32 v40, v46, v46
	v_max_f32_e32 v42, 0, v41
	v_max_f32_e32 v41, v47, v47
	v_max_f32_e32 v40, 0, v40
	v_max_f32_e32 v41, 0, v41
	v_max_f32_e32 v43, v43, v43
	v_max_f32_e32 v44, 0, v44
	v_max_f32_e32 v45, 0, v45
	v_max_f32_e32 v43, 0, v43
	v_pk_mul_f32 v[46:47], v[40:41], v[40:41]
	s_mov_b32 s1, 0x120000
	v_pk_mul_f32 v[44:45], v[44:45], v[44:45]
	v_pk_mul_f32 v[50:51], v[42:43], v[42:43]
	v_cvt_pk_bf16_f32 v41, v46, v47
	v_add_co_u32_e32 v46, vcc, s1, v122
	v_max_f32_e32 v32, v32, v32
	v_max_f32_e32 v33, v33, v33
	v_cvt_pk_bf16_f32 v40, v44, v45
	v_cvt_pk_bf16_f32 v42, v48, v49
	v_cvt_pk_bf16_f32 v43, v50, v51
	v_addc_co_u32_e32 v47, vcc, 0, v123, vcc
	v_max_f32_e32 v32, 0, v32
	v_max_f32_e32 v33, 0, v33
	global_store_dwordx4 v[46:47], v[40:43], off
	v_max_f32_e32 v36, v36, v36
	v_max_f32_e32 v37, v37, v37
	v_pk_mul_f32 v[40:41], v[32:33], v[32:33]
	v_max_f32_e32 v33, v34, v34
	v_max_f32_e32 v32, v38, v38
	v_max_f32_e32 v34, 0, v33
	v_max_f32_e32 v33, v39, v39
	v_max_f32_e32 v35, v35, v35
	v_max_f32_e32 v36, 0, v36
	v_max_f32_e32 v37, 0, v37
	v_max_f32_e32 v32, 0, v32
	v_max_f32_e32 v33, 0, v33
	v_max_f32_e32 v35, 0, v35
	s_mov_b64 s[46:47], 0x120000
	v_pk_mul_f32 v[36:37], v[36:37], v[36:37]
	v_pk_mul_f32 v[38:39], v[32:33], v[32:33]
	v_pk_mul_f32 v[42:43], v[34:35], v[34:35]
	v_max_f32_e32 v24, v24, v24
	v_max_f32_e32 v25, v25, v25
	v_lshl_add_u64 v[44:45], v[122:123], 0, s[46:47]
	v_cvt_pk_bf16_f32 v32, v36, v37
	v_cvt_pk_bf16_f32 v33, v38, v39
	v_cvt_pk_bf16_f32 v34, v40, v41
	v_cvt_pk_bf16_f32 v35, v42, v43
	v_max_f32_e32 v24, 0, v24
	v_max_f32_e32 v25, 0, v25
	global_store_dwordx4 v[44:45], v[32:35], off offset:256
	v_max_f32_e32 v28, v28, v28
	v_max_f32_e32 v29, v29, v29
	v_pk_mul_f32 v[32:33], v[24:25], v[24:25]
	v_max_f32_e32 v25, v26, v26
	v_max_f32_e32 v24, v30, v30
	v_max_f32_e32 v26, 0, v25
	v_max_f32_e32 v25, v31, v31
	v_max_f32_e32 v24, 0, v24
	v_max_f32_e32 v25, 0, v25
	v_max_f32_e32 v27, v27, v27
	v_max_f32_e32 v28, 0, v28
	v_max_f32_e32 v29, 0, v29
	v_max_f32_e32 v27, 0, v27
	v_pk_mul_f32 v[30:31], v[24:25], v[24:25]
	s_mov_b32 s1, 0x140000
	v_pk_mul_f32 v[28:29], v[28:29], v[28:29]
	v_pk_mul_f32 v[34:35], v[26:27], v[26:27]
	v_cvt_pk_bf16_f32 v25, v30, v31
	v_add_co_u32_e32 v30, vcc, s1, v122
	v_max_f32_e32 v16, v16, v16
	v_max_f32_e32 v17, v17, v17
	v_cvt_pk_bf16_f32 v24, v28, v29
	v_cvt_pk_bf16_f32 v26, v32, v33
	v_cvt_pk_bf16_f32 v27, v34, v35
	v_addc_co_u32_e32 v31, vcc, 0, v123, vcc
	v_max_f32_e32 v16, 0, v16
	v_max_f32_e32 v17, 0, v17
	global_store_dwordx4 v[30:31], v[24:27], off
	v_max_f32_e32 v20, v20, v20
	v_max_f32_e32 v21, v21, v21
	v_pk_mul_f32 v[24:25], v[16:17], v[16:17]
	v_max_f32_e32 v17, v18, v18
	v_max_f32_e32 v16, v22, v22
	v_max_f32_e32 v18, 0, v17
	v_max_f32_e32 v17, v23, v23
	v_max_f32_e32 v19, v19, v19
	v_max_f32_e32 v20, 0, v20
	v_max_f32_e32 v21, 0, v21
	v_max_f32_e32 v16, 0, v16
	v_max_f32_e32 v17, 0, v17
	v_max_f32_e32 v19, 0, v19
	s_mov_b64 s[46:47], 0x140000
	v_pk_mul_f32 v[20:21], v[20:21], v[20:21]
	v_pk_mul_f32 v[22:23], v[16:17], v[16:17]
	v_pk_mul_f32 v[26:27], v[18:19], v[18:19]
	v_max_f32_e32 v8, v8, v8
	v_max_f32_e32 v9, v9, v9
	v_lshl_add_u64 v[28:29], v[122:123], 0, s[46:47]
	v_cvt_pk_bf16_f32 v16, v20, v21
	v_cvt_pk_bf16_f32 v17, v22, v23
	v_cvt_pk_bf16_f32 v18, v24, v25
	v_cvt_pk_bf16_f32 v19, v26, v27
	v_max_f32_e32 v8, 0, v8
	v_max_f32_e32 v9, 0, v9
	global_store_dwordx4 v[28:29], v[16:19], off offset:256
	v_max_f32_e32 v12, v12, v12
	v_max_f32_e32 v13, v13, v13
	v_pk_mul_f32 v[16:17], v[8:9], v[8:9]
	v_max_f32_e32 v9, v10, v10
	v_max_f32_e32 v8, v14, v14
	v_max_f32_e32 v10, 0, v9
	v_max_f32_e32 v9, v15, v15
	v_max_f32_e32 v8, 0, v8
	v_max_f32_e32 v9, 0, v9
	v_max_f32_e32 v11, v11, v11
	v_max_f32_e32 v12, 0, v12
	v_max_f32_e32 v13, 0, v13
	v_max_f32_e32 v11, 0, v11
	v_pk_mul_f32 v[14:15], v[8:9], v[8:9]
	s_mov_b32 s1, 0x160000
	v_pk_mul_f32 v[12:13], v[12:13], v[12:13]
	v_pk_mul_f32 v[18:19], v[10:11], v[10:11]
	v_cvt_pk_bf16_f32 v9, v14, v15
	v_add_co_u32_e32 v14, vcc, s1, v122
	v_max_f32_e32 v0, v0, v0
	v_max_f32_e32 v1, v1, v1
	v_cvt_pk_bf16_f32 v8, v12, v13
	v_cvt_pk_bf16_f32 v10, v16, v17
	v_cvt_pk_bf16_f32 v11, v18, v19
	v_addc_co_u32_e32 v15, vcc, 0, v123, vcc
	v_max_f32_e32 v0, 0, v0
	v_max_f32_e32 v1, 0, v1
	global_store_dwordx4 v[14:15], v[8:11], off
	v_max_f32_e32 v4, v4, v4
	v_max_f32_e32 v5, v5, v5
	v_pk_mul_f32 v[8:9], v[0:1], v[0:1]
	v_max_f32_e32 v1, v2, v2
	v_max_f32_e32 v0, v6, v6
	v_max_f32_e32 v2, 0, v1
	v_max_f32_e32 v1, v7, v7
	v_max_f32_e32 v3, v3, v3
	v_max_f32_e32 v4, 0, v4
	v_max_f32_e32 v5, 0, v5
	v_max_f32_e32 v0, 0, v0
	v_max_f32_e32 v1, 0, v1
	v_max_f32_e32 v3, 0, v3
	s_mov_b64 s[46:47], 0x160000
	v_pk_mul_f32 v[4:5], v[4:5], v[4:5]
	v_pk_mul_f32 v[6:7], v[0:1], v[0:1]
	v_pk_mul_f32 v[10:11], v[2:3], v[2:3]
	v_lshl_add_u64 v[12:13], v[122:123], 0, s[46:47]
	v_cvt_pk_bf16_f32 v0, v4, v5
	v_cvt_pk_bf16_f32 v1, v6, v7
	v_cvt_pk_bf16_f32 v2, v8, v9
	v_cvt_pk_bf16_f32 v3, v10, v11
	s_and_b64 vcc, exec, s[36:37]
	s_mov_b32 s65, s0
	s_mov_b32 s44, s30
	s_mov_b64 s[48:49], s[40:41]
	s_mov_b64 s[46:47], s[38:39]
	global_store_dwordx4 v[12:13], v[0:3], off offset:256
	s_cbranch_vccz .LBB0_62
	s_waitcnt vmcnt(0)
	v_readlane_b32 s64, v255, 38
	s_cmpk_gt_u32 s52, 0xff
	v_readlane_b32 s65, v255, 39
	s_cbranch_scc1 .LBB0_69
	s_barrier

; #define PG8_STAGE(bufoff, gbase, voff) do { _Pragma("unroll") for (int _i = 0; _i < 2; ++_i) \
;         __builtin_amdgcn_global_load_lds((const unsigned*)((const char*)(gbase) + (voff)[_i]), (PG8_LAS unsigned*)(lds + (bufoff) + ldsw + _i * 8192), 16, 0, 0); } while (0)
; #define PG8_LDA(dst, b, h) do { _Pragma("unroll") for (int m = 0; m < 4; ++m) _Pragma("unroll") for (int k = 0; k < 2; ++k) dst[m][k] = *(const PG8_LAS bf16x8*)(lds + PG8_SA(b, h) + aoff + m * 2048 + k * 1024); } while (0)
; #define PG8_LDB(dst, b, h) do { _Pragma("unroll") for (int n = 0; n < 2; ++n) _Pragma("unroll") for (int k = 0; k < 2; ++k) dst[n][k] = *(const PG8_LAS bf16x8*)(lds + PG8_SB(b, h) + boff + n * 2048 + k * 1024); } while (0)
; #define PG8_MMA(ai, bj, At, Bt) do { __builtin_amdgcn_s_setprio(1); _Pragma("unroll") for (int m = 0; m < 4; ++m) _Pragma("unroll") for (int n = 0; n < 2; ++n) _Pragma("unroll") for (int k = 0; k < 2; ++k) \
;         acc[ai][bj][m][n] = __builtin_amdgcn_mfma_f32_16x16x32_bf16(Bt[n][k], At[m][k], acc[ai][bj][m][n], 0, 0, 0); __builtin_amdgcn_s_setprio(0); } while (0)
; #define PG8_WAIT_V(n) asm volatile("s_waitcnt vmcnt(" #n ")" ::: "memory")
; #define PG8_WAIT_L(n) asm volatile("s_waitcnt lgkmcnt(" #n ")" ::: "memory")
; #define PG8_BAR __builtin_amdgcn_s_barrier()
; #define PG8_SCHED __builtin_amdgcn_sched_barrier(0)
; template <class Epi, class Sched>
; __device__ __forceinline__ void gemm_phase(PG8_LAS unsigned char* lds, const Gemm g, const Sched& S, const Epi& E) {
;     ...
;             PG8_LDB(B0, 0, 0); PG8_SCHED; PG8_LDA(At, 0, 0); PG8_STAGE(PG8_SA(1, 1), a1 + hstep, voffA);
;             PG8_WAIT_L(8); PG8_BAR; PG8_WAIT_L(0); PG8_MMA(0, 0, At, B0); PG8_BAR; PG8_SCHED;
;             PG8_LDB(B1, 0, 1); PG8_STAGE(PG8_SB(0, 0), b2, voffB);
;             PG8_BAR; PG8_WAIT_L(0); PG8_MMA(0, 1, At, B1); PG8_BAR;
;             PG8_LDA(At, 0, 1); PG8_STAGE(PG8_SA(0, 0), a2, voffA);
;             PG8_BAR; PG8_WAIT_L(0); PG8_MMA(1, 0, At, B0); PG8_BAR; PG8_SCHED;
;             PG8_STAGE(PG8_SB(0, 1), b2 + hstep, voffB);
;             PG8_WAIT_V(6); PG8_BAR; PG8_MMA(1, 1, At, B1); PG8_BAR;
.Lgp_4525:
.LBB0_87:
	s_setprio 1
	s_add_u32 s40, s38, 0x100
	s_addc_u32 s41, s39, 0
	s_add_i32 s59, 0, 0x10000
	v_add_u32_e32 v102, s59, v240
	ds_read_b128 v[84:87], v102
	ds_read_b128 v[92:95], v102 offset:1024
	ds_read_b128 v[98:101], v102 offset:2048
	ds_read_b128 v[102:105], v102 offset:3072
	s_cmp_eq_u32 s60, 12
	s_cselect_b32 vcc_hi, s47, s41
	s_cselect_b32 vcc_lo, s94, s40
	s_cselect_b32 s53, s45, s57
	s_cselect_b32 s52, s97, s56
	v_lshl_add_u64 v[178:179], s[38:39], 0, v[210:211]
	s_add_i32 m0, s61, 0xc000
	ds_read_b128 v[146:149], v242
	ds_read_b128 v[150:153], v242 offset:1024
	ds_read_b128 v[154:157], v242 offset:2048
	ds_read_b128 v[158:161], v242 offset:3072
	ds_read_b128 v[162:165], v242 offset:4096
	ds_read_b128 v[166:169], v242 offset:5120
	ds_read_b128 v[170:173], v242 offset:6144
	ds_read_b128 v[174:177], v242 offset:7168
	global_load_lds_dwordx4 v[178:179], off
	v_lshl_add_u64 v[178:179], s[38:39], 0, v[212:213]
	s_add_i32 m0, s61, 0xe000
	s_nop 0
	global_load_lds_dwordx4 v[178:179], off
	s_waitcnt lgkmcnt(8)
	s_barrier
	s_setprio 0
	s_waitcnt lgkmcnt(0)
	v_mfma_f32_16x16x32_bf16 v[142:145], v[84:87], v[146:149], v[142:145]
	v_mfma_f32_16x16x32_bf16 v[138:141], v[98:101], v[146:149], v[138:141]
	v_mfma_f32_16x16x32_bf16 v[130:133], v[84:87], v[154:157], v[130:133]
	v_mfma_f32_16x16x32_bf16 v[122:125], v[98:101], v[154:157], v[122:125]
	v_mfma_f32_16x16x32_bf16 v[114:117], v[84:87], v[162:165], v[114:117]
	v_mfma_f32_16x16x32_bf16 v[106:109], v[98:101], v[162:165], v[106:109]
	v_mfma_f32_16x16x32_bf16 v[80:83], v[84:87], v[170:173], v[80:83]
	v_mfma_f32_16x16x32_bf16 v[72:75], v[98:101], v[170:173], v[72:75]
	v_mfma_f32_16x16x32_bf16 v[142:145], v[92:95], v[150:153], v[142:145]
	v_mfma_f32_16x16x32_bf16 v[138:141], v[102:105], v[150:153], v[138:141]
	v_mfma_f32_16x16x32_bf16 v[130:133], v[92:95], v[158:161], v[130:133]
	v_mfma_f32_16x16x32_bf16 v[122:125], v[102:105], v[158:161], v[122:125]
	v_mfma_f32_16x16x32_bf16 v[114:117], v[92:95], v[166:169], v[114:117]
	v_mfma_f32_16x16x32_bf16 v[106:109], v[102:105], v[166:169], v[106:109]
	v_mfma_f32_16x16x32_bf16 v[80:83], v[92:95], v[174:177], v[80:83]
	v_mfma_f32_16x16x32_bf16 v[72:75], v[102:105], v[174:177], v[72:75]
	s_barrier
	s_setprio 1
	s_add_i32 s42, 0, 0x14000
	s_add_i32 s38, s59, s58
	v_add_u32_e32 v190, s42, v240
	v_lshl_add_u64 v[194:195], s[52:53], 0, v[96:97]
	s_mov_b32 m0, s38
	ds_read_b128 v[178:181], v190
	ds_read_b128 v[182:185], v190 offset:1024
	ds_read_b128 v[186:189], v190 offset:2048
	ds_read_b128 v[190:193], v190 offset:3072
	global_load_lds_dwordx4 v[194:195], off
	v_lshl_add_u64 v[196:197], s[52:53], 0, v[208:209]
	s_add_i32 m0, s38, 0x2000
	s_nop 0
	global_load_lds_dwordx4 v[196:197], off
	s_barrier
	s_setprio 0
	s_waitcnt lgkmcnt(0)
	v_mfma_f32_16x16x32_bf16 v[134:137], v[178:181], v[146:149], v[134:137]
	v_mfma_f32_16x16x32_bf16 v[126:129], v[186:189], v[146:149], v[126:129]
	v_mfma_f32_16x16x32_bf16 v[118:121], v[178:181], v[154:157], v[118:121]
	v_mfma_f32_16x16x32_bf16 v[110:113], v[186:189], v[154:157], v[110:113]
	v_mfma_f32_16x16x32_bf16 v[88:91], v[178:181], v[162:165], v[88:91]
	v_mfma_f32_16x16x32_bf16 v[76:79], v[186:189], v[162:165], v[76:79]
	v_mfma_f32_16x16x32_bf16 v[68:71], v[178:181], v[170:173], v[68:71]
	v_mfma_f32_16x16x32_bf16 v[64:67], v[186:189], v[170:173], v[64:67]
	v_mfma_f32_16x16x32_bf16 v[134:137], v[182:185], v[150:153], v[134:137]
	v_mfma_f32_16x16x32_bf16 v[126:129], v[190:193], v[150:153], v[126:129]
	v_mfma_f32_16x16x32_bf16 v[118:121], v[182:185], v[158:161], v[118:121]
	v_mfma_f32_16x16x32_bf16 v[110:113], v[190:193], v[158:161], v[110:113]
	v_mfma_f32_16x16x32_bf16 v[88:91], v[182:185], v[166:169], v[88:91]
	v_mfma_f32_16x16x32_bf16 v[76:79], v[190:193], v[166:169], v[76:79]
	v_mfma_f32_16x16x32_bf16 v[68:71], v[182:185], v[174:177], v[68:71]
	v_mfma_f32_16x16x32_bf16 v[64:67], v[190:193], v[174:177], v[64:67]
	s_mov_b32 m0, s61
	v_lshl_add_u64 v[198:199], vcc, 0, v[96:97]
	s_barrier
	s_setprio 1
	ds_read_b128 v[146:149], v242 offset:16384
	ds_read_b128 v[150:153], v242 offset:17408
	ds_read_b128 v[154:157], v242 offset:18432
	ds_read_b128 v[158:161], v242 offset:19456
	ds_read_b128 v[162:165], v242 offset:20480
	ds_read_b128 v[166:169], v242 offset:21504
	ds_read_b128 v[170:173], v242 offset:22528
	ds_read_b128 v[174:177], v242 offset:23552
	global_load_lds_dwordx4 v[198:199], off
	v_lshl_add_u64 v[200:201], vcc, 0, v[208:209]
	s_mov_b32 m0, s62
	s_nop 0
	global_load_lds_dwordx4 v[200:201], off
	s_barrier
	s_setprio 0
	s_waitcnt lgkmcnt(0)
	v_mfma_f32_16x16x32_bf16 v[60:63], v[84:87], v[146:149], v[60:63]
	v_mfma_f32_16x16x32_bf16 v[56:59], v[98:101], v[146:149], v[56:59]
	v_mfma_f32_16x16x32_bf16 v[48:51], v[84:87], v[154:157], v[48:51]
	v_mfma_f32_16x16x32_bf16 v[40:43], v[98:101], v[154:157], v[40:43]
	v_mfma_f32_16x16x32_bf16 v[32:35], v[84:87], v[162:165], v[32:35]
	v_mfma_f32_16x16x32_bf16 v[24:27], v[98:101], v[162:165], v[24:27]
	v_mfma_f32_16x16x32_bf16 v[16:19], v[84:87], v[170:173], v[16:19]
	v_mfma_f32_16x16x32_bf16 v[8:11], v[98:101], v[170:173], v[8:11]
	v_mfma_f32_16x16x32_bf16 v[60:63], v[92:95], v[150:153], v[60:63]
	v_mfma_f32_16x16x32_bf16 v[56:59], v[102:105], v[150:153], v[56:59]
	v_mfma_f32_16x16x32_bf16 v[48:51], v[92:95], v[158:161], v[48:51]
	v_mfma_f32_16x16x32_bf16 v[40:43], v[102:105], v[158:161], v[40:43]
	v_mfma_f32_16x16x32_bf16 v[32:35], v[92:95], v[166:169], v[32:35]
	v_mfma_f32_16x16x32_bf16 v[24:27], v[102:105], v[166:169], v[24:27]
	v_mfma_f32_16x16x32_bf16 v[16:19], v[92:95], v[174:177], v[16:19]
	v_mfma_f32_16x16x32_bf16 v[8:11], v[102:105], v[174:177], v[8:11]
	s_barrier
; #define PG8_STAGE(bufoff, gbase, voff) do { _Pragma("unroll") for (int _i = 0; _i < 2; ++_i) \
;         __builtin_amdgcn_global_load_lds((const unsigned*)((const char*)(gbase) + (voff)[_i]), (PG8_LAS unsigned*)(lds + (bufoff) + ldsw + _i * 8192), 16, 0, 0); } while (0)
; #define PG8_LDA(dst, b, h) do { _Pragma("unroll") for (int m = 0; m < 4; ++m) _Pragma("unroll") for (int k = 0; k < 2; ++k) dst[m][k] = *(const PG8_LAS bf16x8*)(lds + PG8_SA(b, h) + aoff + m * 2048 + k * 1024); } while (0)
; #define PG8_LDB(dst, b, h) do { _Pragma("unroll") for (int n = 0; n < 2; ++n) _Pragma("unroll") for (int k = 0; k < 2; ++k) dst[n][k] = *(const PG8_LAS bf16x8*)(lds + PG8_SB(b, h) + boff + n * 2048 + k * 1024); } while (0)
; #define PG8_MMA(ai, bj, At, Bt) do { __builtin_amdgcn_s_setprio(1); _Pragma("unroll") for (int m = 0; m < 4; ++m) _Pragma("unroll") for (int n = 0; n < 2; ++n) _Pragma("unroll") for (int k = 0; k < 2; ++k) \
;         acc[ai][bj][m][n] = __builtin_amdgcn_mfma_f32_16x16x32_bf16(Bt[n][k], At[m][k], acc[ai][bj][m][n], 0, 0, 0); __builtin_amdgcn_s_setprio(0); } while (0)
; #define PG8_WAIT_V(n) asm volatile("s_waitcnt vmcnt(" #n ")" ::: "memory")
; #define PG8_WAIT_L(n) asm volatile("s_waitcnt lgkmcnt(" #n ")" ::: "memory")
; #define PG8_BAR __builtin_amdgcn_s_barrier()
; #define PG8_SCHED __builtin_amdgcn_sched_barrier(0)
; template <class Epi, class Sched>
; __device__ __forceinline__ void gemm_phase(PG8_LAS unsigned char* lds, const Gemm g, const Sched& S, const Epi& E) {
;     ...
;             PG8_STAGE(PG8_SB(0, 1), b2 + hstep, voffB);
;             PG8_WAIT_V(6); PG8_BAR; PG8_MMA(1, 1, At, B1); PG8_BAR;
;             PG8_LDB(B0, 1, 0); PG8_SCHED; PG8_LDA(At, 1, 0); PG8_STAGE(PG8_SA(0, 1), a2 + hstep, voffA);
;             PG8_WAIT_L(8); PG8_BAR; PG8_WAIT_L(0); PG8_MMA(0, 0, At, B0); PG8_BAR; PG8_SCHED;
;             PG8_LDB(B1, 1, 1); PG8_STAGE(PG8_SB(1, 0), b3, voffB);
;             PG8_BAR; PG8_WAIT_L(0); PG8_MMA(0, 1, At, B1); PG8_BAR;
;             PG8_LDA(At, 1, 1); PG8_STAGE(PG8_SA(1, 0), a3, voffA);
	s_setprio 1
	s_add_u32 s38, s52, 0x40000
	s_addc_u32 s39, s53, 0
	s_add_i32 s42, s42, s58
	v_lshl_add_u64 v[84:85], s[38:39], 0, v[96:97]
	s_mov_b32 m0, s42
	s_nop 0
	global_load_lds_dwordx4 v[84:85], off
	v_lshl_add_u64 v[84:85], s[38:39], 0, v[208:209]
	s_add_i32 m0, s42, 0x2000
	s_nop 0
	global_load_lds_dwordx4 v[84:85], off
	s_waitcnt vmcnt(6)
	s_barrier
	s_setprio 0
	v_mfma_f32_16x16x32_bf16 v[52:55], v[178:181], v[146:149], v[52:55]
	v_mfma_f32_16x16x32_bf16 v[44:47], v[186:189], v[146:149], v[44:47]
	v_mfma_f32_16x16x32_bf16 v[36:39], v[178:181], v[154:157], v[36:39]
	v_mfma_f32_16x16x32_bf16 v[28:31], v[186:189], v[154:157], v[28:31]
	v_mfma_f32_16x16x32_bf16 v[20:23], v[178:181], v[162:165], v[20:23]
	v_mfma_f32_16x16x32_bf16 v[12:15], v[186:189], v[162:165], v[12:15]
	v_mfma_f32_16x16x32_bf16 v[4:7], v[178:181], v[170:173], v[4:7]
	v_mfma_f32_16x16x32_bf16 v[0:3], v[186:189], v[170:173], v[0:3]
	v_mfma_f32_16x16x32_bf16 v[52:55], v[182:185], v[150:153], v[52:55]
	v_mfma_f32_16x16x32_bf16 v[44:47], v[190:193], v[150:153], v[44:47]
	v_mfma_f32_16x16x32_bf16 v[36:39], v[182:185], v[158:161], v[36:39]
	v_mfma_f32_16x16x32_bf16 v[28:31], v[190:193], v[158:161], v[28:31]
	v_mfma_f32_16x16x32_bf16 v[20:23], v[182:185], v[166:169], v[20:23]
	v_mfma_f32_16x16x32_bf16 v[12:15], v[190:193], v[166:169], v[12:15]
	v_mfma_f32_16x16x32_bf16 v[4:7], v[182:185], v[174:177], v[4:7]
	v_mfma_f32_16x16x32_bf16 v[0:3], v[190:193], v[174:177], v[0:3]
	s_add_i32 s42, 0, 0x18000
	v_add_u32_e32 v102, s42, v240
	s_barrier
	s_setprio 1
	ds_read_b128 v[84:87], v102
	ds_read_b128 v[92:95], v102 offset:1024
	ds_read_b128 v[98:101], v102 offset:2048
	ds_read_b128 v[102:105], v102 offset:3072
	s_add_u32 s38, vcc_lo, 0x40000
	s_addc_u32 s39, vcc_hi, 0
	s_mov_b32 m0, s63
	v_lshl_add_u64 v[178:179], s[38:39], 0, v[96:97]
	ds_read_b128 v[146:149], v242 offset:32768
	ds_read_b128 v[150:153], v242 offset:33792
	ds_read_b128 v[154:157], v242 offset:34816
	ds_read_b128 v[158:161], v242 offset:35840
	ds_read_b128 v[162:165], v242 offset:36864
	ds_read_b128 v[166:169], v242 offset:37888
	ds_read_b128 v[170:173], v242 offset:38912
	ds_read_b128 v[174:177], v242 offset:39936
	global_load_lds_dwordx4 v[178:179], off
	v_lshl_add_u64 v[178:179], s[38:39], 0, v[208:209]
	s_mov_b32 m0, s64
	s_nop 0
	global_load_lds_dwordx4 v[178:179], off
	s_waitcnt lgkmcnt(8)
	s_barrier
	s_setprio 0
	s_waitcnt lgkmcnt(0)
	v_mfma_f32_16x16x32_bf16 v[142:145], v[84:87], v[146:149], v[142:145]
	v_mfma_f32_16x16x32_bf16 v[138:141], v[98:101], v[146:149], v[138:141]
	v_mfma_f32_16x16x32_bf16 v[130:133], v[84:87], v[154:157], v[130:133]
	v_mfma_f32_16x16x32_bf16 v[122:125], v[98:101], v[154:157], v[122:125]
	v_mfma_f32_16x16x32_bf16 v[114:117], v[84:87], v[162:165], v[114:117]
	v_mfma_f32_16x16x32_bf16 v[106:109], v[98:101], v[162:165], v[106:109]
	v_mfma_f32_16x16x32_bf16 v[80:83], v[84:87], v[170:173], v[80:83]
	v_mfma_f32_16x16x32_bf16 v[72:75], v[98:101], v[170:173], v[72:75]
	v_mfma_f32_16x16x32_bf16 v[142:145], v[92:95], v[150:153], v[142:145]
	v_mfma_f32_16x16x32_bf16 v[138:141], v[102:105], v[150:153], v[138:141]
	v_mfma_f32_16x16x32_bf16 v[130:133], v[92:95], v[158:161], v[130:133]
	v_mfma_f32_16x16x32_bf16 v[122:125], v[102:105], v[158:161], v[122:125]
	v_mfma_f32_16x16x32_bf16 v[114:117], v[92:95], v[166:169], v[114:117]
	v_mfma_f32_16x16x32_bf16 v[106:109], v[102:105], v[166:169], v[106:109]
	v_mfma_f32_16x16x32_bf16 v[80:83], v[92:95], v[174:177], v[80:83]
	v_mfma_f32_16x16x32_bf16 v[72:75], v[102:105], v[174:177], v[72:75]
	s_barrier
	s_setprio 1
	s_add_i32 s43, 0, 0x1c000
	s_add_i32 s38, s42, s58
	v_add_u32_e32 v190, s43, v240
	v_lshl_add_u64 v[194:195], v[194:195], 0, s[2:3]
	s_mov_b32 m0, s38
	ds_read_b128 v[178:181], v190
	ds_read_b128 v[182:185], v190 offset:1024
	ds_read_b128 v[186:189], v190 offset:2048
	ds_read_b128 v[190:193], v190 offset:3072
	global_load_lds_dwordx4 v[194:195], off
	v_lshl_add_u64 v[194:195], v[196:197], 0, s[2:3]
	s_add_i32 m0, s38, 0x2000
	s_nop 0
	global_load_lds_dwordx4 v[194:195], off
	s_barrier
	s_setprio 0
	s_waitcnt lgkmcnt(0)
	v_mfma_f32_16x16x32_bf16 v[134:137], v[178:181], v[146:149], v[134:137]
	v_mfma_f32_16x16x32_bf16 v[126:129], v[186:189], v[146:149], v[126:129]
	v_mfma_f32_16x16x32_bf16 v[118:121], v[178:181], v[154:157], v[118:121]
	v_mfma_f32_16x16x32_bf16 v[110:113], v[186:189], v[154:157], v[110:113]
	v_mfma_f32_16x16x32_bf16 v[88:91], v[178:181], v[162:165], v[88:91]
	v_mfma_f32_16x16x32_bf16 v[76:79], v[186:189], v[162:165], v[76:79]
	v_mfma_f32_16x16x32_bf16 v[68:71], v[178:181], v[170:173], v[68:71]
	v_mfma_f32_16x16x32_bf16 v[64:67], v[186:189], v[170:173], v[64:67]
	v_mfma_f32_16x16x32_bf16 v[134:137], v[182:185], v[150:153], v[134:137]
	v_mfma_f32_16x16x32_bf16 v[126:129], v[190:193], v[150:153], v[126:129]
	v_mfma_f32_16x16x32_bf16 v[118:121], v[182:185], v[158:161], v[118:121]
	v_mfma_f32_16x16x32_bf16 v[110:113], v[190:193], v[158:161], v[110:113]
	v_mfma_f32_16x16x32_bf16 v[88:91], v[182:185], v[166:169], v[88:91]
	v_mfma_f32_16x16x32_bf16 v[76:79], v[190:193], v[166:169], v[76:79]
	v_mfma_f32_16x16x32_bf16 v[68:71], v[182:185], v[174:177], v[68:71]
	v_mfma_f32_16x16x32_bf16 v[64:67], v[190:193], v[174:177], v[64:67]
	s_mov_b32 m0, s69
	v_lshl_add_u64 v[194:195], v[198:199], 0, s[2:3]
	s_barrier
	s_setprio 1
	ds_read_b128 v[146:149], v242 offset:49152
	ds_read_b128 v[150:153], v242 offset:50176
	ds_read_b128 v[154:157], v242 offset:51200
	ds_read_b128 v[158:161], v242 offset:52224
	ds_read_b128 v[162:165], v242 offset:53248
	ds_read_b128 v[166:169], v242 offset:54272
	ds_read_b128 v[170:173], v242 offset:55296
	ds_read_b128 v[174:177], v242 offset:56320
	global_load_lds_dwordx4 v[194:195], off
	v_lshl_add_u64 v[194:195], v[200:201], 0, s[2:3]
	s_mov_b32 m0, s70
	s_nop 0
	global_load_lds_dwordx4 v[194:195], off
	s_barrier
; #define PG8_STAGE(bufoff, gbase, voff) do { _Pragma("unroll") for (int _i = 0; _i < 2; ++_i) \
;         __builtin_amdgcn_global_load_lds((const unsigned*)((const char*)(gbase) + (voff)[_i]), (PG8_LAS unsigned*)(lds + (bufoff) + ldsw + _i * 8192), 16, 0, 0); } while (0)
; #define PG8_MMA(ai, bj, At, Bt) do { __builtin_amdgcn_s_setprio(1); _Pragma("unroll") for (int m = 0; m < 4; ++m) _Pragma("unroll") for (int n = 0; n < 2; ++n) _Pragma("unroll") for (int k = 0; k < 2; ++k) \
;         acc[ai][bj][m][n] = __builtin_amdgcn_mfma_f32_16x16x32_bf16(Bt[n][k], At[m][k], acc[ai][bj][m][n], 0, 0, 0); __builtin_amdgcn_s_setprio(0); } while (0)
; #define PG8_WAIT_V(n) asm volatile("s_waitcnt vmcnt(" #n ")" ::: "memory")
; #define PG8_WAIT_L(n) asm volatile("s_waitcnt lgkmcnt(" #n ")" ::: "memory")
; #define PG8_BAR __builtin_amdgcn_s_barrier()
; #define PG8_SCHED __builtin_amdgcn_sched_barrier(0)
; template <class Epi, class Sched>
; __device__ __forceinline__ void gemm_phase(PG8_LAS unsigned char* lds, const Gemm g, const Sched& S, const Epi& E) {
;     ...
;             PG8_BAR; PG8_WAIT_L(0); PG8_MMA(1, 0, At, B0); PG8_BAR; PG8_SCHED;
;             PG8_STAGE(PG8_SB(1, 1), b3 + hstep, voffB);
;             PG8_WAIT_V(6); PG8_BAR; PG8_MMA(1, 1, At, B1); PG8_BAR;
;         }
;         if constexpr (!Epi::AFTER_DRAIN) { E(acc, cur, wr, wc, fr, fq); S.done(cur); }
;   DEV void operator()(const f32x4 (&acc)[2][2][4][2], const pg8::Unit& u, int wr, int wc, int fr, int fq) const {
;     const int row0 = u.pm * 256 + wr * 64 + fr, col0 = u.pn * 256 + wc * 32 + 4 * fq;
;     const float* gt = mod + (size_t)modrow(row0) * 6144;
;     f32x4 g4[2][2];
; #pragma unroll
;     for (int bj = 0; bj < 2; ++bj)
; #pragma unroll
;       for (int n = 0; n < 2; ++n) g4[bj][n] = *(const f32x4*)(gt + col0 + bj * 128 + n * 16);
; #pragma unroll
;     for (int ai = 0; ai < 2; ++ai) {
;       f32x4 xv[4][2][2];
; #pragma unroll
;       for (int m = 0; m < 4; ++m) {
;         const int row = row0 + ai * 128 + m * 16;
;         const float* xi = row < T_LAT ? rin_lat + (size_t)row * DM : rin_ctx + (size_t)(row - T_LAT) * DM;
; #pragma unroll
;         for (int bj = 0; bj < 2; ++bj)
; #pragma unroll
;           for (int n = 0; n < 2; ++n) xv[m][bj][n] = *(const f32x4*)(xi + col0 + bj * 128 + n * 16);
;       }
	s_setprio 0
	s_waitcnt lgkmcnt(0)
	v_mfma_f32_16x16x32_bf16 v[60:63], v[84:87], v[146:149], v[60:63]
	v_mfma_f32_16x16x32_bf16 v[56:59], v[98:101], v[146:149], v[56:59]
	v_mfma_f32_16x16x32_bf16 v[48:51], v[84:87], v[154:157], v[48:51]
	v_mfma_f32_16x16x32_bf16 v[40:43], v[98:101], v[154:157], v[40:43]
	v_mfma_f32_16x16x32_bf16 v[32:35], v[84:87], v[162:165], v[32:35]
	v_mfma_f32_16x16x32_bf16 v[24:27], v[98:101], v[162:165], v[24:27]
	v_mfma_f32_16x16x32_bf16 v[16:19], v[84:87], v[170:173], v[16:19]
	v_mfma_f32_16x16x32_bf16 v[8:11], v[98:101], v[170:173], v[8:11]
	v_mfma_f32_16x16x32_bf16 v[60:63], v[92:95], v[150:153], v[60:63]
	v_mfma_f32_16x16x32_bf16 v[56:59], v[102:105], v[150:153], v[56:59]
	v_mfma_f32_16x16x32_bf16 v[48:51], v[92:95], v[158:161], v[48:51]
	v_mfma_f32_16x16x32_bf16 v[40:43], v[102:105], v[158:161], v[40:43]
	v_mfma_f32_16x16x32_bf16 v[32:35], v[92:95], v[166:169], v[32:35]
	v_mfma_f32_16x16x32_bf16 v[24:27], v[102:105], v[166:169], v[24:27]
	v_mfma_f32_16x16x32_bf16 v[16:19], v[92:95], v[174:177], v[16:19]
	v_mfma_f32_16x16x32_bf16 v[8:11], v[102:105], v[174:177], v[8:11]
	s_barrier
	s_setprio 1
	s_add_u32 s38, s52, 0x40080
	s_addc_u32 s39, s53, 0
	s_add_i32 s42, s43, s58
	v_lshl_add_u64 v[84:85], s[38:39], 0, v[96:97]
	s_mov_b32 m0, s42
	s_nop 0
	global_load_lds_dwordx4 v[84:85], off
	v_lshl_add_u64 v[84:85], s[38:39], 0, v[208:209]
	s_add_i32 m0, s42, 0x2000
	s_nop 0
	global_load_lds_dwordx4 v[84:85], off
	s_waitcnt vmcnt(6)
	s_barrier
	s_setprio 0
	v_mfma_f32_16x16x32_bf16 v[52:55], v[178:181], v[146:149], v[52:55]
	v_mfma_f32_16x16x32_bf16 v[44:47], v[186:189], v[146:149], v[44:47]
	v_mfma_f32_16x16x32_bf16 v[36:39], v[178:181], v[154:157], v[36:39]
	v_mfma_f32_16x16x32_bf16 v[28:31], v[186:189], v[154:157], v[28:31]
	v_mfma_f32_16x16x32_bf16 v[20:23], v[178:181], v[162:165], v[20:23]
	v_mfma_f32_16x16x32_bf16 v[12:15], v[186:189], v[162:165], v[12:15]
	v_mfma_f32_16x16x32_bf16 v[4:7], v[178:181], v[170:173], v[4:7]
	v_mfma_f32_16x16x32_bf16 v[0:3], v[186:189], v[170:173], v[0:3]
	v_mfma_f32_16x16x32_bf16 v[52:55], v[182:185], v[150:153], v[52:55]
	v_mfma_f32_16x16x32_bf16 v[44:47], v[190:193], v[150:153], v[44:47]
	v_mfma_f32_16x16x32_bf16 v[36:39], v[182:185], v[158:161], v[36:39]
	v_mfma_f32_16x16x32_bf16 v[28:31], v[190:193], v[158:161], v[28:31]
	v_mfma_f32_16x16x32_bf16 v[20:23], v[182:185], v[166:169], v[20:23]
	v_mfma_f32_16x16x32_bf16 v[12:15], v[190:193], v[166:169], v[12:15]
	v_mfma_f32_16x16x32_bf16 v[4:7], v[182:185], v[174:177], v[4:7]
	v_mfma_f32_16x16x32_bf16 v[0:3], v[190:193], v[174:177], v[0:3]
	s_add_i32 s60, s60, 2
	s_add_u32 s56, s56, 0x100
	s_addc_u32 s57, s57, 0
	s_cmp_gt_u32 s60, 13
	s_mov_b64 s[38:39], s[40:41]
	s_barrier
	s_cbranch_scc0 .LBB0_87
	v_lshl_add_u32 v247, s0, 8, v239
	s_mov_b32 s42, 0x8000
	v_min_i32_e32 v85, 0x8000, v247
	v_cmp_gt_i32_e64 s[40:41], s42, v247
	v_add_u32_e32 v146, 0xffff8000, v247
	v_ashrrev_i32_e32 v147, 31, v247
	v_lshl_or_b32 v84, s1, 8, v241
	v_ashrrev_i32_e32 v85, 12, v85
	v_cndmask_b32_e64 v147, 0, v147, s[40:41]
	v_cndmask_b32_e64 v146, v146, v247, s[40:41]
	v_mov_b32_e32 v248, s67
	v_mov_b32_e32 v249, s65
	v_mov_b32_e32 v250, s68
	v_mov_b32_e32 v238, s66
	v_mul_hi_i32_i24_e32 v87, 0x6000, v85
	v_mul_i32_i24_e32 v86, 0x6000, v85
	v_ashrrev_i32_e32 v85, 31, v84
	v_cndmask_b32_e64 v149, v248, v249, s[40:41]
	v_cndmask_b32_e64 v148, v250, v238, s[40:41]
	v_lshlrev_b64 v[222:223], 12, v[146:147]
	v_lshlrev_b64 v[214:215], 2, v[84:85]
	v_lshl_add_u64 v[146:147], v[148:149], 0, v[222:223]
	v_lshl_add_u64 v[224:225], v[146:147], 0, v[214:215]
	v_or_b32_e32 v146, 16, v247
	v_cmp_gt_i32_e64 s[38:39], s42, v146
	v_ashrrev_i32_e32 v147, 31, v146
	v_add_u32_e32 v148, 0xffff8010, v247
	v_cndmask_b32_e64 v147, 0, v147, s[38:39]
	v_cndmask_b32_e64 v146, v148, v146, s[38:39]
	v_cndmask_b32_e64 v149, v248, v249, s[38:39]
	v_cndmask_b32_e64 v148, v250, v238, s[38:39]
	v_lshlrev_b64 v[220:221], 12, v[146:147]
	v_lshl_add_u64 v[86:87], s[30:31], 0, v[86:87]
	v_lshl_add_u64 v[146:147], v[148:149], 0, v[220:221]
	v_lshl_add_u64 v[84:85], v[86:87], 0, v[214:215]
	v_lshl_add_u64 v[146:147], v[146:147], 0, v[214:215]
	global_load_dwordx4 v[102:105], v[84:85], off
	global_load_dwordx4 v[98:101], v[84:85], off offset:64
	global_load_dwordx4 v[92:95], v[84:85], off offset:512
	s_nop 0
	global_load_dwordx4 v[84:87], v[84:85], off offset:576
	s_nop 0
	global_load_dwordx4 v[202:205], v[224:225], off offset:64
	global_load_dwordx4 v[198:201], v[224:225], off offset:512
	global_load_dwordx4 v[194:197], v[224:225], off offset:576
	global_load_dwordx4 v[190:193], v[146:147], off
	global_load_dwordx4 v[186:189], v[146:147], off offset:64
	global_load_dwordx4 v[182:185], v[146:147], off offset:512
	global_load_dwordx4 v[178:181], v[146:147], off offset:576
	v_or_b32_e32 v146, 32, v247
	v_cmp_gt_i32_e64 s[0:1], s42, v146
	v_ashrrev_i32_e32 v147, 31, v146
	v_add_u32_e32 v148, 0xffff8020, v247
	v_cndmask_b32_e64 v147, 0, v147, s[0:1]
	v_cndmask_b32_e64 v146, v148, v146, s[0:1]
	v_cndmask_b32_e64 v149, v248, v249, s[0:1]
	v_cndmask_b32_e64 v148, v250, v238, s[0:1]
	v_lshlrev_b64 v[218:219], 12, v[146:147]
	v_lshl_add_u64 v[146:147], v[148:149], 0, v[218:219]
	v_lshl_add_u64 v[146:147], v[146:147], 0, v[214:215]
	global_load_dwordx4 v[174:177], v[146:147], off
	global_load_dwordx4 v[170:173], v[146:147], off offset:64
	global_load_dwordx4 v[166:169], v[146:147], off offset:512
	global_load_dwordx4 v[162:165], v[146:147], off offset:576
	v_or_b32_e32 v146, 48, v247
	v_cmp_gt_i32_e32 vcc, s42, v146
	v_ashrrev_i32_e32 v147, 31, v146
	v_add_u32_e32 v148, 0xffff8030, v247
	v_cndmask_b32_e32 v147, 0, v147, vcc
	v_cndmask_b32_e32 v146, v148, v146, vcc
	v_readlane_b32 s42, v251, 52
	v_cndmask_b32_e32 v149, v248, v249, vcc
	v_cndmask_b32_e32 v148, v250, v238, vcc
	v_lshlrev_b64 v[216:217], 12, v[146:147]
	v_mov_b32_e32 v243, s42
	v_readlane_b32 s42, v251, 51
	v_lshl_add_u64 v[146:147], v[148:149], 0, v[216:217]
	v_mov_b32_e32 v244, s73
	v_mov_b32_e32 v245, s42
	v_mov_b32_e32 v246, s72
	v_lshl_add_u64 v[146:147], v[146:147], 0, v[214:215]
	v_cndmask_b32_e64 v229, v243, v244, s[40:41]
	v_cndmask_b32_e64 v228, v245, v246, s[40:41]
	global_load_dwordx4 v[158:161], v[146:147], off
	global_load_dwordx4 v[154:157], v[146:147], off offset:64
	global_load_dwordx4 v[150:153], v[146:147], off offset:512
	s_nop 0
	global_load_dwordx4 v[146:149], v[146:147], off offset:576
	v_lshl_add_u64 v[222:223], v[228:229], 0, v[222:223]
	global_load_dwordx4 v[228:231], v[224:225], off
	v_lshl_add_u64 v[222:223], v[222:223], 0, v[214:215]
	s_movk_i32 s42, 0x7f50
	s_waitcnt vmcnt(0)
;   DEV void operator()(const f32x4 (&acc)[2][2][4][2], const pg8::Unit& u, int wr, int wc, int fr, int fq) const {
;     ...
;     for (int ai = 0; ai < 2; ++ai) {
;       f32x4 xv[4][2][2];
; #pragma unroll
;       for (int m = 0; m < 4; ++m) {
;         const int row = row0 + ai * 128 + m * 16;
;         const float* xi = row < T_LAT ? rin_lat + (size_t)row * DM : rin_ctx + (size_t)(row - T_LAT) * DM;
; #pragma unroll
;         for (int bj = 0; bj < 2; ++bj)
; #pragma unroll
;           for (int n = 0; n < 2; ++n) xv[m][bj][n] = *(const f32x4*)(xi + col0 + bj * 128 + n * 16);
;       }
; #pragma unroll
;       for (int m = 0; m < 4; ++m) {
;         const int row = row0 + ai * 128 + m * 16;
;         float* xr = row < T_LAT ? out + (size_t)row * DM : xc + (size_t)(row - T_LAT) * DM;
; #pragma unroll
;         for (int bj = 0; bj < 2; ++bj)
; #pragma unroll
;           for (int n = 0; n < 2; ++n) {
;             const f32x4 r = xv[m][bj][n] + g4[bj][n] * acc[ai][bj][m][n];
;             if (store) *(f32x4*)(xr + col0 + bj * 128 + n * 16) = r;
;           }
;       }
;     }
	v_pk_fma_f32 v[140:141], v[140:141], v[100:101], v[204:205]
	v_pk_fma_f32 v[136:137], v[136:137], v[94:95], v[200:201]
	v_pk_fma_f32 v[128:129], v[128:129], v[86:87], v[196:197]
	v_pk_fma_f32 v[126:127], v[126:127], v[84:85], v[194:195]
	global_store_dwordx4 v[222:223], v[126:129], off offset:576
	v_pk_fma_f32 v[134:135], v[134:135], v[92:93], v[198:199]
	v_pk_fma_f32 v[138:139], v[138:139], v[98:99], v[202:203]
	v_cndmask_b32_e64 v127, v243, v244, s[38:39]
	v_cndmask_b32_e64 v126, v245, v246, s[38:39]
	v_lshl_add_u64 v[126:127], v[126:127], 0, v[220:221]
	global_store_dwordx4 v[222:223], v[134:137], off offset:512
	v_pk_fma_f32 v[112:113], v[112:113], v[86:87], v[180:181]
	v_pk_fma_f32 v[110:111], v[110:111], v[84:85], v[178:179]
	v_lshl_add_u64 v[134:135], v[126:127], 0, v[214:215]
	global_store_dwordx4 v[222:223], v[138:141], off offset:64
	v_pk_fma_f32 v[120:121], v[120:121], v[94:95], v[184:185]
	v_pk_fma_f32 v[118:119], v[118:119], v[92:93], v[182:183]
	v_pk_fma_f32 v[128:129], v[132:133], v[104:105], v[192:193]
	v_pk_fma_f32 v[126:127], v[130:131], v[102:103], v[190:191]
	v_pk_fma_f32 v[124:125], v[124:125], v[100:101], v[188:189]
	v_pk_fma_f32 v[122:123], v[122:123], v[98:99], v[186:187]
	v_pk_fma_f32 v[78:79], v[78:79], v[86:87], v[164:165]
	v_pk_fma_f32 v[76:77], v[76:77], v[84:85], v[162:163]
	v_pk_fma_f32 v[90:91], v[90:91], v[94:95], v[168:169]
	v_pk_fma_f32 v[88:89], v[88:89], v[92:93], v[166:167]
	v_pk_fma_f32 v[108:109], v[108:109], v[100:101], v[172:173]
	v_pk_fma_f32 v[106:107], v[106:107], v[98:99], v[170:171]
	v_pk_fma_f32 v[74:75], v[74:75], v[100:101], v[156:157]
	v_pk_fma_f32 v[68:69], v[68:69], v[92:93], v[150:151]
	v_pk_fma_f32 v[66:67], v[66:67], v[86:87], v[148:149]
	v_pk_fma_f32 v[64:65], v[64:65], v[84:85], v[146:147]
	v_pk_fma_f32 v[144:145], v[144:145], v[104:105], v[230:231]
	v_pk_fma_f32 v[142:143], v[142:143], v[102:103], v[228:229]
	global_store_dwordx4 v[222:223], v[142:145], off
	global_store_dwordx4 v[134:135], v[110:113], off offset:576
	global_store_dwordx4 v[134:135], v[118:121], off offset:512
	global_store_dwordx4 v[134:135], v[126:129], off
	v_cndmask_b32_e64 v111, v243, v244, s[0:1]
	v_cndmask_b32_e64 v110, v245, v246, s[0:1]
	v_lshl_add_u64 v[110:111], v[110:111], 0, v[218:219]
	v_lshl_add_u64 v[118:119], v[110:111], 0, v[214:215]
	global_store_dwordx4 v[134:135], v[122:125], off offset:64
	global_store_dwordx4 v[118:119], v[76:79], off offset:576
	v_pk_fma_f32 v[112:113], v[116:117], v[104:105], v[176:177]
	v_pk_fma_f32 v[110:111], v[114:115], v[102:103], v[174:175]
	v_cndmask_b32_e32 v77, v243, v244, vcc
	v_cndmask_b32_e32 v76, v245, v246, vcc
	v_lshl_add_u64 v[76:77], v[76:77], 0, v[216:217]
	global_store_dwordx4 v[118:119], v[88:91], off offset:512
	global_store_dwordx4 v[118:119], v[110:113], off
	global_store_dwordx4 v[118:119], v[106:109], off offset:64
	v_lshl_add_u64 v[88:89], v[76:77], 0, v[214:215]
	global_store_dwordx4 v[88:89], v[64:67], off offset:576
	s_movk_i32 s0, 0x7f80
	v_cmp_gt_i32_e64 s[40:41], s0, v247
	v_add_u32_e32 v64, 0x80, v247
	v_ashrrev_i32_e32 v65, 31, v64
	v_add_u32_e32 v66, 0xffff8080, v247
	v_cndmask_b32_e64 v65, 0, v65, s[40:41]
	v_cndmask_b32_e64 v64, v66, v64, s[40:41]
	v_cndmask_b32_e64 v67, v248, v249, s[40:41]
	v_cndmask_b32_e64 v66, v250, v238, s[40:41]
	v_lshlrev_b64 v[148:149], 12, v[64:65]
	v_lshl_add_u64 v[64:65], v[66:67], 0, v[148:149]
	v_lshl_add_u64 v[150:151], v[64:65], 0, v[214:215]
	v_add_u32_e32 v64, 0x90, v247
	s_movk_i32 s0, 0x7f70
	v_cmp_gt_i32_e64 s[38:39], s0, v247
	v_ashrrev_i32_e32 v65, 31, v64
	v_add_u32_e32 v66, 0xffff8090, v247
	v_cndmask_b32_e64 v65, 0, v65, s[38:39]
	v_cndmask_b32_e64 v64, v66, v64, s[38:39]
	v_cndmask_b32_e64 v67, v248, v249, s[38:39]
	v_cndmask_b32_e64 v66, v250, v238, s[38:39]
	v_lshlrev_b64 v[146:147], 12, v[64:65]
	v_pk_fma_f32 v[78:79], v[82:83], v[104:105], v[160:161]
	v_pk_fma_f32 v[76:77], v[80:81], v[102:103], v[158:159]
	v_pk_fma_f32 v[72:73], v[72:73], v[98:99], v[154:155]
	v_pk_fma_f32 v[70:71], v[70:71], v[94:95], v[152:153]
	v_lshl_add_u64 v[64:65], v[66:67], 0, v[146:147]
	global_store_dwordx4 v[88:89], v[76:79], off
	global_store_dwordx4 v[88:89], v[72:75], off offset:64
	global_store_dwordx4 v[88:89], v[68:71], off offset:512
	v_lshl_add_u64 v[64:65], v[64:65], 0, v[214:215]
	global_load_dwordx4 v[138:141], v[150:151], off offset:64
	global_load_dwordx4 v[134:137], v[150:151], off offset:512
	global_load_dwordx4 v[130:133], v[150:151], off offset:576
	global_load_dwordx4 v[126:129], v[64:65], off
	global_load_dwordx4 v[122:125], v[64:65], off offset:64
	global_load_dwordx4 v[118:121], v[64:65], off offset:512
	global_load_dwordx4 v[114:117], v[64:65], off offset:576
	v_add_u32_e32 v64, 0xa0, v247
	s_movk_i32 s0, 0x7f60
	v_cmp_gt_i32_e64 s[0:1], s0, v247
	v_ashrrev_i32_e32 v65, 31, v64
	v_add_u32_e32 v66, 0xffff80a0, v247
	v_cndmask_b32_e64 v65, 0, v65, s[0:1]
	v_cndmask_b32_e64 v64, v66, v64, s[0:1]
	v_cndmask_b32_e64 v67, v248, v249, s[0:1]
	v_cndmask_b32_e64 v66, v250, v238, s[0:1]
	v_lshlrev_b64 v[144:145], 12, v[64:65]
	v_lshl_add_u64 v[64:65], v[66:67], 0, v[144:145]
	v_lshl_add_u64 v[64:65], v[64:65], 0, v[214:215]
	global_load_dwordx4 v[110:113], v[64:65], off
	global_load_dwordx4 v[106:109], v[64:65], off offset:64
	global_load_dwordx4 v[88:91], v[64:65], off offset:512
	global_load_dwordx4 v[80:83], v[64:65], off offset:576
	v_add_u32_e32 v64, 0xb0, v247
	v_cmp_gt_i32_e32 vcc, s42, v247
	v_ashrrev_i32_e32 v65, 31, v64
	v_add_u32_e32 v66, 0xffff80b0, v247
	v_cndmask_b32_e32 v65, 0, v65, vcc
	v_cndmask_b32_e32 v64, v66, v64, vcc
	v_cndmask_b32_e32 v67, v248, v249, vcc
	v_cndmask_b32_e32 v66, v250, v238, vcc
	v_lshlrev_b64 v[142:143], 12, v[64:65]
	v_lshl_add_u64 v[64:65], v[66:67], 0, v[142:143]
	v_lshl_add_u64 v[64:65], v[64:65], 0, v[214:215]
	v_cndmask_b32_e64 v153, v243, v244, s[40:41]
	v_cndmask_b32_e64 v152, v245, v246, s[40:41]
	global_load_dwordx4 v[76:79], v[64:65], off
	global_load_dwordx4 v[72:75], v[64:65], off offset:64
	global_load_dwordx4 v[68:71], v[64:65], off offset:512
	s_nop 0
	global_load_dwordx4 v[64:67], v[64:65], off offset:576
	v_lshl_add_u64 v[148:149], v[152:153], 0, v[148:149]
	global_load_dwordx4 v[150:153], v[150:151], off
	v_lshl_add_u64 v[148:149], v[148:149], 0, v[214:215]
	s_mov_b64 s[40:41], s[50:51]
	s_waitcnt vmcnt(0)
; #define PG8_WAIT_V(n) asm volatile("s_waitcnt vmcnt(" #n ")" ::: "memory")
; #define PG8_BAR __builtin_amdgcn_s_barrier()
; template <class Epi, class Sched>
; __device__ __forceinline__ void gemm_phase(PG8_LAS unsigned char* lds, const Gemm g, const Sched& S, const Epi& E) {
;     ...
;         if constexpr (!Epi::AFTER_DRAIN) { E(acc, cur, wr, wc, fr, fq); S.done(cur); }
;         if (!has_next) break;
; #pragma unroll
;         for (int a = 0; a < 2; ++a)
; #pragma unroll
;             for (int b = 0; b < 2; ++b)
; #pragma unroll
;                 for (int m = 0; m < 4; ++m)
; #pragma unroll
;                     for (int n = 0; n < 2; ++n) acc[a][b][m][n] = (f32x4){0.f, 0.f, 0.f, 0.f};
;         cur = nxt; cA = nA; cB = nB; ++ui;
;     }
;     PG8_WAIT_V(0);
;     if (wr == 0) PG8_BAR;
;     PG8_BAR;
;   DEV void operator()(const f32x4 (&acc)[2][2][4][2], const pg8::Unit& u, int wr, int wc, int fr, int fq) const {
;     ...
;     for (int ai = 0; ai < 2; ++ai) {
;       f32x4 xv[4][2][2];
; #pragma unroll
;       for (int m = 0; m < 4; ++m) {
;         const int row = row0 + ai * 128 + m * 16;
;         const float* xi = row < T_LAT ? rin_lat + (size_t)row * DM : rin_ctx + (size_t)(row - T_LAT) * DM;
; #pragma unroll
;         for (int bj = 0; bj < 2; ++bj)
; #pragma unroll
;           for (int n = 0; n < 2; ++n) xv[m][bj][n] = *(const f32x4*)(xi + col0 + bj * 128 + n * 16);
;       }
; #pragma unroll
;       for (int m = 0; m < 4; ++m) {
;         const int row = row0 + ai * 128 + m * 16;
;         float* xr = row < T_LAT ? out + (size_t)row * DM : xc + (size_t)(row - T_LAT) * DM;
; #pragma unroll
;         for (int bj = 0; bj < 2; ++bj)
; #pragma unroll
;           for (int n = 0; n < 2; ++n) {
;             const f32x4 r = xv[m][bj][n] + g4[bj][n] * acc[ai][bj][m][n];
;             if (store) *(f32x4*)(xr + col0 + bj * 128 + n * 16) = r;
;           }
;       }
;     }
	v_pk_fma_f32 v[58:59], v[58:59], v[100:101], v[140:141]
	v_pk_fma_f32 v[54:55], v[54:55], v[94:95], v[136:137]
	v_pk_fma_f32 v[46:47], v[46:47], v[86:87], v[132:133]
	v_pk_fma_f32 v[44:45], v[44:45], v[84:85], v[130:131]
	global_store_dwordx4 v[148:149], v[44:47], off offset:576
	v_pk_fma_f32 v[52:53], v[52:53], v[92:93], v[134:135]
	v_pk_fma_f32 v[56:57], v[56:57], v[98:99], v[138:139]
	v_cndmask_b32_e64 v45, v243, v244, s[38:39]
	v_cndmask_b32_e64 v44, v245, v246, s[38:39]
	v_lshl_add_u64 v[44:45], v[44:45], 0, v[146:147]
	global_store_dwordx4 v[148:149], v[52:55], off offset:512
	v_pk_fma_f32 v[30:31], v[30:31], v[86:87], v[116:117]
	v_pk_fma_f32 v[28:29], v[28:29], v[84:85], v[114:115]
	v_lshl_add_u64 v[52:53], v[44:45], 0, v[214:215]
	global_store_dwordx4 v[148:149], v[56:59], off offset:64
	v_pk_fma_f32 v[38:39], v[38:39], v[94:95], v[120:121]
	v_pk_fma_f32 v[36:37], v[36:37], v[92:93], v[118:119]
	v_pk_fma_f32 v[46:47], v[50:51], v[104:105], v[128:129]
	v_pk_fma_f32 v[44:45], v[48:49], v[102:103], v[126:127]
	v_pk_fma_f32 v[42:43], v[42:43], v[100:101], v[124:125]
	v_pk_fma_f32 v[40:41], v[40:41], v[98:99], v[122:123]
	v_pk_fma_f32 v[14:15], v[14:15], v[86:87], v[82:83]
	v_pk_fma_f32 v[12:13], v[12:13], v[84:85], v[80:81]
	v_pk_fma_f32 v[22:23], v[22:23], v[94:95], v[90:91]
	v_pk_fma_f32 v[20:21], v[20:21], v[92:93], v[88:89]
	v_pk_fma_f32 v[26:27], v[26:27], v[100:101], v[108:109]
	v_pk_fma_f32 v[24:25], v[24:25], v[98:99], v[106:107]
	s_mov_b64 s[38:39], s[48:49]
	v_pk_fma_f32 v[10:11], v[10:11], v[100:101], v[74:75]
	v_pk_fma_f32 v[8:9], v[8:9], v[98:99], v[72:73]
	v_pk_fma_f32 v[6:7], v[6:7], v[94:95], v[70:71]
	v_pk_fma_f32 v[4:5], v[4:5], v[92:93], v[68:69]
	v_pk_fma_f32 v[62:63], v[62:63], v[104:105], v[152:153]
	v_pk_fma_f32 v[60:61], v[60:61], v[102:103], v[150:151]
	global_store_dwordx4 v[148:149], v[60:63], off
	global_store_dwordx4 v[52:53], v[28:31], off offset:576
	global_store_dwordx4 v[52:53], v[36:39], off offset:512
	global_store_dwordx4 v[52:53], v[44:47], off
	v_cndmask_b32_e64 v29, v243, v244, s[0:1]
	v_cndmask_b32_e64 v28, v245, v246, s[0:1]
	v_lshl_add_u64 v[28:29], v[28:29], 0, v[144:145]
	v_lshl_add_u64 v[36:37], v[28:29], 0, v[214:215]
	global_store_dwordx4 v[52:53], v[40:43], off offset:64
	global_store_dwordx4 v[36:37], v[12:15], off offset:576
	v_pk_fma_f32 v[30:31], v[34:35], v[104:105], v[112:113]
	v_pk_fma_f32 v[28:29], v[32:33], v[102:103], v[110:111]
	v_cndmask_b32_e32 v13, v243, v244, vcc
	v_cndmask_b32_e32 v12, v245, v246, vcc
	v_lshl_add_u64 v[12:13], v[12:13], 0, v[142:143]
	global_store_dwordx4 v[36:37], v[20:23], off offset:512
	v_pk_fma_f32 v[14:15], v[18:19], v[104:105], v[78:79]
	v_pk_fma_f32 v[2:3], v[2:3], v[86:87], v[66:67]
	v_lshl_add_u64 v[20:21], v[12:13], 0, v[214:215]
	v_pk_fma_f32 v[12:13], v[16:17], v[102:103], v[76:77]
	v_pk_fma_f32 v[0:1], v[0:1], v[84:85], v[64:65]
	s_and_b64 vcc, exec, s[36:37]
	s_mov_b32 s1, s44
	s_mov_b32 s0, s46
	global_store_dwordx4 v[36:37], v[28:31], off
	global_store_dwordx4 v[36:37], v[24:27], off offset:64
	global_store_dwordx4 v[20:21], v[12:15], off
	global_store_dwordx4 v[20:21], v[8:11], off offset:64
	global_store_dwordx4 v[20:21], v[4:7], off offset:512
	global_store_dwordx4 v[20:21], v[0:3], off offset:576
	s_cbranch_vccz .LBB0_84
	s_waitcnt vmcnt(0)
	v_readlane_b32 s0, v255, 48
	v_readlane_b32 s66, v255, 34
	v_readlane_b32 s68, v255, 36
	s_cmpk_gt_u32 s0, 0xff
	v_readlane_b32 s67, v255, 35
	v_readlane_b32 s69, v255, 37
	v_readlane_b32 s70, v255, 41
	s_mov_b64 s[78:79], 0
	s_cbranch_scc1 .LBB0_91
	s_barrier

; #define PG8_STAGE(bufoff, gbase, voff) do { _Pragma("unroll") for (int _i = 0; _i < 2; ++_i) \
;         __builtin_amdgcn_global_load_lds((const unsigned*)((const char*)(gbase) + (voff)[_i]), (PG8_LAS unsigned*)(lds + (bufoff) + ldsw + _i * 8192), 16, 0, 0); } while (0)
; #define PG8_LDA(dst, b, h) do { _Pragma("unroll") for (int m = 0; m < 4; ++m) _Pragma("unroll") for (int k = 0; k < 2; ++k) dst[m][k] = *(const PG8_LAS bf16x8*)(lds + PG8_SA(b, h) + aoff + m * 2048 + k * 1024); } while (0)
; #define PG8_LDB(dst, b, h) do { _Pragma("unroll") for (int n = 0; n < 2; ++n) _Pragma("unroll") for (int k = 0; k < 2; ++k) dst[n][k] = *(const PG8_LAS bf16x8*)(lds + PG8_SB(b, h) + boff + n * 2048 + k * 1024); } while (0)
; #define PG8_MMA(ai, bj, At, Bt) do { __builtin_amdgcn_s_setprio(1); _Pragma("unroll") for (int m = 0; m < 4; ++m) _Pragma("unroll") for (int n = 0; n < 2; ++n) _Pragma("unroll") for (int k = 0; k < 2; ++k) \
;         acc[ai][bj][m][n] = __builtin_amdgcn_mfma_f32_16x16x32_bf16(Bt[n][k], At[m][k], acc[ai][bj][m][n], 0, 0, 0); __builtin_amdgcn_s_setprio(0); } while (0)
; #define PG8_WAIT_V(n) asm volatile("s_waitcnt vmcnt(" #n ")" ::: "memory")
; template <class Epi, class Sched>
; __device__ __forceinline__ void gemm_phase(PG8_LAS unsigned char* lds, const Gemm g, const Sched& S, const Epi& E) {
;     ...
;         for (int t = 0; t < nt; t += 2) {
;             const bool last = (t == nt - 2);
;             const char* a1 = cA + (size_t)(t + 1) * kstep;
;             const char* a2 = last ? nA : cA + (size_t)(t + 2) * kstep; const char* b2 = last ? nB : cB + (size_t)(t + 2) * kstep;
;             const char* a3 = a2 + kstep; const char* b3 = b2 + kstep;
;             if (last && has_next) S.a_ready(nxt);
;             PG8_LDB(B0, 0, 0); PG8_SCHED; PG8_LDA(At, 0, 0); PG8_STAGE(PG8_SA(1, 1), a1 + hstep, voffA);
;             PG8_WAIT_L(8); PG8_BAR; PG8_WAIT_L(0); PG8_MMA(0, 0, At, B0); PG8_BAR; PG8_SCHED;
;             PG8_LDB(B1, 0, 1); PG8_STAGE(PG8_SB(0, 0), b2, voffB);
;             PG8_BAR; PG8_WAIT_L(0); PG8_MMA(0, 1, At, B1); PG8_BAR;
;             PG8_LDA(At, 0, 1); PG8_STAGE(PG8_SA(0, 0), a2, voffA);
;             PG8_BAR; PG8_WAIT_L(0); PG8_MMA(1, 0, At, B0); PG8_BAR; PG8_SCHED;
;             PG8_STAGE(PG8_SB(0, 1), b2 + hstep, voffB);
;             PG8_WAIT_V(6); PG8_BAR; PG8_MMA(1, 1, At, B1); PG8_BAR;
.Lgp_5880:
.LBB0_105:
	s_setprio 1
	s_add_u32 s50, s48, 0xfffe0080
	s_addc_u32 s51, s49, -1
	s_add_i32 s70, 0, 0x10000
	v_add_u32_e32 v96, s70, v221
	ds_read_b128 v[130:133], v96
	ds_read_b128 v[134:137], v96 offset:1024
	ds_read_b128 v[138:141], v96 offset:2048
	ds_read_b128 v[142:145], v96 offset:3072
	s_cmp_eq_u32 s69, 4
	s_cselect_b32 s53, s1, s51
	s_cselect_b32 s52, s39, s50
	s_cselect_b32 s51, s31, s68
	s_cselect_b32 s50, s47, s67
	v_lshl_add_u64 v[178:179], s[48:49], 0, v[204:205]
	s_add_i32 m0, s59, 0xc000
	ds_read_b128 v[146:149], v223
	ds_read_b128 v[150:153], v223 offset:1024
	ds_read_b128 v[154:157], v223 offset:2048
	ds_read_b128 v[158:161], v223 offset:3072
	ds_read_b128 v[162:165], v223 offset:4096
	ds_read_b128 v[166:169], v223 offset:5120
	ds_read_b128 v[170:173], v223 offset:6144
	ds_read_b128 v[174:177], v223 offset:7168
	global_load_lds_dwordx4 v[178:179], off
	v_lshl_add_u64 v[178:179], s[48:49], 0, v[208:209]
	s_add_i32 m0, s59, 0xe000
	s_nop 0
	global_load_lds_dwordx4 v[178:179], off
	s_waitcnt lgkmcnt(8)
	s_barrier
	s_setprio 0
	s_waitcnt lgkmcnt(0)
	v_mfma_f32_16x16x32_bf16 v[126:129], v[130:133], v[146:149], v[126:129]
	v_mfma_f32_16x16x32_bf16 v[122:125], v[138:141], v[146:149], v[122:125]
	v_mfma_f32_16x16x32_bf16 v[110:113], v[130:133], v[154:157], v[110:113]
	v_mfma_f32_16x16x32_bf16 v[106:109], v[138:141], v[154:157], v[106:109]
	v_mfma_f32_16x16x32_bf16 v[92:95], v[130:133], v[162:165], v[92:95]
	v_mfma_f32_16x16x32_bf16 v[88:91], v[138:141], v[162:165], v[88:91]
	v_mfma_f32_16x16x32_bf16 v[76:79], v[130:133], v[170:173], v[76:79]
	v_mfma_f32_16x16x32_bf16 v[72:75], v[138:141], v[170:173], v[72:75]
	v_mfma_f32_16x16x32_bf16 v[126:129], v[134:137], v[150:153], v[126:129]
	v_mfma_f32_16x16x32_bf16 v[122:125], v[142:145], v[150:153], v[122:125]
	v_mfma_f32_16x16x32_bf16 v[110:113], v[134:137], v[158:161], v[110:113]
	v_mfma_f32_16x16x32_bf16 v[106:109], v[142:145], v[158:161], v[106:109]
	v_mfma_f32_16x16x32_bf16 v[92:95], v[134:137], v[166:169], v[92:95]
	v_mfma_f32_16x16x32_bf16 v[88:91], v[142:145], v[166:169], v[88:91]
	v_mfma_f32_16x16x32_bf16 v[76:79], v[134:137], v[174:177], v[76:79]
	v_mfma_f32_16x16x32_bf16 v[72:75], v[142:145], v[174:177], v[72:75]
	s_barrier
	s_setprio 1
	s_add_i32 s94, 0, 0x14000
	s_add_i32 s70, s70, s58
	v_add_u32_e32 v96, s94, v221
	v_lshl_add_u64 v[194:195], s[50:51], 0, v[198:199]
	s_mov_b32 m0, s70
	ds_read_b128 v[178:181], v96
	ds_read_b128 v[182:185], v96 offset:1024
	ds_read_b128 v[186:189], v96 offset:2048
	ds_read_b128 v[190:193], v96 offset:3072
	global_load_lds_dwordx4 v[194:195], off
	v_lshl_add_u64 v[210:211], s[50:51], 0, v[202:203]
	s_add_i32 m0, s70, 0x2000
	s_nop 0
	global_load_lds_dwordx4 v[210:211], off
	s_barrier
	s_setprio 0
	s_waitcnt lgkmcnt(0)
	v_mfma_f32_16x16x32_bf16 v[118:121], v[178:181], v[146:149], v[118:121]
	v_mfma_f32_16x16x32_bf16 v[114:117], v[186:189], v[146:149], v[114:117]
	v_mfma_f32_16x16x32_bf16 v[102:105], v[178:181], v[154:157], v[102:105]
	v_mfma_f32_16x16x32_bf16 v[98:101], v[186:189], v[154:157], v[98:101]
	v_mfma_f32_16x16x32_bf16 v[84:87], v[178:181], v[162:165], v[84:87]
	v_mfma_f32_16x16x32_bf16 v[80:83], v[186:189], v[162:165], v[80:83]
	v_mfma_f32_16x16x32_bf16 v[68:71], v[178:181], v[170:173], v[68:71]
	v_mfma_f32_16x16x32_bf16 v[64:67], v[186:189], v[170:173], v[64:67]
	v_mfma_f32_16x16x32_bf16 v[118:121], v[182:185], v[150:153], v[118:121]
	v_mfma_f32_16x16x32_bf16 v[114:117], v[190:193], v[150:153], v[114:117]
	v_mfma_f32_16x16x32_bf16 v[102:105], v[182:185], v[158:161], v[102:105]
	v_mfma_f32_16x16x32_bf16 v[98:101], v[190:193], v[158:161], v[98:101]
	v_mfma_f32_16x16x32_bf16 v[84:87], v[182:185], v[166:169], v[84:87]
	v_mfma_f32_16x16x32_bf16 v[80:83], v[190:193], v[166:169], v[80:83]
	v_mfma_f32_16x16x32_bf16 v[68:71], v[182:185], v[174:177], v[68:71]
	v_mfma_f32_16x16x32_bf16 v[64:67], v[190:193], v[174:177], v[64:67]
	s_mov_b32 m0, s59
	v_lshl_add_u64 v[212:213], s[52:53], 0, v[196:197]
	s_barrier
	s_setprio 1
	ds_read_b128 v[146:149], v223 offset:16384
	ds_read_b128 v[150:153], v223 offset:17408
	ds_read_b128 v[154:157], v223 offset:18432
	ds_read_b128 v[158:161], v223 offset:19456
	ds_read_b128 v[162:165], v223 offset:20480
	ds_read_b128 v[166:169], v223 offset:21504
	ds_read_b128 v[170:173], v223 offset:22528
	ds_read_b128 v[174:177], v223 offset:23552
	global_load_lds_dwordx4 v[212:213], off
	v_lshl_add_u64 v[214:215], s[52:53], 0, v[200:201]
	s_mov_b32 m0, s60
	s_nop 0
	global_load_lds_dwordx4 v[214:215], off
	s_barrier
	s_setprio 0
	s_waitcnt lgkmcnt(0)
	v_mfma_f32_16x16x32_bf16 v[60:63], v[130:133], v[146:149], v[60:63]
	v_mfma_f32_16x16x32_bf16 v[56:59], v[138:141], v[146:149], v[56:59]
	v_mfma_f32_16x16x32_bf16 v[44:47], v[130:133], v[154:157], v[44:47]
	v_mfma_f32_16x16x32_bf16 v[40:43], v[138:141], v[154:157], v[40:43]
	v_mfma_f32_16x16x32_bf16 v[28:31], v[130:133], v[162:165], v[28:31]
	v_mfma_f32_16x16x32_bf16 v[24:27], v[138:141], v[162:165], v[24:27]
	v_mfma_f32_16x16x32_bf16 v[12:15], v[130:133], v[170:173], v[12:15]
	v_mfma_f32_16x16x32_bf16 v[8:11], v[138:141], v[170:173], v[8:11]
	v_mfma_f32_16x16x32_bf16 v[60:63], v[134:137], v[150:153], v[60:63]
	v_mfma_f32_16x16x32_bf16 v[56:59], v[142:145], v[150:153], v[56:59]
	v_mfma_f32_16x16x32_bf16 v[44:47], v[134:137], v[158:161], v[44:47]
	v_mfma_f32_16x16x32_bf16 v[40:43], v[142:145], v[158:161], v[40:43]
	v_mfma_f32_16x16x32_bf16 v[28:31], v[134:137], v[166:169], v[28:31]
	v_mfma_f32_16x16x32_bf16 v[24:27], v[142:145], v[166:169], v[24:27]
	v_mfma_f32_16x16x32_bf16 v[12:15], v[134:137], v[174:177], v[12:15]
	v_mfma_f32_16x16x32_bf16 v[8:11], v[142:145], v[174:177], v[8:11]
	s_barrier
; #define PG8_STAGE(bufoff, gbase, voff) do { _Pragma("unroll") for (int _i = 0; _i < 2; ++_i) \
;         __builtin_amdgcn_global_load_lds((const unsigned*)((const char*)(gbase) + (voff)[_i]), (PG8_LAS unsigned*)(lds + (bufoff) + ldsw + _i * 8192), 16, 0, 0); } while (0)
; #define PG8_LDA(dst, b, h) do { _Pragma("unroll") for (int m = 0; m < 4; ++m) _Pragma("unroll") for (int k = 0; k < 2; ++k) dst[m][k] = *(const PG8_LAS bf16x8*)(lds + PG8_SA(b, h) + aoff + m * 2048 + k * 1024); } while (0)
; #define PG8_LDB(dst, b, h) do { _Pragma("unroll") for (int n = 0; n < 2; ++n) _Pragma("unroll") for (int k = 0; k < 2; ++k) dst[n][k] = *(const PG8_LAS bf16x8*)(lds + PG8_SB(b, h) + boff + n * 2048 + k * 1024); } while (0)
; #define PG8_MMA(ai, bj, At, Bt) do { __builtin_amdgcn_s_setprio(1); _Pragma("unroll") for (int m = 0; m < 4; ++m) _Pragma("unroll") for (int n = 0; n < 2; ++n) _Pragma("unroll") for (int k = 0; k < 2; ++k) \
;         acc[ai][bj][m][n] = __builtin_amdgcn_mfma_f32_16x16x32_bf16(Bt[n][k], At[m][k], acc[ai][bj][m][n], 0, 0, 0); __builtin_amdgcn_s_setprio(0); } while (0)
; #define PG8_WAIT_V(n) asm volatile("s_waitcnt vmcnt(" #n ")" ::: "memory")
; #define PG8_WAIT_L(n) asm volatile("s_waitcnt lgkmcnt(" #n ")" ::: "memory")
; #define PG8_BAR __builtin_amdgcn_s_barrier()
; #define PG8_SCHED __builtin_amdgcn_sched_barrier(0)
; template <class Epi, class Sched>
; __device__ __forceinline__ void gemm_phase(PG8_LAS unsigned char* lds, const Gemm g, const Sched& S, const Epi& E) {
;     ...
;             PG8_STAGE(PG8_SB(0, 1), b2 + hstep, voffB);
;             PG8_WAIT_V(6); PG8_BAR; PG8_MMA(1, 1, At, B1); PG8_BAR;
;             PG8_LDB(B0, 1, 0); PG8_SCHED; PG8_LDA(At, 1, 0); PG8_STAGE(PG8_SA(0, 1), a2 + hstep, voffA);
;             PG8_WAIT_L(8); PG8_BAR; PG8_WAIT_L(0); PG8_MMA(0, 0, At, B0); PG8_BAR; PG8_SCHED;
;             PG8_LDB(B1, 1, 1); PG8_STAGE(PG8_SB(1, 0), b3, voffB);
;             PG8_BAR; PG8_WAIT_L(0); PG8_MMA(0, 1, At, B1); PG8_BAR;
;             PG8_LDA(At, 1, 1); PG8_STAGE(PG8_SA(1, 0), a3, voffA);
;             PG8_BAR; PG8_WAIT_L(0); PG8_MMA(1, 0, At, B0); PG8_BAR; PG8_SCHED;
	s_setprio 1
	s_add_u32 s70, s50, 0x20000
	s_addc_u32 s71, s51, 0
	s_add_i32 s94, s94, s58
	v_lshl_add_u64 v[130:131], s[70:71], 0, v[198:199]
	s_mov_b32 m0, s94
	s_nop 0
	global_load_lds_dwordx4 v[130:131], off
	v_lshl_add_u64 v[130:131], s[70:71], 0, v[202:203]
	s_add_i32 m0, s94, 0x2000
	s_nop 0
	global_load_lds_dwordx4 v[130:131], off
	s_waitcnt vmcnt(6)
	s_barrier
	s_setprio 0
	v_mfma_f32_16x16x32_bf16 v[52:55], v[178:181], v[146:149], v[52:55]
	v_mfma_f32_16x16x32_bf16 v[48:51], v[186:189], v[146:149], v[48:51]
	v_mfma_f32_16x16x32_bf16 v[36:39], v[178:181], v[154:157], v[36:39]
	v_mfma_f32_16x16x32_bf16 v[32:35], v[186:189], v[154:157], v[32:35]
	v_mfma_f32_16x16x32_bf16 v[20:23], v[178:181], v[162:165], v[20:23]
	v_mfma_f32_16x16x32_bf16 v[16:19], v[186:189], v[162:165], v[16:19]
	v_mfma_f32_16x16x32_bf16 v[4:7], v[178:181], v[170:173], v[4:7]
	v_mfma_f32_16x16x32_bf16 v[0:3], v[186:189], v[170:173], v[0:3]
	v_mfma_f32_16x16x32_bf16 v[52:55], v[182:185], v[150:153], v[52:55]
	v_mfma_f32_16x16x32_bf16 v[48:51], v[190:193], v[150:153], v[48:51]
	v_mfma_f32_16x16x32_bf16 v[36:39], v[182:185], v[158:161], v[36:39]
	v_mfma_f32_16x16x32_bf16 v[32:35], v[190:193], v[158:161], v[32:35]
	v_mfma_f32_16x16x32_bf16 v[20:23], v[182:185], v[166:169], v[20:23]
	v_mfma_f32_16x16x32_bf16 v[16:19], v[190:193], v[166:169], v[16:19]
	v_mfma_f32_16x16x32_bf16 v[4:7], v[182:185], v[174:177], v[4:7]
	v_mfma_f32_16x16x32_bf16 v[0:3], v[190:193], v[174:177], v[0:3]
	s_add_i32 s70, 0, 0x18000
	v_add_u32_e32 v96, s70, v221
	s_barrier
	s_setprio 1
	ds_read_b128 v[130:133], v96
	ds_read_b128 v[134:137], v96 offset:1024
	ds_read_b128 v[138:141], v96 offset:2048
	ds_read_b128 v[142:145], v96 offset:3072
	s_add_u32 s52, s52, 0x20000
	s_addc_u32 s53, s53, 0
	s_mov_b32 m0, s61
	v_lshl_add_u64 v[178:179], s[52:53], 0, v[196:197]
	ds_read_b128 v[146:149], v223 offset:32768
	ds_read_b128 v[150:153], v223 offset:33792
	ds_read_b128 v[154:157], v223 offset:34816
	ds_read_b128 v[158:161], v223 offset:35840
	ds_read_b128 v[162:165], v223 offset:36864
	ds_read_b128 v[166:169], v223 offset:37888
	ds_read_b128 v[170:173], v223 offset:38912
	ds_read_b128 v[174:177], v223 offset:39936
	global_load_lds_dwordx4 v[178:179], off
	v_lshl_add_u64 v[178:179], s[52:53], 0, v[200:201]
	s_mov_b32 m0, s62
	s_nop 0
	global_load_lds_dwordx4 v[178:179], off
	s_waitcnt lgkmcnt(8)
	s_barrier
	s_setprio 0
	s_waitcnt lgkmcnt(0)
	v_mfma_f32_16x16x32_bf16 v[126:129], v[130:133], v[146:149], v[126:129]
	v_mfma_f32_16x16x32_bf16 v[122:125], v[138:141], v[146:149], v[122:125]
	v_mfma_f32_16x16x32_bf16 v[110:113], v[130:133], v[154:157], v[110:113]
	v_mfma_f32_16x16x32_bf16 v[106:109], v[138:141], v[154:157], v[106:109]
	v_mfma_f32_16x16x32_bf16 v[92:95], v[130:133], v[162:165], v[92:95]
	v_mfma_f32_16x16x32_bf16 v[88:91], v[138:141], v[162:165], v[88:91]
	v_mfma_f32_16x16x32_bf16 v[76:79], v[130:133], v[170:173], v[76:79]
	v_mfma_f32_16x16x32_bf16 v[72:75], v[138:141], v[170:173], v[72:75]
	v_mfma_f32_16x16x32_bf16 v[126:129], v[134:137], v[150:153], v[126:129]
	v_mfma_f32_16x16x32_bf16 v[122:125], v[142:145], v[150:153], v[122:125]
	v_mfma_f32_16x16x32_bf16 v[110:113], v[134:137], v[158:161], v[110:113]
	v_mfma_f32_16x16x32_bf16 v[106:109], v[142:145], v[158:161], v[106:109]
	v_mfma_f32_16x16x32_bf16 v[92:95], v[134:137], v[166:169], v[92:95]
	v_mfma_f32_16x16x32_bf16 v[88:91], v[142:145], v[166:169], v[88:91]
	v_mfma_f32_16x16x32_bf16 v[76:79], v[134:137], v[174:177], v[76:79]
	v_mfma_f32_16x16x32_bf16 v[72:75], v[142:145], v[174:177], v[72:75]
	s_barrier
	s_setprio 1
	s_add_i32 s52, 0, 0x1c000
	s_add_i32 s53, s70, s58
	v_add_u32_e32 v96, s52, v221
	v_lshl_add_u64 v[194:195], v[194:195], 0, s[2:3]
	s_mov_b32 m0, s53
	ds_read_b128 v[178:181], v96
	ds_read_b128 v[182:185], v96 offset:1024
	ds_read_b128 v[186:189], v96 offset:2048
	ds_read_b128 v[190:193], v96 offset:3072
	global_load_lds_dwordx4 v[194:195], off
	v_lshl_add_u64 v[194:195], v[210:211], 0, s[2:3]
	s_add_i32 m0, s53, 0x2000
	s_nop 0
	global_load_lds_dwordx4 v[194:195], off
	s_barrier
	s_setprio 0
	s_waitcnt lgkmcnt(0)
	v_mfma_f32_16x16x32_bf16 v[118:121], v[178:181], v[146:149], v[118:121]
	v_mfma_f32_16x16x32_bf16 v[114:117], v[186:189], v[146:149], v[114:117]
	v_mfma_f32_16x16x32_bf16 v[102:105], v[178:181], v[154:157], v[102:105]
	v_mfma_f32_16x16x32_bf16 v[98:101], v[186:189], v[154:157], v[98:101]
	v_mfma_f32_16x16x32_bf16 v[84:87], v[178:181], v[162:165], v[84:87]
	v_mfma_f32_16x16x32_bf16 v[80:83], v[186:189], v[162:165], v[80:83]
	v_mfma_f32_16x16x32_bf16 v[68:71], v[178:181], v[170:173], v[68:71]
	v_mfma_f32_16x16x32_bf16 v[64:67], v[186:189], v[170:173], v[64:67]
	v_mfma_f32_16x16x32_bf16 v[118:121], v[182:185], v[150:153], v[118:121]
	v_mfma_f32_16x16x32_bf16 v[114:117], v[190:193], v[150:153], v[114:117]
	v_mfma_f32_16x16x32_bf16 v[102:105], v[182:185], v[158:161], v[102:105]
	v_mfma_f32_16x16x32_bf16 v[98:101], v[190:193], v[158:161], v[98:101]
	v_mfma_f32_16x16x32_bf16 v[84:87], v[182:185], v[166:169], v[84:87]
	v_mfma_f32_16x16x32_bf16 v[80:83], v[190:193], v[166:169], v[80:83]
	v_mfma_f32_16x16x32_bf16 v[68:71], v[182:185], v[174:177], v[68:71]
	v_mfma_f32_16x16x32_bf16 v[64:67], v[190:193], v[174:177], v[64:67]
	s_mov_b32 m0, s63
	v_lshl_add_u64 v[194:195], v[212:213], 0, s[2:3]
	s_barrier
; #define PG8_STAGE(bufoff, gbase, voff) do { _Pragma("unroll") for (int _i = 0; _i < 2; ++_i) \
;         __builtin_amdgcn_global_load_lds((const unsigned*)((const char*)(gbase) + (voff)[_i]), (PG8_LAS unsigned*)(lds + (bufoff) + ldsw + _i * 8192), 16, 0, 0); } while (0)
; #define PG8_MMA(ai, bj, At, Bt) do { __builtin_amdgcn_s_setprio(1); _Pragma("unroll") for (int m = 0; m < 4; ++m) _Pragma("unroll") for (int n = 0; n < 2; ++n) _Pragma("unroll") for (int k = 0; k < 2; ++k) \
;         acc[ai][bj][m][n] = __builtin_amdgcn_mfma_f32_16x16x32_bf16(Bt[n][k], At[m][k], acc[ai][bj][m][n], 0, 0, 0); __builtin_amdgcn_s_setprio(0); } while (0)
; #define PG8_WAIT_V(n) asm volatile("s_waitcnt vmcnt(" #n ")" ::: "memory")
; #define PG8_WAIT_L(n) asm volatile("s_waitcnt lgkmcnt(" #n ")" ::: "memory")
; #define PG8_BAR __builtin_amdgcn_s_barrier()
; #define PG8_SCHED __builtin_amdgcn_sched_barrier(0)
; template <class Epi, class Sched>
; __device__ __forceinline__ void gemm_phase(PG8_LAS unsigned char* lds, const Gemm g, const Sched& S, const Epi& E) {
;     ...
;             PG8_BAR; PG8_WAIT_L(0); PG8_MMA(1, 0, At, B0); PG8_BAR; PG8_SCHED;
;             PG8_STAGE(PG8_SB(1, 1), b3 + hstep, voffB);
;             PG8_WAIT_V(6); PG8_BAR; PG8_MMA(1, 1, At, B1); PG8_BAR;
;         }
;         if constexpr (!Epi::AFTER_DRAIN) { E(acc, cur, wr, wc, fr, fq); S.done(cur); }
;   DEV void operator()(const f32x4 (&acc)[2][2][4][2], const pg8::Unit& u, int wr, int wc, int fr, int fq) const {
;     const int b = u.pn >> 2, pn = u.pn & 3, pm = u.pm - 136 * (b == 0 ? 11 : (b == 1 ? 12 : 6));
;     const bf16_t* G = (const bf16_t*)(ws + (b == 0 ? O_G1 : (b == 1 ? O_G2 : O_G3)));
;     bf16_t* M = (bf16_t*)(ws + O_M);
;     const int row0 = pm * 256 + wr * 64 + fr, col0 = pn * 256 + wc * 32 + 8 * fq;
; #pragma unroll
;     for (int ai = 0; ai < 2; ++ai) {
;       u32x4 gv[4][2], mv[4][2];
; #pragma unroll
;       for (int m = 0; m < 4; ++m)
; #pragma unroll
;         for (int bj = 0; bj < 2; ++bj) {
;           const size_t off = (size_t)(row0 + ai * 128 + m * 16) * DM + col0 + bj * 128;
;           gv[m][bj] = *(const u32x4*)(G + off);
;           mv[m][bj] = (u32x4){0u, 0u, 0u, 0u};
;           if (b > 0) mv[m][bj] = *(const u32x4*)(M + off);
	s_setprio 1
	ds_read_b128 v[146:149], v223 offset:49152
	ds_read_b128 v[150:153], v223 offset:50176
	ds_read_b128 v[154:157], v223 offset:51200
	ds_read_b128 v[158:161], v223 offset:52224
	ds_read_b128 v[162:165], v223 offset:53248
	ds_read_b128 v[166:169], v223 offset:54272
	ds_read_b128 v[170:173], v223 offset:55296
	ds_read_b128 v[174:177], v223 offset:56320
	global_load_lds_dwordx4 v[194:195], off
	v_lshl_add_u64 v[194:195], v[214:215], 0, s[2:3]
	s_mov_b32 m0, s64
	s_nop 0
	global_load_lds_dwordx4 v[194:195], off
	s_barrier
	s_setprio 0
	s_waitcnt lgkmcnt(0)
	v_mfma_f32_16x16x32_bf16 v[60:63], v[130:133], v[146:149], v[60:63]
	v_mfma_f32_16x16x32_bf16 v[56:59], v[138:141], v[146:149], v[56:59]
	v_mfma_f32_16x16x32_bf16 v[44:47], v[130:133], v[154:157], v[44:47]
	v_mfma_f32_16x16x32_bf16 v[40:43], v[138:141], v[154:157], v[40:43]
	v_mfma_f32_16x16x32_bf16 v[28:31], v[130:133], v[162:165], v[28:31]
	v_mfma_f32_16x16x32_bf16 v[24:27], v[138:141], v[162:165], v[24:27]
	v_mfma_f32_16x16x32_bf16 v[12:15], v[130:133], v[170:173], v[12:15]
	v_mfma_f32_16x16x32_bf16 v[8:11], v[138:141], v[170:173], v[8:11]
	v_mfma_f32_16x16x32_bf16 v[60:63], v[134:137], v[150:153], v[60:63]
	v_mfma_f32_16x16x32_bf16 v[56:59], v[142:145], v[150:153], v[56:59]
	v_mfma_f32_16x16x32_bf16 v[44:47], v[134:137], v[158:161], v[44:47]
	v_mfma_f32_16x16x32_bf16 v[40:43], v[142:145], v[158:161], v[40:43]
	v_mfma_f32_16x16x32_bf16 v[28:31], v[134:137], v[166:169], v[28:31]
	v_mfma_f32_16x16x32_bf16 v[24:27], v[142:145], v[166:169], v[24:27]
	v_mfma_f32_16x16x32_bf16 v[12:15], v[134:137], v[174:177], v[12:15]
	v_mfma_f32_16x16x32_bf16 v[8:11], v[142:145], v[174:177], v[8:11]
	s_barrier
	s_setprio 1
	s_add_u32 s50, s50, 0x20080
	s_addc_u32 s51, s51, 0
	s_add_i32 s52, s52, s58
	v_lshl_add_u64 v[130:131], s[50:51], 0, v[198:199]
	s_mov_b32 m0, s52
	s_nop 0
	global_load_lds_dwordx4 v[130:131], off
	v_lshl_add_u64 v[130:131], s[50:51], 0, v[202:203]
	s_add_i32 m0, s52, 0x2000
	s_nop 0
	global_load_lds_dwordx4 v[130:131], off
	s_waitcnt vmcnt(6)
	s_barrier
	s_setprio 0
	v_mfma_f32_16x16x32_bf16 v[52:55], v[178:181], v[146:149], v[52:55]
	v_mfma_f32_16x16x32_bf16 v[48:51], v[186:189], v[146:149], v[48:51]
	v_mfma_f32_16x16x32_bf16 v[36:39], v[178:181], v[154:157], v[36:39]
	v_mfma_f32_16x16x32_bf16 v[32:35], v[186:189], v[154:157], v[32:35]
	v_mfma_f32_16x16x32_bf16 v[20:23], v[178:181], v[162:165], v[20:23]
	v_mfma_f32_16x16x32_bf16 v[16:19], v[186:189], v[162:165], v[16:19]
	v_mfma_f32_16x16x32_bf16 v[4:7], v[178:181], v[170:173], v[4:7]
	v_mfma_f32_16x16x32_bf16 v[0:3], v[186:189], v[170:173], v[0:3]
	v_mfma_f32_16x16x32_bf16 v[52:55], v[182:185], v[150:153], v[52:55]
	v_mfma_f32_16x16x32_bf16 v[48:51], v[190:193], v[150:153], v[48:51]
	v_mfma_f32_16x16x32_bf16 v[36:39], v[182:185], v[158:161], v[36:39]
	v_mfma_f32_16x16x32_bf16 v[32:35], v[190:193], v[158:161], v[32:35]
	v_mfma_f32_16x16x32_bf16 v[20:23], v[182:185], v[166:169], v[20:23]
	v_mfma_f32_16x16x32_bf16 v[16:19], v[190:193], v[166:169], v[16:19]
	v_mfma_f32_16x16x32_bf16 v[4:7], v[182:185], v[174:177], v[4:7]
	v_mfma_f32_16x16x32_bf16 v[0:3], v[190:193], v[174:177], v[0:3]
	s_add_i32 s69, s69, 2
	s_add_u32 s48, s48, 0x100
	s_addc_u32 s49, s49, 0
	s_add_u32 s67, s67, 0x100
	s_addc_u32 s68, s68, 0
	s_cmp_gt_u32 s69, 5
	s_barrier
	s_cbranch_scc0 .LBB0_105
	s_ashr_i32 s1, s0, 2
	s_cmp_eq_u32 s1, 1
	s_movk_i32 s31, 0xf9a0
	s_mov_b32 s39, 0xee00000
	s_cselect_b32 s31, s31, 0xfffffcd0
	s_cselect_b32 s39, s39, 0x13200000
	s_cmp_lt_u32 s0, 4
	s_cselect_b32 s31, 0xfffffa28, s31
	s_cselect_b32 s39, 0x6600000, s39
	s_add_i32 s31, s31, s46
	s_add_u32 s46, s74, s39
	s_addc_u32 s47, s75, 0
	v_lshl_add_u32 v212, s31, 8, v220
	s_lshl_b32 s0, s0, 8
	s_and_b32 s0, s0, 0x300
	v_ashrrev_i32_e32 v213, 31, v212
	v_or_b32_e32 v224, s0, v222
	v_lshlrev_b64 v[130:131], 10, v[212:213]
	v_or_b32_e32 v130, v130, v224
	v_lshl_add_u64 v[132:133], v[130:131], 1, s[46:47]
	global_load_dwordx4 v[188:191], v[132:133], off
	s_cmp_gt_i32 s1, 0
	s_cselect_b64 s[48:49], -1, 0
	s_cmp_lt_i32 s1, 1
	v_lshl_add_u64 v[130:131], v[130:131], 1, s[74:75]
	s_cbranch_scc1 .LBB0_108
	global_load_dwordx4 v[192:195], v[130:131], off
	s_branch .LBB0_109

; #define PG8_STAGE(bufoff, gbase, voff) do { _Pragma("unroll") for (int _i = 0; _i < 2; ++_i) \
;         __builtin_amdgcn_global_load_lds((const unsigned*)((const char*)(gbase) + (voff)[_i]), (PG8_LAS unsigned*)(lds + (bufoff) + ldsw + _i * 8192), 16, 0, 0); } while (0)
; #define PG8_LDA(dst, b, h) do { _Pragma("unroll") for (int m = 0; m < 4; ++m) _Pragma("unroll") for (int k = 0; k < 2; ++k) dst[m][k] = *(const PG8_LAS bf16x8*)(lds + PG8_SA(b, h) + aoff + m * 2048 + k * 1024); } while (0)
; #define PG8_LDB(dst, b, h) do { _Pragma("unroll") for (int n = 0; n < 2; ++n) _Pragma("unroll") for (int k = 0; k < 2; ++k) dst[n][k] = *(const PG8_LAS bf16x8*)(lds + PG8_SB(b, h) + boff + n * 2048 + k * 1024); } while (0)
; #define PG8_MMA(ai, bj, At, Bt) do { __builtin_amdgcn_s_setprio(1); _Pragma("unroll") for (int m = 0; m < 4; ++m) _Pragma("unroll") for (int n = 0; n < 2; ++n) _Pragma("unroll") for (int k = 0; k < 2; ++k) \
;         acc[ai][bj][m][n] = __builtin_amdgcn_mfma_f32_16x16x32_bf16(Bt[n][k], At[m][k], acc[ai][bj][m][n], 0, 0, 0); __builtin_amdgcn_s_setprio(0); } while (0)
; #define PG8_WAIT_V(n) asm volatile("s_waitcnt vmcnt(" #n ")" ::: "memory")
; template <class Epi, class Sched>
; __device__ __forceinline__ void gemm_phase(PG8_LAS unsigned char* lds, const Gemm g, const Sched& S, const Epi& E) {
;     ...
;         for (int t = 0; t < nt; t += 2) {
;             const bool last = (t == nt - 2);
;             const char* a1 = cA + (size_t)(t + 1) * kstep;
;             const char* a2 = last ? nA : cA + (size_t)(t + 2) * kstep; const char* b2 = last ? nB : cB + (size_t)(t + 2) * kstep;
;             const char* a3 = a2 + kstep; const char* b3 = b2 + kstep;
;             if (last && has_next) S.a_ready(nxt);
;             PG8_LDB(B0, 0, 0); PG8_SCHED; PG8_LDA(At, 0, 0); PG8_STAGE(PG8_SA(1, 1), a1 + hstep, voffA);
;             PG8_WAIT_L(8); PG8_BAR; PG8_WAIT_L(0); PG8_MMA(0, 0, At, B0); PG8_BAR; PG8_SCHED;
;             PG8_LDB(B1, 0, 1); PG8_STAGE(PG8_SB(0, 0), b2, voffB);
;             PG8_BAR; PG8_WAIT_L(0); PG8_MMA(0, 1, At, B1); PG8_BAR;
;             PG8_LDA(At, 0, 1); PG8_STAGE(PG8_SA(0, 0), a2, voffA);
;             PG8_BAR; PG8_WAIT_L(0); PG8_MMA(1, 0, At, B0); PG8_BAR; PG8_SCHED;
;             PG8_STAGE(PG8_SB(0, 1), b2 + hstep, voffB);
;             PG8_WAIT_V(6); PG8_BAR; PG8_MMA(1, 1, At, B1); PG8_BAR;
.Lgp_7151:
.LBB0_152:
	s_setprio 1
	s_add_u32 s48, s46, 0xfffc0080
	s_addc_u32 s49, s47, -1
	s_add_i32 s71, 0, 0x10000
	v_add_u32_e32 v96, s71, v147
	ds_read_b128 v[142:145], v96
	ds_read_b128 v[150:153], v96 offset:1024
	ds_read_b128 v[154:157], v96 offset:2048
	ds_read_b128 v[158:161], v96 offset:3072
	s_cmp_eq_u32 s70, 12
	s_cselect_b32 s51, s31, s49
	s_cselect_b32 s50, s66, s48
	s_cselect_b32 s49, s1, s69
	s_cselect_b32 s48, s67, s68
	v_lshl_add_u64 v[194:195], s[46:47], 0, v[138:139]
	s_add_i32 m0, s45, 0xc000
	ds_read_b128 v[162:165], v149
	ds_read_b128 v[166:169], v149 offset:1024
	ds_read_b128 v[170:173], v149 offset:2048
	ds_read_b128 v[174:177], v149 offset:3072
	ds_read_b128 v[178:181], v149 offset:4096
	ds_read_b128 v[182:185], v149 offset:5120
	ds_read_b128 v[186:189], v149 offset:6144
	ds_read_b128 v[190:193], v149 offset:7168
	global_load_lds_dwordx4 v[194:195], off
	v_lshl_add_u64 v[194:195], s[46:47], 0, v[140:141]
	s_add_i32 m0, s45, 0xe000
	s_nop 0
	global_load_lds_dwordx4 v[194:195], off
	s_waitcnt lgkmcnt(8)
	s_barrier
	s_setprio 0
	s_waitcnt lgkmcnt(0)
	v_mfma_f32_16x16x32_bf16 v[126:129], v[142:145], v[162:165], v[126:129]
	v_mfma_f32_16x16x32_bf16 v[122:125], v[154:157], v[162:165], v[122:125]
	v_mfma_f32_16x16x32_bf16 v[110:113], v[142:145], v[170:173], v[110:113]
	v_mfma_f32_16x16x32_bf16 v[106:109], v[154:157], v[170:173], v[106:109]
	v_mfma_f32_16x16x32_bf16 v[92:95], v[142:145], v[178:181], v[92:95]
	v_mfma_f32_16x16x32_bf16 v[88:91], v[154:157], v[178:181], v[88:91]
	v_mfma_f32_16x16x32_bf16 v[76:79], v[142:145], v[186:189], v[76:79]
	v_mfma_f32_16x16x32_bf16 v[72:75], v[154:157], v[186:189], v[72:75]
	v_mfma_f32_16x16x32_bf16 v[126:129], v[150:153], v[166:169], v[126:129]
	v_mfma_f32_16x16x32_bf16 v[122:125], v[158:161], v[166:169], v[122:125]
	v_mfma_f32_16x16x32_bf16 v[110:113], v[150:153], v[174:177], v[110:113]
	v_mfma_f32_16x16x32_bf16 v[106:109], v[158:161], v[174:177], v[106:109]
	v_mfma_f32_16x16x32_bf16 v[92:95], v[150:153], v[182:185], v[92:95]
	v_mfma_f32_16x16x32_bf16 v[88:91], v[158:161], v[182:185], v[88:91]
	v_mfma_f32_16x16x32_bf16 v[76:79], v[150:153], v[190:193], v[76:79]
	v_mfma_f32_16x16x32_bf16 v[72:75], v[158:161], v[190:193], v[72:75]
	s_barrier
	s_setprio 1
	s_add_i32 s94, 0, 0x14000
	s_add_i32 s71, s71, s56
	v_add_u32_e32 v96, s94, v147
	v_lshl_add_u64 v[212:213], s[48:49], 0, v[134:135]
	s_mov_b32 m0, s71
	ds_read_b128 v[194:197], v96
	ds_read_b128 v[198:201], v96 offset:1024
	ds_read_b128 v[202:205], v96 offset:2048
	ds_read_b128 v[208:211], v96 offset:3072
	global_load_lds_dwordx4 v[212:213], off
	v_lshl_add_u64 v[214:215], s[48:49], 0, v[130:131]
	s_add_i32 m0, s71, 0x2000
	s_nop 0
	global_load_lds_dwordx4 v[214:215], off
	s_barrier
	s_setprio 0
	s_waitcnt lgkmcnt(0)
	v_mfma_f32_16x16x32_bf16 v[118:121], v[194:197], v[162:165], v[118:121]
	v_mfma_f32_16x16x32_bf16 v[114:117], v[202:205], v[162:165], v[114:117]
	v_mfma_f32_16x16x32_bf16 v[102:105], v[194:197], v[170:173], v[102:105]
	v_mfma_f32_16x16x32_bf16 v[98:101], v[202:205], v[170:173], v[98:101]
	v_mfma_f32_16x16x32_bf16 v[84:87], v[194:197], v[178:181], v[84:87]
	v_mfma_f32_16x16x32_bf16 v[80:83], v[202:205], v[178:181], v[80:83]
	v_mfma_f32_16x16x32_bf16 v[68:71], v[194:197], v[186:189], v[68:71]
	v_mfma_f32_16x16x32_bf16 v[64:67], v[202:205], v[186:189], v[64:67]
	v_mfma_f32_16x16x32_bf16 v[118:121], v[198:201], v[166:169], v[118:121]
	v_mfma_f32_16x16x32_bf16 v[114:117], v[208:211], v[166:169], v[114:117]
	v_mfma_f32_16x16x32_bf16 v[102:105], v[198:201], v[174:177], v[102:105]
	v_mfma_f32_16x16x32_bf16 v[98:101], v[208:211], v[174:177], v[98:101]
	v_mfma_f32_16x16x32_bf16 v[84:87], v[198:201], v[182:185], v[84:87]
	v_mfma_f32_16x16x32_bf16 v[80:83], v[208:211], v[182:185], v[80:83]
	v_mfma_f32_16x16x32_bf16 v[68:71], v[198:201], v[190:193], v[68:71]
	v_mfma_f32_16x16x32_bf16 v[64:67], v[208:211], v[190:193], v[64:67]
	s_mov_b32 m0, s45
	v_lshl_add_u64 v[216:217], s[50:51], 0, v[136:137]
	s_barrier
	s_setprio 1
	ds_read_b128 v[162:165], v149 offset:16384
	ds_read_b128 v[166:169], v149 offset:17408
	ds_read_b128 v[170:173], v149 offset:18432
	ds_read_b128 v[174:177], v149 offset:19456
	ds_read_b128 v[178:181], v149 offset:20480
	ds_read_b128 v[182:185], v149 offset:21504
	ds_read_b128 v[186:189], v149 offset:22528
	ds_read_b128 v[190:193], v149 offset:23552
	global_load_lds_dwordx4 v[216:217], off
	v_lshl_add_u64 v[218:219], s[50:51], 0, v[132:133]
	s_mov_b32 m0, s59
	s_nop 0
	global_load_lds_dwordx4 v[218:219], off
	s_barrier
	s_setprio 0
	s_waitcnt lgkmcnt(0)
	v_mfma_f32_16x16x32_bf16 v[60:63], v[142:145], v[162:165], v[60:63]
	v_mfma_f32_16x16x32_bf16 v[56:59], v[154:157], v[162:165], v[56:59]
	v_mfma_f32_16x16x32_bf16 v[44:47], v[142:145], v[170:173], v[44:47]
	v_mfma_f32_16x16x32_bf16 v[40:43], v[154:157], v[170:173], v[40:43]
	v_mfma_f32_16x16x32_bf16 v[28:31], v[142:145], v[178:181], v[28:31]
	v_mfma_f32_16x16x32_bf16 v[24:27], v[154:157], v[178:181], v[24:27]
	v_mfma_f32_16x16x32_bf16 v[12:15], v[142:145], v[186:189], v[12:15]
	v_mfma_f32_16x16x32_bf16 v[8:11], v[154:157], v[186:189], v[8:11]
	v_mfma_f32_16x16x32_bf16 v[60:63], v[150:153], v[166:169], v[60:63]
	v_mfma_f32_16x16x32_bf16 v[56:59], v[158:161], v[166:169], v[56:59]
	v_mfma_f32_16x16x32_bf16 v[44:47], v[150:153], v[174:177], v[44:47]
	v_mfma_f32_16x16x32_bf16 v[40:43], v[158:161], v[174:177], v[40:43]
	v_mfma_f32_16x16x32_bf16 v[28:31], v[150:153], v[182:185], v[28:31]
	v_mfma_f32_16x16x32_bf16 v[24:27], v[158:161], v[182:185], v[24:27]
	v_mfma_f32_16x16x32_bf16 v[12:15], v[150:153], v[190:193], v[12:15]
	v_mfma_f32_16x16x32_bf16 v[8:11], v[158:161], v[190:193], v[8:11]
	s_barrier
; #define PG8_STAGE(bufoff, gbase, voff) do { _Pragma("unroll") for (int _i = 0; _i < 2; ++_i) \
;         __builtin_amdgcn_global_load_lds((const unsigned*)((const char*)(gbase) + (voff)[_i]), (PG8_LAS unsigned*)(lds + (bufoff) + ldsw + _i * 8192), 16, 0, 0); } while (0)
; #define PG8_LDA(dst, b, h) do { _Pragma("unroll") for (int m = 0; m < 4; ++m) _Pragma("unroll") for (int k = 0; k < 2; ++k) dst[m][k] = *(const PG8_LAS bf16x8*)(lds + PG8_SA(b, h) + aoff + m * 2048 + k * 1024); } while (0)
; #define PG8_LDB(dst, b, h) do { _Pragma("unroll") for (int n = 0; n < 2; ++n) _Pragma("unroll") for (int k = 0; k < 2; ++k) dst[n][k] = *(const PG8_LAS bf16x8*)(lds + PG8_SB(b, h) + boff + n * 2048 + k * 1024); } while (0)
; #define PG8_MMA(ai, bj, At, Bt) do { __builtin_amdgcn_s_setprio(1); _Pragma("unroll") for (int m = 0; m < 4; ++m) _Pragma("unroll") for (int n = 0; n < 2; ++n) _Pragma("unroll") for (int k = 0; k < 2; ++k) \
;         acc[ai][bj][m][n] = __builtin_amdgcn_mfma_f32_16x16x32_bf16(Bt[n][k], At[m][k], acc[ai][bj][m][n], 0, 0, 0); __builtin_amdgcn_s_setprio(0); } while (0)
; #define PG8_WAIT_V(n) asm volatile("s_waitcnt vmcnt(" #n ")" ::: "memory")
; #define PG8_WAIT_L(n) asm volatile("s_waitcnt lgkmcnt(" #n ")" ::: "memory")
; #define PG8_BAR __builtin_amdgcn_s_barrier()
; #define PG8_SCHED __builtin_amdgcn_sched_barrier(0)
; template <class Epi, class Sched>
; __device__ __forceinline__ void gemm_phase(PG8_LAS unsigned char* lds, const Gemm g, const Sched& S, const Epi& E) {
;     ...
;             PG8_STAGE(PG8_SB(0, 1), b2 + hstep, voffB);
;             PG8_WAIT_V(6); PG8_BAR; PG8_MMA(1, 1, At, B1); PG8_BAR;
;             PG8_LDB(B0, 1, 0); PG8_SCHED; PG8_LDA(At, 1, 0); PG8_STAGE(PG8_SA(0, 1), a2 + hstep, voffA);
;             PG8_WAIT_L(8); PG8_BAR; PG8_WAIT_L(0); PG8_MMA(0, 0, At, B0); PG8_BAR; PG8_SCHED;
;             PG8_LDB(B1, 1, 1); PG8_STAGE(PG8_SB(1, 0), b3, voffB);
;             PG8_BAR; PG8_WAIT_L(0); PG8_MMA(0, 1, At, B1); PG8_BAR;
;             PG8_LDA(At, 1, 1); PG8_STAGE(PG8_SA(1, 0), a3, voffA);
;             PG8_BAR; PG8_WAIT_L(0); PG8_MMA(1, 0, At, B0); PG8_BAR; PG8_SCHED;
	s_setprio 1
	s_add_u32 vcc_lo, s48, 0x40000
	s_addc_u32 vcc_hi, s49, 0
	s_add_i32 s71, s94, s56
	v_lshl_add_u64 v[142:143], vcc, 0, v[134:135]
	s_mov_b32 m0, s71
	s_nop 0
	global_load_lds_dwordx4 v[142:143], off
	v_lshl_add_u64 v[142:143], vcc, 0, v[130:131]
	s_add_i32 m0, s71, 0x2000
	s_nop 0
	global_load_lds_dwordx4 v[142:143], off
	s_waitcnt vmcnt(6)
	s_barrier
	s_setprio 0
	v_mfma_f32_16x16x32_bf16 v[52:55], v[194:197], v[162:165], v[52:55]
	v_mfma_f32_16x16x32_bf16 v[48:51], v[202:205], v[162:165], v[48:51]
	v_mfma_f32_16x16x32_bf16 v[36:39], v[194:197], v[170:173], v[36:39]
	v_mfma_f32_16x16x32_bf16 v[32:35], v[202:205], v[170:173], v[32:35]
	v_mfma_f32_16x16x32_bf16 v[20:23], v[194:197], v[178:181], v[20:23]
	v_mfma_f32_16x16x32_bf16 v[16:19], v[202:205], v[178:181], v[16:19]
	v_mfma_f32_16x16x32_bf16 v[4:7], v[194:197], v[186:189], v[4:7]
	v_mfma_f32_16x16x32_bf16 v[0:3], v[202:205], v[186:189], v[0:3]
	v_mfma_f32_16x16x32_bf16 v[52:55], v[198:201], v[166:169], v[52:55]
	v_mfma_f32_16x16x32_bf16 v[48:51], v[208:211], v[166:169], v[48:51]
	v_mfma_f32_16x16x32_bf16 v[36:39], v[198:201], v[174:177], v[36:39]
	v_mfma_f32_16x16x32_bf16 v[32:35], v[208:211], v[174:177], v[32:35]
	v_mfma_f32_16x16x32_bf16 v[20:23], v[198:201], v[182:185], v[20:23]
	v_mfma_f32_16x16x32_bf16 v[16:19], v[208:211], v[182:185], v[16:19]
	v_mfma_f32_16x16x32_bf16 v[4:7], v[198:201], v[190:193], v[4:7]
	v_mfma_f32_16x16x32_bf16 v[0:3], v[208:211], v[190:193], v[0:3]
	s_add_i32 s71, 0, 0x18000
	v_add_u32_e32 v96, s71, v147
	s_barrier
	s_setprio 1
	ds_read_b128 v[142:145], v96
	ds_read_b128 v[150:153], v96 offset:1024
	ds_read_b128 v[154:157], v96 offset:2048
	ds_read_b128 v[158:161], v96 offset:3072
	s_add_u32 s50, s50, 0x40000
	s_addc_u32 s51, s51, 0
	s_mov_b32 m0, s60
	v_lshl_add_u64 v[194:195], s[50:51], 0, v[136:137]
	ds_read_b128 v[162:165], v149 offset:32768
	ds_read_b128 v[166:169], v149 offset:33792
	ds_read_b128 v[170:173], v149 offset:34816
	ds_read_b128 v[174:177], v149 offset:35840
	ds_read_b128 v[178:181], v149 offset:36864
	ds_read_b128 v[182:185], v149 offset:37888
	ds_read_b128 v[186:189], v149 offset:38912
	ds_read_b128 v[190:193], v149 offset:39936
	global_load_lds_dwordx4 v[194:195], off
	v_lshl_add_u64 v[194:195], s[50:51], 0, v[132:133]
	s_mov_b32 m0, s61
	s_nop 0
	global_load_lds_dwordx4 v[194:195], off
	s_waitcnt lgkmcnt(8)
	s_barrier
	s_setprio 0
	s_waitcnt lgkmcnt(0)
	v_mfma_f32_16x16x32_bf16 v[126:129], v[142:145], v[162:165], v[126:129]
	v_mfma_f32_16x16x32_bf16 v[122:125], v[154:157], v[162:165], v[122:125]
	v_mfma_f32_16x16x32_bf16 v[110:113], v[142:145], v[170:173], v[110:113]
	v_mfma_f32_16x16x32_bf16 v[106:109], v[154:157], v[170:173], v[106:109]
	v_mfma_f32_16x16x32_bf16 v[92:95], v[142:145], v[178:181], v[92:95]
	v_mfma_f32_16x16x32_bf16 v[88:91], v[154:157], v[178:181], v[88:91]
	v_mfma_f32_16x16x32_bf16 v[76:79], v[142:145], v[186:189], v[76:79]
	v_mfma_f32_16x16x32_bf16 v[72:75], v[154:157], v[186:189], v[72:75]
	v_mfma_f32_16x16x32_bf16 v[126:129], v[150:153], v[166:169], v[126:129]
	v_mfma_f32_16x16x32_bf16 v[122:125], v[158:161], v[166:169], v[122:125]
	v_mfma_f32_16x16x32_bf16 v[110:113], v[150:153], v[174:177], v[110:113]
	v_mfma_f32_16x16x32_bf16 v[106:109], v[158:161], v[174:177], v[106:109]
	v_mfma_f32_16x16x32_bf16 v[92:95], v[150:153], v[182:185], v[92:95]
	v_mfma_f32_16x16x32_bf16 v[88:91], v[158:161], v[182:185], v[88:91]
	v_mfma_f32_16x16x32_bf16 v[76:79], v[150:153], v[190:193], v[76:79]
	v_mfma_f32_16x16x32_bf16 v[72:75], v[158:161], v[190:193], v[72:75]
	s_barrier
	s_setprio 1
	s_add_i32 s50, 0, 0x1c000
	s_add_i32 s51, s71, s56
	v_add_u32_e32 v96, s50, v147
	v_lshl_add_u64 v[212:213], v[212:213], 0, s[2:3]
	s_mov_b32 m0, s51
	ds_read_b128 v[194:197], v96
	ds_read_b128 v[198:201], v96 offset:1024
	ds_read_b128 v[202:205], v96 offset:2048
	ds_read_b128 v[208:211], v96 offset:3072
	global_load_lds_dwordx4 v[212:213], off
	v_lshl_add_u64 v[212:213], v[214:215], 0, s[2:3]
	s_add_i32 m0, s51, 0x2000
	s_nop 0
	global_load_lds_dwordx4 v[212:213], off
	s_barrier
	s_setprio 0
	s_waitcnt lgkmcnt(0)
	v_mfma_f32_16x16x32_bf16 v[118:121], v[194:197], v[162:165], v[118:121]
	v_mfma_f32_16x16x32_bf16 v[114:117], v[202:205], v[162:165], v[114:117]
	v_mfma_f32_16x16x32_bf16 v[102:105], v[194:197], v[170:173], v[102:105]
	v_mfma_f32_16x16x32_bf16 v[98:101], v[202:205], v[170:173], v[98:101]
	v_mfma_f32_16x16x32_bf16 v[84:87], v[194:197], v[178:181], v[84:87]
	v_mfma_f32_16x16x32_bf16 v[80:83], v[202:205], v[178:181], v[80:83]
	v_mfma_f32_16x16x32_bf16 v[68:71], v[194:197], v[186:189], v[68:71]
	v_mfma_f32_16x16x32_bf16 v[64:67], v[202:205], v[186:189], v[64:67]
	v_mfma_f32_16x16x32_bf16 v[118:121], v[198:201], v[166:169], v[118:121]
	v_mfma_f32_16x16x32_bf16 v[114:117], v[208:211], v[166:169], v[114:117]
	v_mfma_f32_16x16x32_bf16 v[102:105], v[198:201], v[174:177], v[102:105]
	v_mfma_f32_16x16x32_bf16 v[98:101], v[208:211], v[174:177], v[98:101]
	v_mfma_f32_16x16x32_bf16 v[84:87], v[198:201], v[182:185], v[84:87]
	v_mfma_f32_16x16x32_bf16 v[80:83], v[208:211], v[182:185], v[80:83]
	v_mfma_f32_16x16x32_bf16 v[68:71], v[198:201], v[190:193], v[68:71]
	v_mfma_f32_16x16x32_bf16 v[64:67], v[208:211], v[190:193], v[64:67]
	s_mov_b32 m0, s62
	v_lshl_add_u64 v[212:213], v[216:217], 0, s[2:3]
	s_barrier
	s_setprio 1
	ds_read_b128 v[162:165], v149 offset:49152
	ds_read_b128 v[166:169], v149 offset:50176
	ds_read_b128 v[170:173], v149 offset:51200
	ds_read_b128 v[174:177], v149 offset:52224
	ds_read_b128 v[178:181], v149 offset:53248
	ds_read_b128 v[182:185], v149 offset:54272
	ds_read_b128 v[186:189], v149 offset:55296
	ds_read_b128 v[190:193], v149 offset:56320
	global_load_lds_dwordx4 v[212:213], off
	v_lshl_add_u64 v[212:213], v[218:219], 0, s[2:3]
	s_mov_b32 m0, s63
	s_nop 0
	global_load_lds_dwordx4 v[212:213], off
	s_barrier
; DEV float sigmoidf_(float x) { return __builtin_amdgcn_rcpf(1.f + __expf(-x)); }
; #define PG8_STAGE(bufoff, gbase, voff) do { _Pragma("unroll") for (int _i = 0; _i < 2; ++_i) \
;         __builtin_amdgcn_global_load_lds((const unsigned*)((const char*)(gbase) + (voff)[_i]), (PG8_LAS unsigned*)(lds + (bufoff) + ldsw + _i * 8192), 16, 0, 0); } while (0)
; #define PG8_MMA(ai, bj, At, Bt) do { __builtin_amdgcn_s_setprio(1); _Pragma("unroll") for (int m = 0; m < 4; ++m) _Pragma("unroll") for (int n = 0; n < 2; ++n) _Pragma("unroll") for (int k = 0; k < 2; ++k) \
;         acc[ai][bj][m][n] = __builtin_amdgcn_mfma_f32_16x16x32_bf16(Bt[n][k], At[m][k], acc[ai][bj][m][n], 0, 0, 0); __builtin_amdgcn_s_setprio(0); } while (0)
; #define PG8_WAIT_V(n) asm volatile("s_waitcnt vmcnt(" #n ")" ::: "memory")
; #define PG8_WAIT_L(n) asm volatile("s_waitcnt lgkmcnt(" #n ")" ::: "memory")
; #define PG8_BAR __builtin_amdgcn_s_barrier()
; #define PG8_SCHED __builtin_amdgcn_sched_barrier(0)
; template <class Epi, class Sched>
; __device__ __forceinline__ void gemm_phase(PG8_LAS unsigned char* lds, const Gemm g, const Sched& S, const Epi& E) {
;     ...
;             PG8_BAR; PG8_WAIT_L(0); PG8_MMA(1, 0, At, B0); PG8_BAR; PG8_SCHED;
;             PG8_STAGE(PG8_SB(1, 1), b3 + hstep, voffB);
;             PG8_WAIT_V(6); PG8_BAR; PG8_MMA(1, 1, At, B1); PG8_BAR;
;   DEV void operator()(const f32x4 (&acc)[2][2][4][2], const pg8::Unit& u, int wr, int wc, int fr, int fq) const {
;     const int b = u.pn >> 2, pn = u.pn & 3;
;     bf16_t* G = (bf16_t*)(ws + (b == 0 ? O_G1 : (b == 1 ? O_G2 : O_G3)));
;     const int row0 = u.pm * 256 + wr * 64 + fr, col0 = pn * 256 + wc * 32 + 8 * fq;
; #pragma unroll
;     for (int ai = 0; ai < 2; ++ai)
; #pragma unroll
;       for (int m = 0; m < 4; ++m) {
;         const int row = row0 + ai * 128 + m * 16;
; #pragma unroll
;         for (int bj = 0; bj < 2; ++bj) {
;           const f32x4 a0 = acc[ai][bj][m][0], a1 = acc[ai][bj][m][1];
;           u32x4 o;
;           o[0] = pk2(sigmoidf_(a0[0]), sigmoidf_(a0[1])); o[1] = pk2(sigmoidf_(a0[2]), sigmoidf_(a0[3]));
;           o[2] = pk2(sigmoidf_(a1[0]), sigmoidf_(a1[1])); o[3] = pk2(sigmoidf_(a1[2]), sigmoidf_(a1[3]));
;           *(u32x4*)(G + (size_t)row * DM + col0 + bj * 128) = o;
	s_setprio 0
	s_waitcnt lgkmcnt(0)
	v_mfma_f32_16x16x32_bf16 v[60:63], v[142:145], v[162:165], v[60:63]
	v_mfma_f32_16x16x32_bf16 v[56:59], v[154:157], v[162:165], v[56:59]
	v_mfma_f32_16x16x32_bf16 v[44:47], v[142:145], v[170:173], v[44:47]
	v_mfma_f32_16x16x32_bf16 v[40:43], v[154:157], v[170:173], v[40:43]
	v_mfma_f32_16x16x32_bf16 v[28:31], v[142:145], v[178:181], v[28:31]
	v_mfma_f32_16x16x32_bf16 v[24:27], v[154:157], v[178:181], v[24:27]
	v_mfma_f32_16x16x32_bf16 v[12:15], v[142:145], v[186:189], v[12:15]
	v_mfma_f32_16x16x32_bf16 v[8:11], v[154:157], v[186:189], v[8:11]
	v_mfma_f32_16x16x32_bf16 v[60:63], v[150:153], v[166:169], v[60:63]
	v_mfma_f32_16x16x32_bf16 v[56:59], v[158:161], v[166:169], v[56:59]
	v_mfma_f32_16x16x32_bf16 v[44:47], v[150:153], v[174:177], v[44:47]
	v_mfma_f32_16x16x32_bf16 v[40:43], v[158:161], v[174:177], v[40:43]
	v_mfma_f32_16x16x32_bf16 v[28:31], v[150:153], v[182:185], v[28:31]
	v_mfma_f32_16x16x32_bf16 v[24:27], v[158:161], v[182:185], v[24:27]
	v_mfma_f32_16x16x32_bf16 v[12:15], v[150:153], v[190:193], v[12:15]
	v_mfma_f32_16x16x32_bf16 v[8:11], v[158:161], v[190:193], v[8:11]
	s_barrier
	s_setprio 1
	s_add_u32 s48, s48, 0x40080
	s_addc_u32 s49, s49, 0
	s_add_i32 s50, s50, s56
	v_lshl_add_u64 v[142:143], s[48:49], 0, v[134:135]
	s_mov_b32 m0, s50
	s_nop 0
	global_load_lds_dwordx4 v[142:143], off
	v_lshl_add_u64 v[142:143], s[48:49], 0, v[130:131]
	s_add_i32 m0, s50, 0x2000
	s_nop 0
	global_load_lds_dwordx4 v[142:143], off
	s_waitcnt vmcnt(6)
	s_barrier
	s_setprio 0
	v_mfma_f32_16x16x32_bf16 v[52:55], v[194:197], v[162:165], v[52:55]
	v_mfma_f32_16x16x32_bf16 v[48:51], v[202:205], v[162:165], v[48:51]
	v_mfma_f32_16x16x32_bf16 v[36:39], v[194:197], v[170:173], v[36:39]
	v_mfma_f32_16x16x32_bf16 v[32:35], v[202:205], v[170:173], v[32:35]
	v_mfma_f32_16x16x32_bf16 v[20:23], v[194:197], v[178:181], v[20:23]
	v_mfma_f32_16x16x32_bf16 v[16:19], v[202:205], v[178:181], v[16:19]
	v_mfma_f32_16x16x32_bf16 v[4:7], v[194:197], v[186:189], v[4:7]
	v_mfma_f32_16x16x32_bf16 v[0:3], v[202:205], v[186:189], v[0:3]
	v_mfma_f32_16x16x32_bf16 v[52:55], v[198:201], v[166:169], v[52:55]
	v_mfma_f32_16x16x32_bf16 v[48:51], v[208:211], v[166:169], v[48:51]
	v_mfma_f32_16x16x32_bf16 v[36:39], v[198:201], v[174:177], v[36:39]
	v_mfma_f32_16x16x32_bf16 v[32:35], v[208:211], v[174:177], v[32:35]
	v_mfma_f32_16x16x32_bf16 v[20:23], v[198:201], v[182:185], v[20:23]
	v_mfma_f32_16x16x32_bf16 v[16:19], v[208:211], v[182:185], v[16:19]
	v_mfma_f32_16x16x32_bf16 v[4:7], v[198:201], v[190:193], v[4:7]
	v_mfma_f32_16x16x32_bf16 v[0:3], v[208:211], v[190:193], v[0:3]
	s_add_i32 s70, s70, 2
	s_add_u32 s46, s46, 0x100
	s_addc_u32 s47, s47, 0
	s_add_u32 s68, s68, 0x100
	s_addc_u32 s69, s69, 0
	s_cmp_gt_u32 s70, 13
	s_barrier
	s_cbranch_scc0 .LBB0_152
	s_and_b32 s1, s65, -4
	s_cmp_eq_u32 s1, 4
	s_mov_b32 s1, 0xee00000
	s_cselect_b32 s1, s1, 0x13200000
	s_cmp_gt_u32 s65, 3
	s_cselect_b32 s1, s1, 0x6600000
	s_add_u32 s46, s74, s1
	s_addc_u32 s47, s75, 0
	s_lshl_b32 s1, s65, 8
	s_and_b32 s1, s1, 0x300
	v_mul_f32_e32 v122, 0xbfb8aa3b, v122
	v_or_b32_e32 v96, s1, v148
	v_exp_f32_e32 v122, v122
	v_mul_f32_e32 v123, 0xbfb8aa3b, v123
	v_lshl_add_u32 v144, s44, 8, v146
	v_lshlrev_b32_e32 v96, 1, v96
	v_exp_f32_e32 v123, v123
	v_lshl_add_u64 v[142:143], s[46:47], 0, v[96:97]
	v_ashrrev_i32_e32 v145, 31, v144
	v_mul_f32_e32 v96, 0xbfb8aa3b, v126
	v_mul_f32_e32 v126, 0xbfb8aa3b, v127
	v_lshlrev_b64 v[150:151], 11, v[144:145]
	v_exp_f32_e32 v96, v96
	v_exp_f32_e32 v145, v126
	v_add_f32_e32 v122, 1.0, v122
	v_lshl_add_u64 v[126:127], v[142:143], 0, v[150:151]
	v_rcp_f32_e32 v150, v122
	v_add_f32_e32 v122, 1.0, v123
	v_mul_f32_e32 v123, 0xbfb8aa3b, v124
	v_exp_f32_e32 v123, v123
	v_mul_f32_e32 v124, 0xbfb8aa3b, v125
	v_mul_f32_e32 v114, 0xbfb8aa3b, v114
	v_add_f32_e32 v96, 1.0, v96
	v_add_f32_e32 v145, 1.0, v145
	v_mul_f32_e32 v128, 0xbfb8aa3b, v128
	v_mul_f32_e32 v129, 0xbfb8aa3b, v129
	v_exp_f32_e32 v124, v124
	v_exp_f32_e32 v114, v114
	v_mul_f32_e32 v115, 0xbfb8aa3b, v115
	v_rcp_f32_e32 v96, v96
	v_exp_f32_e32 v128, v128
	v_exp_f32_e32 v129, v129
	v_rcp_f32_e32 v145, v145
	v_exp_f32_e32 v115, v115
	v_rcp_f32_e32 v125, v122
	v_add_f32_e32 v122, 1.0, v123
	v_rcp_f32_e32 v151, v122
	v_add_f32_e32 v122, 1.0, v124
	v_add_f32_e32 v114, 1.0, v114
	v_add_f32_e32 v128, 1.0, v128
	v_add_f32_e32 v129, 1.0, v129
	v_rcp_f32_e32 v152, v122
	v_cvt_pk_bf16_f32 v122, v96, v145
	v_mul_f32_e32 v96, 0xbfb8aa3b, v118
	v_mul_f32_e32 v118, 0xbfb8aa3b, v119
	v_mul_f32_e32 v119, 0xbfb8aa3b, v120
	v_mul_f32_e32 v120, 0xbfb8aa3b, v121
	v_rcp_f32_e32 v121, v114
	v_add_f32_e32 v114, 1.0, v115
	v_mul_f32_e32 v115, 0xbfb8aa3b, v116
	v_rcp_f32_e32 v128, v128
	v_rcp_f32_e32 v129, v129
	v_exp_f32_e32 v115, v115
	v_mul_f32_e32 v116, 0xbfb8aa3b, v117
	v_exp_f32_e32 v96, v96
	v_exp_f32_e32 v118, v118
	v_exp_f32_e32 v119, v119
	v_exp_f32_e32 v120, v120
	v_exp_f32_e32 v116, v116
	v_cvt_pk_bf16_f32 v123, v128, v129
	v_cvt_pk_bf16_f32 v124, v150, v125
	v_cvt_pk_bf16_f32 v125, v151, v152
	v_rcp_f32_e32 v117, v114
	v_add_f32_e32 v114, 1.0, v115
	global_store_dwordx4 v[126:127], v[122:125], off
	v_add_f32_e32 v96, 1.0, v96
	v_add_f32_e32 v118, 1.0, v118
	v_add_f32_e32 v119, 1.0, v119
	v_add_f32_e32 v120, 1.0, v120
	v_rcp_f32_e32 v122, v114
	v_add_f32_e32 v114, 1.0, v116
	v_rcp_f32_e32 v96, v96
	v_rcp_f32_e32 v118, v118
	v_rcp_f32_e32 v119, v119
	v_rcp_f32_e32 v120, v120
	v_rcp_f32_e32 v123, v114
	v_mul_f32_e32 v106, 0xbfb8aa3b, v106
	v_exp_f32_e32 v106, v106
	v_mul_f32_e32 v107, 0xbfb8aa3b, v107
	v_cvt_pk_bf16_f32 v114, v96, v118
	v_cvt_pk_bf16_f32 v115, v119, v120
	v_cvt_pk_bf16_f32 v116, v121, v117
; DEV float sigmoidf_(float x) { return __builtin_amdgcn_rcpf(1.f + __expf(-x)); }
;   DEV void operator()(const f32x4 (&acc)[2][2][4][2], const pg8::Unit& u, int wr, int wc, int fr, int fq) const {
;     const int b = u.pn >> 2, pn = u.pn & 3;
;     bf16_t* G = (bf16_t*)(ws + (b == 0 ? O_G1 : (b == 1 ? O_G2 : O_G3)));
;     const int row0 = u.pm * 256 + wr * 64 + fr, col0 = pn * 256 + wc * 32 + 8 * fq;
; #pragma unroll
;     for (int ai = 0; ai < 2; ++ai)
; #pragma unroll
;       for (int m = 0; m < 4; ++m) {
;         const int row = row0 + ai * 128 + m * 16;
; #pragma unroll
;         for (int bj = 0; bj < 2; ++bj) {
;           const f32x4 a0 = acc[ai][bj][m][0], a1 = acc[ai][bj][m][1];
;           u32x4 o;
;           o[0] = pk2(sigmoidf_(a0[0]), sigmoidf_(a0[1])); o[1] = pk2(sigmoidf_(a0[2]), sigmoidf_(a0[3]));
;           o[2] = pk2(sigmoidf_(a1[0]), sigmoidf_(a1[1])); o[3] = pk2(sigmoidf_(a1[2]), sigmoidf_(a1[3]));
;           *(u32x4*)(G + (size_t)row * DM + col0 + bj * 128) = o;
;         }
;       }
;   }
	v_cvt_pk_bf16_f32 v117, v122, v123
	v_exp_f32_e32 v107, v107
	global_store_dwordx4 v[126:127], v[114:117], off offset:256
	v_mul_f32_e32 v96, 0xbfb8aa3b, v110
	v_mul_f32_e32 v110, 0xbfb8aa3b, v111
	v_or_b32_e32 v114, 16, v144
	v_ashrrev_i32_e32 v115, 31, v114
	v_exp_f32_e32 v96, v96
	v_exp_f32_e32 v116, v110
	v_lshlrev_b64 v[114:115], 11, v[114:115]
	v_add_f32_e32 v106, 1.0, v106
	v_lshl_add_u64 v[110:111], v[142:143], 0, v[114:115]
	v_rcp_f32_e32 v115, v106
	v_add_f32_e32 v106, 1.0, v107
	v_mul_f32_e32 v107, 0xbfb8aa3b, v108
	v_exp_f32_e32 v107, v107
	v_mul_f32_e32 v108, 0xbfb8aa3b, v109
	v_mul_f32_e32 v98, 0xbfb8aa3b, v98
	v_add_f32_e32 v96, 1.0, v96
	v_add_f32_e32 v114, 1.0, v116
	v_mul_f32_e32 v112, 0xbfb8aa3b, v112
	v_mul_f32_e32 v113, 0xbfb8aa3b, v113
	v_exp_f32_e32 v108, v108
	v_exp_f32_e32 v98, v98
	v_mul_f32_e32 v99, 0xbfb8aa3b, v99
	v_rcp_f32_e32 v96, v96
	v_exp_f32_e32 v112, v112
	v_exp_f32_e32 v113, v113
	v_rcp_f32_e32 v114, v114
	v_exp_f32_e32 v99, v99
	v_rcp_f32_e32 v109, v106
	v_add_f32_e32 v106, 1.0, v107
	v_rcp_f32_e32 v116, v106
	v_add_f32_e32 v106, 1.0, v108
	v_add_f32_e32 v98, 1.0, v98
	v_add_f32_e32 v112, 1.0, v112
	v_add_f32_e32 v113, 1.0, v113
	v_rcp_f32_e32 v117, v106
	v_cvt_pk_bf16_f32 v106, v96, v114
	v_mul_f32_e32 v96, 0xbfb8aa3b, v102
	v_mul_f32_e32 v102, 0xbfb8aa3b, v103
	v_mul_f32_e32 v103, 0xbfb8aa3b, v104
	v_mul_f32_e32 v104, 0xbfb8aa3b, v105
	v_rcp_f32_e32 v105, v98
	v_add_f32_e32 v98, 1.0, v99
	v_mul_f32_e32 v99, 0xbfb8aa3b, v100
	v_rcp_f32_e32 v112, v112
	v_rcp_f32_e32 v113, v113
	v_exp_f32_e32 v99, v99
	v_mul_f32_e32 v100, 0xbfb8aa3b, v101
	v_exp_f32_e32 v96, v96
	v_exp_f32_e32 v102, v102
	v_exp_f32_e32 v103, v103
	v_exp_f32_e32 v104, v104
	v_exp_f32_e32 v100, v100
	v_cvt_pk_bf16_f32 v107, v112, v113
	v_cvt_pk_bf16_f32 v108, v115, v109
	v_cvt_pk_bf16_f32 v109, v116, v117
	v_rcp_f32_e32 v101, v98
	v_add_f32_e32 v98, 1.0, v99
	global_store_dwordx4 v[110:111], v[106:109], off
	v_add_f32_e32 v96, 1.0, v96
	v_add_f32_e32 v102, 1.0, v102
	v_add_f32_e32 v103, 1.0, v103
	v_add_f32_e32 v104, 1.0, v104
	v_rcp_f32_e32 v106, v98
	v_add_f32_e32 v98, 1.0, v100
	v_rcp_f32_e32 v96, v96
	v_rcp_f32_e32 v102, v102
	v_rcp_f32_e32 v103, v103
	v_rcp_f32_e32 v104, v104
	v_rcp_f32_e32 v107, v98
	v_mul_f32_e32 v88, 0xbfb8aa3b, v88
	v_exp_f32_e32 v88, v88
	v_mul_f32_e32 v89, 0xbfb8aa3b, v89
	v_cvt_pk_bf16_f32 v98, v96, v102
	v_cvt_pk_bf16_f32 v99, v103, v104
	v_cvt_pk_bf16_f32 v100, v105, v101
	v_cvt_pk_bf16_f32 v101, v106, v107
	v_exp_f32_e32 v89, v89
	global_store_dwordx4 v[110:111], v[98:101], off offset:256
	v_mul_f32_e32 v92, 0xbfb8aa3b, v92
	v_exp_f32_e32 v96, v92
	v_or_b32_e32 v98, 32, v144
	v_ashrrev_i32_e32 v99, 31, v98
	v_lshlrev_b64 v[98:99], 11, v[98:99]
	v_mul_f32_e32 v92, 0xbfb8aa3b, v93
	v_add_f32_e32 v88, 1.0, v88
	v_exp_f32_e32 v100, v92
	v_lshl_add_u64 v[92:93], v[142:143], 0, v[98:99]
	v_rcp_f32_e32 v99, v88
	v_add_f32_e32 v88, 1.0, v89
	v_mul_f32_e32 v89, 0xbfb8aa3b, v90
	v_mul_f32_e32 v94, 0xbfb8aa3b, v94
	v_mul_f32_e32 v95, 0xbfb8aa3b, v95
	v_exp_f32_e32 v89, v89
	v_mul_f32_e32 v90, 0xbfb8aa3b, v91
	v_exp_f32_e32 v94, v94
	v_exp_f32_e32 v95, v95
	v_exp_f32_e32 v90, v90
	v_rcp_f32_e32 v91, v88
	v_add_f32_e32 v88, 1.0, v89
	v_add_f32_e32 v96, 1.0, v96
	v_add_f32_e32 v98, 1.0, v100
	v_add_f32_e32 v94, 1.0, v94
	v_add_f32_e32 v95, 1.0, v95
	v_rcp_f32_e32 v100, v88
	v_add_f32_e32 v88, 1.0, v90
	v_mul_f32_e32 v80, 0xbfb8aa3b, v80
	v_rcp_f32_e32 v96, v96
	v_rcp_f32_e32 v98, v98
	v_rcp_f32_e32 v94, v94
	v_rcp_f32_e32 v95, v95
	v_rcp_f32_e32 v101, v88
	v_exp_f32_e32 v80, v80
	v_mul_f32_e32 v81, 0xbfb8aa3b, v81
	v_exp_f32_e32 v81, v81
	v_cvt_pk_bf16_f32 v88, v96, v98
	v_cvt_pk_bf16_f32 v89, v94, v95
	v_cvt_pk_bf16_f32 v90, v99, v91
	v_cvt_pk_bf16_f32 v91, v100, v101
	v_add_f32_e32 v80, 1.0, v80
	global_store_dwordx4 v[92:93], v[88:91], off
	v_mul_f32_e32 v84, 0xbfb8aa3b, v84
	v_mul_f32_e32 v85, 0xbfb8aa3b, v85
	v_rcp_f32_e32 v88, v80
	v_add_f32_e32 v80, 1.0, v81
	v_mul_f32_e32 v81, 0xbfb8aa3b, v82
	v_mul_f32_e32 v86, 0xbfb8aa3b, v86
	v_mul_f32_e32 v87, 0xbfb8aa3b, v87
	v_exp_f32_e32 v81, v81
	v_mul_f32_e32 v82, 0xbfb8aa3b, v83
	v_exp_f32_e32 v84, v84
	v_exp_f32_e32 v85, v85
	v_exp_f32_e32 v86, v86
	v_exp_f32_e32 v87, v87
	v_exp_f32_e32 v82, v82
	v_rcp_f32_e32 v83, v80
	v_add_f32_e32 v80, 1.0, v81
	v_add_f32_e32 v84, 1.0, v84
	v_add_f32_e32 v85, 1.0, v85
	v_add_f32_e32 v86, 1.0, v86
	v_add_f32_e32 v87, 1.0, v87
	v_rcp_f32_e32 v89, v80
	v_add_f32_e32 v80, 1.0, v82
	v_rcp_f32_e32 v84, v84
	v_rcp_f32_e32 v85, v85
	v_rcp_f32_e32 v86, v86
	v_rcp_f32_e32 v87, v87
	v_rcp_f32_e32 v90, v80
	v_mul_f32_e32 v72, 0xbfb8aa3b, v72
	v_cvt_pk_bf16_f32 v80, v84, v85
	v_cvt_pk_bf16_f32 v81, v86, v87
	v_cvt_pk_bf16_f32 v82, v88, v83
	v_cvt_pk_bf16_f32 v83, v89, v90
	v_mul_f32_e32 v76, 0xbfb8aa3b, v76
	v_exp_f32_e32 v72, v72
	v_mul_f32_e32 v73, 0xbfb8aa3b, v73
	global_store_dwordx4 v[92:93], v[80:83], off offset:256
	v_exp_f32_e32 v73, v73
	v_add_f32_e32 v72, 1.0, v72
	v_exp_f32_e32 v82, v76
	v_or_b32_e32 v80, 48, v144
	v_ashrrev_i32_e32 v81, 31, v80
	v_lshlrev_b64 v[80:81], 11, v[80:81]
	v_mul_f32_e32 v76, 0xbfb8aa3b, v77
	v_exp_f32_e32 v83, v76
	v_lshl_add_u64 v[76:77], v[142:143], 0, v[80:81]
	v_add_f32_e32 v80, 1.0, v82
	v_rcp_f32_e32 v82, v72
	v_add_f32_e32 v72, 1.0, v73
	v_mul_f32_e32 v73, 0xbfb8aa3b, v74
	v_mul_f32_e32 v78, 0xbfb8aa3b, v78
	v_mul_f32_e32 v79, 0xbfb8aa3b, v79
	v_exp_f32_e32 v73, v73
	v_mul_f32_e32 v74, 0xbfb8aa3b, v75
	v_exp_f32_e32 v78, v78
	v_exp_f32_e32 v79, v79
	v_exp_f32_e32 v74, v74
	v_rcp_f32_e32 v75, v72
	v_add_f32_e32 v72, 1.0, v73
	v_add_f32_e32 v81, 1.0, v83
	v_add_f32_e32 v78, 1.0, v78
; DEV float sigmoidf_(float x) { return __builtin_amdgcn_rcpf(1.f + __expf(-x)); }
;   DEV void operator()(const f32x4 (&acc)[2][2][4][2], const pg8::Unit& u, int wr, int wc, int fr, int fq) const {
;     const int b = u.pn >> 2, pn = u.pn & 3;
;     bf16_t* G = (bf16_t*)(ws + (b == 0 ? O_G1 : (b == 1 ? O_G2 : O_G3)));
;     const int row0 = u.pm * 256 + wr * 64 + fr, col0 = pn * 256 + wc * 32 + 8 * fq;
; #pragma unroll
;     for (int ai = 0; ai < 2; ++ai)
; #pragma unroll
;       for (int m = 0; m < 4; ++m) {
;         const int row = row0 + ai * 128 + m * 16;
; #pragma unroll
;         for (int bj = 0; bj < 2; ++bj) {
;           const f32x4 a0 = acc[ai][bj][m][0], a1 = acc[ai][bj][m][1];
;           u32x4 o;
;           o[0] = pk2(sigmoidf_(a0[0]), sigmoidf_(a0[1])); o[1] = pk2(sigmoidf_(a0[2]), sigmoidf_(a0[3]));
;           o[2] = pk2(sigmoidf_(a1[0]), sigmoidf_(a1[1])); o[3] = pk2(sigmoidf_(a1[2]), sigmoidf_(a1[3]));
;           *(u32x4*)(G + (size_t)row * DM + col0 + bj * 128) = o;
;         }
;       }
;   }
	v_add_f32_e32 v79, 1.0, v79
	v_rcp_f32_e32 v83, v72
	v_add_f32_e32 v72, 1.0, v74
	v_mul_f32_e32 v64, 0xbfb8aa3b, v64
	v_rcp_f32_e32 v80, v80
	v_rcp_f32_e32 v81, v81
	v_rcp_f32_e32 v78, v78
	v_rcp_f32_e32 v79, v79
	v_rcp_f32_e32 v84, v72
	v_exp_f32_e32 v64, v64
	v_mul_f32_e32 v65, 0xbfb8aa3b, v65
	v_exp_f32_e32 v65, v65
	v_cvt_pk_bf16_f32 v72, v80, v81
	v_cvt_pk_bf16_f32 v73, v78, v79
	v_cvt_pk_bf16_f32 v74, v82, v75
	v_cvt_pk_bf16_f32 v75, v83, v84
	v_add_f32_e32 v64, 1.0, v64
	global_store_dwordx4 v[76:77], v[72:75], off
	v_mul_f32_e32 v68, 0xbfb8aa3b, v68
	v_mul_f32_e32 v69, 0xbfb8aa3b, v69
	v_rcp_f32_e32 v72, v64
	v_add_f32_e32 v64, 1.0, v65
	v_mul_f32_e32 v65, 0xbfb8aa3b, v66
	v_mul_f32_e32 v70, 0xbfb8aa3b, v70
	v_mul_f32_e32 v71, 0xbfb8aa3b, v71
	v_exp_f32_e32 v65, v65
	v_mul_f32_e32 v66, 0xbfb8aa3b, v67
	v_exp_f32_e32 v68, v68
	v_exp_f32_e32 v69, v69
	v_exp_f32_e32 v70, v70
	v_exp_f32_e32 v71, v71
	v_exp_f32_e32 v66, v66
	v_rcp_f32_e32 v67, v64
	v_add_f32_e32 v64, 1.0, v65
	v_add_f32_e32 v68, 1.0, v68
	v_add_f32_e32 v69, 1.0, v69
	v_add_f32_e32 v70, 1.0, v70
	v_add_f32_e32 v71, 1.0, v71
	v_rcp_f32_e32 v73, v64
	v_add_f32_e32 v64, 1.0, v66
	v_mul_f32_e32 v56, 0xbfb8aa3b, v56
	v_rcp_f32_e32 v68, v68
	v_rcp_f32_e32 v69, v69
	v_rcp_f32_e32 v70, v70
	v_rcp_f32_e32 v71, v71
	v_rcp_f32_e32 v74, v64
	v_exp_f32_e32 v56, v56
	v_mul_f32_e32 v57, 0xbfb8aa3b, v57
	v_exp_f32_e32 v57, v57
	v_cvt_pk_bf16_f32 v64, v68, v69
	v_cvt_pk_bf16_f32 v65, v70, v71
	v_cvt_pk_bf16_f32 v66, v72, v67
	v_cvt_pk_bf16_f32 v67, v73, v74
	v_add_f32_e32 v56, 1.0, v56
	global_store_dwordx4 v[76:77], v[64:67], off offset:256
	v_mul_f32_e32 v60, 0xbfb8aa3b, v60
	v_mul_f32_e32 v62, 0xbfb8aa3b, v62
	v_mul_f32_e32 v63, 0xbfb8aa3b, v63
	v_rcp_f32_e32 v66, v56
	v_add_f32_e32 v56, 1.0, v57
	v_mul_f32_e32 v57, 0xbfb8aa3b, v58
	v_exp_f32_e32 v64, v60
	v_mul_f32_e32 v60, 0xbfb8aa3b, v61
	v_exp_f32_e32 v62, v62
	v_exp_f32_e32 v63, v63
	v_exp_f32_e32 v57, v57
	v_mul_f32_e32 v58, 0xbfb8aa3b, v59
	v_exp_f32_e32 v65, v60
	v_exp_f32_e32 v58, v58
	v_add_f32_e32 v62, 1.0, v62
	v_add_f32_e32 v63, 1.0, v63
	v_rcp_f32_e32 v59, v56
	v_add_f32_e32 v56, 1.0, v57
	v_add_f32_e32 v64, 1.0, v64
	v_add_f32_e32 v65, 1.0, v65
	v_rcp_f32_e32 v62, v62
	v_rcp_f32_e32 v63, v63
	v_rcp_f32_e32 v67, v56
	v_add_f32_e32 v56, 1.0, v58
	v_mul_f32_e32 v48, 0xbfb8aa3b, v48
	v_rcp_f32_e32 v64, v64
	v_rcp_f32_e32 v65, v65
	v_rcp_f32_e32 v68, v56
	v_exp_f32_e32 v48, v48
	v_mul_f32_e32 v49, 0xbfb8aa3b, v49
	v_exp_f32_e32 v49, v49
	s_mov_b32 s1, 0x40000
	v_cvt_pk_bf16_f32 v57, v62, v63
	v_add_co_u32_e32 v62, vcc, s1, v126
	v_cvt_pk_bf16_f32 v56, v64, v65
	v_cvt_pk_bf16_f32 v58, v66, v59
	v_cvt_pk_bf16_f32 v59, v67, v68
	v_addc_co_u32_e32 v63, vcc, 0, v127, vcc
	v_add_f32_e32 v48, 1.0, v48
	global_store_dwordx4 v[62:63], v[56:59], off
	v_mul_f32_e32 v52, 0xbfb8aa3b, v52
	v_mul_f32_e32 v53, 0xbfb8aa3b, v53
	v_rcp_f32_e32 v56, v48
	v_add_f32_e32 v48, 1.0, v49
	v_mul_f32_e32 v49, 0xbfb8aa3b, v50
	v_mul_f32_e32 v54, 0xbfb8aa3b, v54
	v_mul_f32_e32 v55, 0xbfb8aa3b, v55
	v_exp_f32_e32 v49, v49
	v_mul_f32_e32 v50, 0xbfb8aa3b, v51
	v_exp_f32_e32 v52, v52
	v_exp_f32_e32 v53, v53
	v_exp_f32_e32 v54, v54
	v_exp_f32_e32 v55, v55
	v_exp_f32_e32 v50, v50
	v_rcp_f32_e32 v51, v48
	v_add_f32_e32 v48, 1.0, v49
	v_add_f32_e32 v52, 1.0, v52
	v_add_f32_e32 v53, 1.0, v53
	v_add_f32_e32 v54, 1.0, v54
	v_add_f32_e32 v55, 1.0, v55
	v_rcp_f32_e32 v57, v48
	v_add_f32_e32 v48, 1.0, v50
	v_mul_f32_e32 v40, 0xbfb8aa3b, v40
	v_rcp_f32_e32 v52, v52
	v_rcp_f32_e32 v53, v53
	v_rcp_f32_e32 v54, v54
	v_rcp_f32_e32 v55, v55
	v_rcp_f32_e32 v58, v48
	v_exp_f32_e32 v40, v40
	v_mul_f32_e32 v41, 0xbfb8aa3b, v41
	v_exp_f32_e32 v41, v41
	s_mov_b64 s[46:47], 0x40000
	v_lshl_add_u64 v[60:61], v[126:127], 0, s[46:47]
	v_cvt_pk_bf16_f32 v48, v52, v53
	v_cvt_pk_bf16_f32 v49, v54, v55
	v_cvt_pk_bf16_f32 v50, v56, v51
	v_cvt_pk_bf16_f32 v51, v57, v58
	v_add_f32_e32 v40, 1.0, v40
	global_store_dwordx4 v[60:61], v[48:51], off offset:256
	v_mul_f32_e32 v44, 0xbfb8aa3b, v44
	v_mul_f32_e32 v46, 0xbfb8aa3b, v46
	v_mul_f32_e32 v47, 0xbfb8aa3b, v47
	v_rcp_f32_e32 v50, v40
	v_add_f32_e32 v40, 1.0, v41
	v_mul_f32_e32 v41, 0xbfb8aa3b, v42
	v_exp_f32_e32 v48, v44
	v_mul_f32_e32 v44, 0xbfb8aa3b, v45
	v_exp_f32_e32 v46, v46
	v_exp_f32_e32 v47, v47
	v_exp_f32_e32 v41, v41
	v_mul_f32_e32 v42, 0xbfb8aa3b, v43
	v_exp_f32_e32 v49, v44
	v_exp_f32_e32 v42, v42
	v_add_f32_e32 v46, 1.0, v46
	v_add_f32_e32 v47, 1.0, v47
	v_rcp_f32_e32 v43, v40
	v_add_f32_e32 v40, 1.0, v41
	v_add_f32_e32 v48, 1.0, v48
	v_add_f32_e32 v49, 1.0, v49
	v_rcp_f32_e32 v46, v46
	v_rcp_f32_e32 v47, v47
	v_rcp_f32_e32 v51, v40
	v_add_f32_e32 v40, 1.0, v42
	v_mul_f32_e32 v32, 0xbfb8aa3b, v32
	v_rcp_f32_e32 v48, v48
	v_rcp_f32_e32 v49, v49
	v_rcp_f32_e32 v52, v40
	v_exp_f32_e32 v32, v32
	v_mul_f32_e32 v33, 0xbfb8aa3b, v33
	v_exp_f32_e32 v33, v33
	s_mov_b32 s1, 0x48000
	v_cvt_pk_bf16_f32 v41, v46, v47
	v_add_co_u32_e32 v46, vcc, s1, v126
	v_cvt_pk_bf16_f32 v40, v48, v49
	v_cvt_pk_bf16_f32 v42, v50, v43
	v_cvt_pk_bf16_f32 v43, v51, v52
	v_addc_co_u32_e32 v47, vcc, 0, v127, vcc
	v_add_f32_e32 v32, 1.0, v32
	global_store_dwordx4 v[46:47], v[40:43], off
	v_mul_f32_e32 v36, 0xbfb8aa3b, v36
	v_mul_f32_e32 v37, 0xbfb8aa3b, v37
	v_rcp_f32_e32 v40, v32
	v_add_f32_e32 v32, 1.0, v33
	v_mul_f32_e32 v33, 0xbfb8aa3b, v34
	v_mul_f32_e32 v38, 0xbfb8aa3b, v38
	v_mul_f32_e32 v39, 0xbfb8aa3b, v39
	v_exp_f32_e32 v33, v33
	v_mul_f32_e32 v34, 0xbfb8aa3b, v35
	v_exp_f32_e32 v36, v36
	v_exp_f32_e32 v37, v37
	v_exp_f32_e32 v38, v38
	v_exp_f32_e32 v39, v39
; DEV float sigmoidf_(float x) { return __builtin_amdgcn_rcpf(1.f + __expf(-x)); }
; #define PG8_WAIT_V(n) asm volatile("s_waitcnt vmcnt(" #n ")" ::: "memory")
; #define PG8_BAR __builtin_amdgcn_s_barrier()
; template <class Epi, class Sched>
; __device__ __forceinline__ void gemm_phase(PG8_LAS unsigned char* lds, const Gemm g, const Sched& S, const Epi& E) {
;     ...
;         if (!has_next) break;
; #pragma unroll
;         for (int a = 0; a < 2; ++a)
; #pragma unroll
;             for (int b = 0; b < 2; ++b)
; #pragma unroll
;                 for (int m = 0; m < 4; ++m)
; #pragma unroll
;                     for (int n = 0; n < 2; ++n) acc[a][b][m][n] = (f32x4){0.f, 0.f, 0.f, 0.f};
;         cur = nxt; cA = nA; cB = nB; ++ui;
;     }
;     PG8_WAIT_V(0);
;     if (wr == 0) PG8_BAR;
;   DEV void operator()(const f32x4 (&acc)[2][2][4][2], const pg8::Unit& u, int wr, int wc, int fr, int fq) const {
;     const int b = u.pn >> 2, pn = u.pn & 3;
;     bf16_t* G = (bf16_t*)(ws + (b == 0 ? O_G1 : (b == 1 ? O_G2 : O_G3)));
;     const int row0 = u.pm * 256 + wr * 64 + fr, col0 = pn * 256 + wc * 32 + 8 * fq;
; #pragma unroll
;     for (int ai = 0; ai < 2; ++ai)
; #pragma unroll
;       for (int m = 0; m < 4; ++m) {
;         const int row = row0 + ai * 128 + m * 16;
; #pragma unroll
;         for (int bj = 0; bj < 2; ++bj) {
;           const f32x4 a0 = acc[ai][bj][m][0], a1 = acc[ai][bj][m][1];
;           u32x4 o;
;           o[0] = pk2(sigmoidf_(a0[0]), sigmoidf_(a0[1])); o[1] = pk2(sigmoidf_(a0[2]), sigmoidf_(a0[3]));
;           o[2] = pk2(sigmoidf_(a1[0]), sigmoidf_(a1[1])); o[3] = pk2(sigmoidf_(a1[2]), sigmoidf_(a1[3]));
;           *(u32x4*)(G + (size_t)row * DM + col0 + bj * 128) = o;
;         }
;       }
;   }
	v_exp_f32_e32 v34, v34
	v_rcp_f32_e32 v35, v32
	v_add_f32_e32 v32, 1.0, v33
	v_add_f32_e32 v36, 1.0, v36
	v_add_f32_e32 v37, 1.0, v37
	v_add_f32_e32 v38, 1.0, v38
	v_add_f32_e32 v39, 1.0, v39
	v_rcp_f32_e32 v41, v32
	v_add_f32_e32 v32, 1.0, v34
	v_mul_f32_e32 v24, 0xbfb8aa3b, v24
	v_rcp_f32_e32 v36, v36
	v_rcp_f32_e32 v37, v37
	v_rcp_f32_e32 v38, v38
	v_rcp_f32_e32 v39, v39
	v_rcp_f32_e32 v42, v32
	v_exp_f32_e32 v24, v24
	v_mul_f32_e32 v25, 0xbfb8aa3b, v25
	v_exp_f32_e32 v25, v25
	s_mov_b64 s[46:47], 0x48000
	v_lshl_add_u64 v[44:45], v[126:127], 0, s[46:47]
	v_cvt_pk_bf16_f32 v32, v36, v37
	v_cvt_pk_bf16_f32 v33, v38, v39
	v_cvt_pk_bf16_f32 v34, v40, v35
	v_cvt_pk_bf16_f32 v35, v41, v42
	v_add_f32_e32 v24, 1.0, v24
	global_store_dwordx4 v[44:45], v[32:35], off offset:256
	v_mul_f32_e32 v28, 0xbfb8aa3b, v28
	v_mul_f32_e32 v30, 0xbfb8aa3b, v30
	v_mul_f32_e32 v31, 0xbfb8aa3b, v31
	v_rcp_f32_e32 v34, v24
	v_add_f32_e32 v24, 1.0, v25
	v_mul_f32_e32 v25, 0xbfb8aa3b, v26
	v_exp_f32_e32 v32, v28
	v_mul_f32_e32 v28, 0xbfb8aa3b, v29
	v_exp_f32_e32 v30, v30
	v_exp_f32_e32 v31, v31
	v_exp_f32_e32 v25, v25
	v_mul_f32_e32 v26, 0xbfb8aa3b, v27
	v_exp_f32_e32 v33, v28
	v_exp_f32_e32 v26, v26
	v_add_f32_e32 v30, 1.0, v30
	v_add_f32_e32 v31, 1.0, v31
	v_rcp_f32_e32 v27, v24
	v_add_f32_e32 v24, 1.0, v25
	v_add_f32_e32 v32, 1.0, v32
	v_add_f32_e32 v33, 1.0, v33
	v_rcp_f32_e32 v30, v30
	v_rcp_f32_e32 v31, v31
	v_rcp_f32_e32 v35, v24
	v_add_f32_e32 v24, 1.0, v26
	v_mul_f32_e32 v16, 0xbfb8aa3b, v16
	v_rcp_f32_e32 v32, v32
	v_rcp_f32_e32 v33, v33
	v_rcp_f32_e32 v36, v24
	v_exp_f32_e32 v16, v16
	v_mul_f32_e32 v17, 0xbfb8aa3b, v17
	v_exp_f32_e32 v17, v17
	s_mov_b32 s1, 0x50000
	v_cvt_pk_bf16_f32 v25, v30, v31
	v_add_co_u32_e32 v30, vcc, s1, v126
	v_cvt_pk_bf16_f32 v24, v32, v33
	v_cvt_pk_bf16_f32 v26, v34, v27
	v_cvt_pk_bf16_f32 v27, v35, v36
	v_addc_co_u32_e32 v31, vcc, 0, v127, vcc
	v_add_f32_e32 v16, 1.0, v16
	global_store_dwordx4 v[30:31], v[24:27], off
	v_mul_f32_e32 v20, 0xbfb8aa3b, v20
	v_mul_f32_e32 v21, 0xbfb8aa3b, v21
	v_rcp_f32_e32 v24, v16
	v_add_f32_e32 v16, 1.0, v17
	v_mul_f32_e32 v17, 0xbfb8aa3b, v18
	v_mul_f32_e32 v22, 0xbfb8aa3b, v22
	v_mul_f32_e32 v23, 0xbfb8aa3b, v23
	v_exp_f32_e32 v17, v17
	v_mul_f32_e32 v18, 0xbfb8aa3b, v19
	v_exp_f32_e32 v20, v20
	v_exp_f32_e32 v21, v21
	v_exp_f32_e32 v22, v22
	v_exp_f32_e32 v23, v23
	v_exp_f32_e32 v18, v18
	v_rcp_f32_e32 v19, v16
	v_add_f32_e32 v16, 1.0, v17
	v_add_f32_e32 v20, 1.0, v20
	v_add_f32_e32 v21, 1.0, v21
	v_add_f32_e32 v22, 1.0, v22
	v_add_f32_e32 v23, 1.0, v23
	v_rcp_f32_e32 v25, v16
	v_add_f32_e32 v16, 1.0, v18
	v_mul_f32_e32 v8, 0xbfb8aa3b, v8
	v_rcp_f32_e32 v20, v20
	v_rcp_f32_e32 v21, v21
	v_rcp_f32_e32 v22, v22
	v_rcp_f32_e32 v23, v23
	v_rcp_f32_e32 v26, v16
	v_exp_f32_e32 v8, v8
	v_mul_f32_e32 v9, 0xbfb8aa3b, v9
	v_exp_f32_e32 v9, v9
	s_mov_b64 s[46:47], 0x50000
	v_lshl_add_u64 v[28:29], v[126:127], 0, s[46:47]
	v_cvt_pk_bf16_f32 v16, v20, v21
	v_cvt_pk_bf16_f32 v17, v22, v23
	v_cvt_pk_bf16_f32 v18, v24, v19
	v_cvt_pk_bf16_f32 v19, v25, v26
	v_add_f32_e32 v8, 1.0, v8
	global_store_dwordx4 v[28:29], v[16:19], off offset:256
	v_mul_f32_e32 v12, 0xbfb8aa3b, v12
	v_mul_f32_e32 v14, 0xbfb8aa3b, v14
	v_mul_f32_e32 v15, 0xbfb8aa3b, v15
	v_rcp_f32_e32 v18, v8
	v_add_f32_e32 v8, 1.0, v9
	v_mul_f32_e32 v9, 0xbfb8aa3b, v10
	v_exp_f32_e32 v16, v12
	v_mul_f32_e32 v12, 0xbfb8aa3b, v13
	v_exp_f32_e32 v14, v14
	v_exp_f32_e32 v15, v15
	v_exp_f32_e32 v9, v9
	v_mul_f32_e32 v10, 0xbfb8aa3b, v11
	v_exp_f32_e32 v17, v12
	v_exp_f32_e32 v10, v10
	v_add_f32_e32 v14, 1.0, v14
	v_add_f32_e32 v15, 1.0, v15
	v_rcp_f32_e32 v11, v8
	v_add_f32_e32 v8, 1.0, v9
	v_add_f32_e32 v16, 1.0, v16
	v_add_f32_e32 v17, 1.0, v17
	v_rcp_f32_e32 v14, v14
	v_rcp_f32_e32 v15, v15
	v_rcp_f32_e32 v19, v8
	v_add_f32_e32 v8, 1.0, v10
	v_mul_f32_e32 v0, 0xbfb8aa3b, v0
	v_rcp_f32_e32 v16, v16
	v_rcp_f32_e32 v17, v17
	v_rcp_f32_e32 v20, v8
	v_exp_f32_e32 v0, v0
	v_mul_f32_e32 v1, 0xbfb8aa3b, v1
	v_exp_f32_e32 v1, v1
	s_mov_b32 s1, 0x58000
	v_cvt_pk_bf16_f32 v9, v14, v15
	v_add_co_u32_e32 v14, vcc, s1, v126
	v_cvt_pk_bf16_f32 v8, v16, v17
	v_cvt_pk_bf16_f32 v10, v18, v11
	v_cvt_pk_bf16_f32 v11, v19, v20
	v_addc_co_u32_e32 v15, vcc, 0, v127, vcc
	v_add_f32_e32 v0, 1.0, v0
	global_store_dwordx4 v[14:15], v[8:11], off
	v_mul_f32_e32 v4, 0xbfb8aa3b, v4
	v_mul_f32_e32 v5, 0xbfb8aa3b, v5
	v_rcp_f32_e32 v8, v0
	v_add_f32_e32 v0, 1.0, v1
	v_mul_f32_e32 v1, 0xbfb8aa3b, v2
	v_mul_f32_e32 v6, 0xbfb8aa3b, v6
	v_mul_f32_e32 v7, 0xbfb8aa3b, v7
	v_exp_f32_e32 v1, v1
	v_mul_f32_e32 v2, 0xbfb8aa3b, v3
	v_exp_f32_e32 v4, v4
	v_exp_f32_e32 v5, v5
	v_exp_f32_e32 v6, v6
	v_exp_f32_e32 v7, v7
	v_exp_f32_e32 v2, v2
	v_rcp_f32_e32 v3, v0
	v_add_f32_e32 v0, 1.0, v1
	v_add_f32_e32 v4, 1.0, v4
	v_add_f32_e32 v5, 1.0, v5
	v_add_f32_e32 v6, 1.0, v6
	v_add_f32_e32 v7, 1.0, v7
	v_rcp_f32_e32 v9, v0
	v_add_f32_e32 v0, 1.0, v2
	v_rcp_f32_e32 v4, v4
	v_rcp_f32_e32 v5, v5
	v_rcp_f32_e32 v6, v6
	v_rcp_f32_e32 v7, v7
	v_rcp_f32_e32 v10, v0
	s_mov_b64 s[46:47], 0x58000
	v_lshl_add_u64 v[12:13], v[126:127], 0, s[46:47]
	v_cvt_pk_bf16_f32 v0, v4, v5
	v_cvt_pk_bf16_f32 v1, v6, v7
	v_cvt_pk_bf16_f32 v2, v8, v3
	v_cvt_pk_bf16_f32 v3, v9, v10
	s_and_b64 vcc, exec, s[36:37]
	s_mov_b32 s65, s0
	s_mov_b32 s44, s30
	s_mov_b64 s[48:49], s[40:41]
	s_mov_b64 s[46:47], s[38:39]
	global_store_dwordx4 v[12:13], v[0:3], off offset:256
	s_cbranch_vccz .LBB0_149
	s_waitcnt vmcnt(0)
	v_readlane_b32 s64, v255, 38
	s_cmpk_gt_u32 s53, 0xff
	v_readlane_b32 s65, v255, 39
	s_cbranch_scc1 .LBB0_156
	s_barrier

; #define PG8_STAGE(bufoff, gbase, voff) do { _Pragma("unroll") for (int _i = 0; _i < 2; ++_i) \
;         __builtin_amdgcn_global_load_lds((const unsigned*)((const char*)(gbase) + (voff)[_i]), (PG8_LAS unsigned*)(lds + (bufoff) + ldsw + _i * 8192), 16, 0, 0); } while (0)
; #define PG8_LDA(dst, b, h) do { _Pragma("unroll") for (int m = 0; m < 4; ++m) _Pragma("unroll") for (int k = 0; k < 2; ++k) dst[m][k] = *(const PG8_LAS bf16x8*)(lds + PG8_SA(b, h) + aoff + m * 2048 + k * 1024); } while (0)
; #define PG8_LDB(dst, b, h) do { _Pragma("unroll") for (int n = 0; n < 2; ++n) _Pragma("unroll") for (int k = 0; k < 2; ++k) dst[n][k] = *(const PG8_LAS bf16x8*)(lds + PG8_SB(b, h) + boff + n * 2048 + k * 1024); } while (0)
; #define PG8_MMA(ai, bj, At, Bt) do { __builtin_amdgcn_s_setprio(1); _Pragma("unroll") for (int m = 0; m < 4; ++m) _Pragma("unroll") for (int n = 0; n < 2; ++n) _Pragma("unroll") for (int k = 0; k < 2; ++k) \
;         acc[ai][bj][m][n] = __builtin_amdgcn_mfma_f32_16x16x32_bf16(Bt[n][k], At[m][k], acc[ai][bj][m][n], 0, 0, 0); __builtin_amdgcn_s_setprio(0); } while (0)
; #define PG8_WAIT_V(n) asm volatile("s_waitcnt vmcnt(" #n ")" ::: "memory")
; template <class Epi, class Sched>
; __device__ __forceinline__ void gemm_phase(PG8_LAS unsigned char* lds, const Gemm g, const Sched& S, const Epi& E) {
;     ...
;         for (int t = 0; t < nt; t += 2) {
;             const bool last = (t == nt - 2);
;             const char* a1 = cA + (size_t)(t + 1) * kstep;
;             const char* a2 = last ? nA : cA + (size_t)(t + 2) * kstep; const char* b2 = last ? nB : cB + (size_t)(t + 2) * kstep;
;             const char* a3 = a2 + kstep; const char* b3 = b2 + kstep;
;             if (last && has_next) S.a_ready(nxt);
;             PG8_LDB(B0, 0, 0); PG8_SCHED; PG8_LDA(At, 0, 0); PG8_STAGE(PG8_SA(1, 1), a1 + hstep, voffA);
;             PG8_WAIT_L(8); PG8_BAR; PG8_WAIT_L(0); PG8_MMA(0, 0, At, B0); PG8_BAR; PG8_SCHED;
;             PG8_LDB(B1, 0, 1); PG8_STAGE(PG8_SB(0, 0), b2, voffB);
;             PG8_BAR; PG8_WAIT_L(0); PG8_MMA(0, 1, At, B1); PG8_BAR;
;             PG8_LDA(At, 0, 1); PG8_STAGE(PG8_SA(0, 0), a2, voffA);
;             PG8_BAR; PG8_WAIT_L(0); PG8_MMA(1, 0, At, B0); PG8_BAR; PG8_SCHED;
;             PG8_STAGE(PG8_SB(0, 1), b2 + hstep, voffB);
;             PG8_WAIT_V(6); PG8_BAR; PG8_MMA(1, 1, At, B1); PG8_BAR;
.Lgp_21593:
.LBB0_654:
	s_setprio 1
	s_add_u32 s30, s0, 0xfffc0080
	s_addc_u32 s31, s1, -1
	s_add_i32 s62, 0, 0x10000
	v_add_u32_e32 v96, s62, v162
	ds_read_b128 v[144:147], v96
	ds_read_b128 v[148:151], v96 offset:1024
	ds_read_b128 v[152:155], v96 offset:2048
	ds_read_b128 v[156:159], v96 offset:3072
	s_cmp_eq_u32 s61, 12
	s_cselect_b32 s49, s43, s31
	s_cselect_b32 s48, s57, s30
	s_cselect_b32 s31, s41, s60
	s_cselect_b32 s30, s58, s59
	v_lshl_add_u64 v[160:161], s[0:1], 0, v[140:141]
	s_add_i32 m0, s52, 0xc000
	ds_read_b128 v[170:173], v168
	ds_read_b128 v[174:177], v168 offset:1024
	ds_read_b128 v[178:181], v168 offset:2048
	ds_read_b128 v[182:185], v168 offset:3072
	ds_read_b128 v[186:189], v168 offset:4096
	ds_read_b128 v[190:193], v168 offset:5120
	ds_read_b128 v[194:197], v168 offset:6144
	ds_read_b128 v[198:201], v168 offset:7168
	global_load_lds_dwordx4 v[160:161], off
	v_lshl_add_u64 v[160:161], s[0:1], 0, v[142:143]
	s_add_i32 m0, s52, 0xe000
	s_nop 0
	global_load_lds_dwordx4 v[160:161], off
	s_waitcnt lgkmcnt(8)
	s_barrier
	s_setprio 0
	s_waitcnt lgkmcnt(0)
	v_mfma_f32_16x16x32_bf16 v[126:129], v[144:147], v[170:173], v[126:129]
	v_mfma_f32_16x16x32_bf16 v[118:121], v[152:155], v[170:173], v[118:121]
	v_mfma_f32_16x16x32_bf16 v[110:113], v[144:147], v[178:181], v[110:113]
	v_mfma_f32_16x16x32_bf16 v[102:105], v[152:155], v[178:181], v[102:105]
	v_mfma_f32_16x16x32_bf16 v[92:95], v[144:147], v[186:189], v[92:95]
	v_mfma_f32_16x16x32_bf16 v[84:87], v[152:155], v[186:189], v[84:87]
	v_mfma_f32_16x16x32_bf16 v[76:79], v[144:147], v[194:197], v[76:79]
	v_mfma_f32_16x16x32_bf16 v[68:71], v[152:155], v[194:197], v[68:71]
	v_mfma_f32_16x16x32_bf16 v[126:129], v[148:151], v[174:177], v[126:129]
	v_mfma_f32_16x16x32_bf16 v[118:121], v[156:159], v[174:177], v[118:121]
	v_mfma_f32_16x16x32_bf16 v[110:113], v[148:151], v[182:185], v[110:113]
	v_mfma_f32_16x16x32_bf16 v[102:105], v[156:159], v[182:185], v[102:105]
	v_mfma_f32_16x16x32_bf16 v[92:95], v[148:151], v[190:193], v[92:95]
	v_mfma_f32_16x16x32_bf16 v[84:87], v[156:159], v[190:193], v[84:87]
	v_mfma_f32_16x16x32_bf16 v[76:79], v[148:151], v[198:201], v[76:79]
	v_mfma_f32_16x16x32_bf16 v[68:71], v[156:159], v[198:201], v[68:71]
	s_barrier
	s_setprio 1
	s_add_i32 s64, 0, 0x14000
	s_add_i32 s62, s62, s51
	v_add_u32_e32 v96, s64, v162
	v_lshl_add_u64 v[160:161], s[30:31], 0, v[134:135]
	s_mov_b32 m0, s62
	ds_read_b128 v[202:205], v96
	ds_read_b128 v[208:211], v96 offset:1024
	ds_read_b128 v[212:215], v96 offset:2048
	ds_read_b128 v[216:219], v96 offset:3072
	global_load_lds_dwordx4 v[160:161], off
	v_lshl_add_u64 v[220:221], s[30:31], 0, v[130:131]
	s_add_i32 m0, s62, 0x2000
	s_nop 0
	global_load_lds_dwordx4 v[220:221], off
	s_barrier
	s_setprio 0
	s_waitcnt lgkmcnt(0)
	v_mfma_f32_16x16x32_bf16 v[122:125], v[202:205], v[170:173], v[122:125]
	v_mfma_f32_16x16x32_bf16 v[114:117], v[212:215], v[170:173], v[114:117]
	v_mfma_f32_16x16x32_bf16 v[106:109], v[202:205], v[178:181], v[106:109]
	v_mfma_f32_16x16x32_bf16 v[98:101], v[212:215], v[178:181], v[98:101]
	v_mfma_f32_16x16x32_bf16 v[88:91], v[202:205], v[186:189], v[88:91]
	v_mfma_f32_16x16x32_bf16 v[80:83], v[212:215], v[186:189], v[80:83]
	v_mfma_f32_16x16x32_bf16 v[72:75], v[202:205], v[194:197], v[72:75]
	v_mfma_f32_16x16x32_bf16 v[64:67], v[212:215], v[194:197], v[64:67]
	v_mfma_f32_16x16x32_bf16 v[122:125], v[208:211], v[174:177], v[122:125]
	v_mfma_f32_16x16x32_bf16 v[114:117], v[216:219], v[174:177], v[114:117]
	v_mfma_f32_16x16x32_bf16 v[106:109], v[208:211], v[182:185], v[106:109]
	v_mfma_f32_16x16x32_bf16 v[98:101], v[216:219], v[182:185], v[98:101]
	v_mfma_f32_16x16x32_bf16 v[88:91], v[208:211], v[190:193], v[88:91]
	v_mfma_f32_16x16x32_bf16 v[80:83], v[216:219], v[190:193], v[80:83]
	v_mfma_f32_16x16x32_bf16 v[72:75], v[208:211], v[198:201], v[72:75]
	v_mfma_f32_16x16x32_bf16 v[64:67], v[216:219], v[198:201], v[64:67]
	s_mov_b32 m0, s52
	v_lshl_add_u64 v[222:223], s[48:49], 0, v[136:137]
	s_barrier
	s_setprio 1
	ds_read_b128 v[170:173], v168 offset:16384
	ds_read_b128 v[174:177], v168 offset:17408
	ds_read_b128 v[178:181], v168 offset:18432
	ds_read_b128 v[182:185], v168 offset:19456
	ds_read_b128 v[186:189], v168 offset:20480
	ds_read_b128 v[190:193], v168 offset:21504
	ds_read_b128 v[194:197], v168 offset:22528
	ds_read_b128 v[198:201], v168 offset:23552
	global_load_lds_dwordx4 v[222:223], off
	v_lshl_add_u64 v[224:225], s[48:49], 0, v[132:133]
	s_mov_b32 m0, s53
	s_nop 0
	global_load_lds_dwordx4 v[224:225], off
	s_barrier
	s_setprio 0
	s_waitcnt lgkmcnt(0)
	v_mfma_f32_16x16x32_bf16 v[60:63], v[144:147], v[170:173], v[60:63]
	v_mfma_f32_16x16x32_bf16 v[52:55], v[152:155], v[170:173], v[52:55]
	v_mfma_f32_16x16x32_bf16 v[44:47], v[144:147], v[178:181], v[44:47]
	v_mfma_f32_16x16x32_bf16 v[36:39], v[152:155], v[178:181], v[36:39]
	v_mfma_f32_16x16x32_bf16 v[28:31], v[144:147], v[186:189], v[28:31]
	v_mfma_f32_16x16x32_bf16 v[20:23], v[152:155], v[186:189], v[20:23]
	v_mfma_f32_16x16x32_bf16 v[12:15], v[144:147], v[194:197], v[12:15]
	v_mfma_f32_16x16x32_bf16 v[4:7], v[152:155], v[194:197], v[4:7]
	v_mfma_f32_16x16x32_bf16 v[60:63], v[148:151], v[174:177], v[60:63]
	v_mfma_f32_16x16x32_bf16 v[52:55], v[156:159], v[174:177], v[52:55]
	v_mfma_f32_16x16x32_bf16 v[44:47], v[148:151], v[182:185], v[44:47]
	v_mfma_f32_16x16x32_bf16 v[36:39], v[156:159], v[182:185], v[36:39]
	v_mfma_f32_16x16x32_bf16 v[28:31], v[148:151], v[190:193], v[28:31]
	v_mfma_f32_16x16x32_bf16 v[20:23], v[156:159], v[190:193], v[20:23]
	v_mfma_f32_16x16x32_bf16 v[12:15], v[148:151], v[198:201], v[12:15]
	v_mfma_f32_16x16x32_bf16 v[4:7], v[156:159], v[198:201], v[4:7]
	s_barrier
; #define PG8_STAGE(bufoff, gbase, voff) do { _Pragma("unroll") for (int _i = 0; _i < 2; ++_i) \
;         __builtin_amdgcn_global_load_lds((const unsigned*)((const char*)(gbase) + (voff)[_i]), (PG8_LAS unsigned*)(lds + (bufoff) + ldsw + _i * 8192), 16, 0, 0); } while (0)
; #define PG8_LDA(dst, b, h) do { _Pragma("unroll") for (int m = 0; m < 4; ++m) _Pragma("unroll") for (int k = 0; k < 2; ++k) dst[m][k] = *(const PG8_LAS bf16x8*)(lds + PG8_SA(b, h) + aoff + m * 2048 + k * 1024); } while (0)
; #define PG8_LDB(dst, b, h) do { _Pragma("unroll") for (int n = 0; n < 2; ++n) _Pragma("unroll") for (int k = 0; k < 2; ++k) dst[n][k] = *(const PG8_LAS bf16x8*)(lds + PG8_SB(b, h) + boff + n * 2048 + k * 1024); } while (0)
; #define PG8_MMA(ai, bj, At, Bt) do { __builtin_amdgcn_s_setprio(1); _Pragma("unroll") for (int m = 0; m < 4; ++m) _Pragma("unroll") for (int n = 0; n < 2; ++n) _Pragma("unroll") for (int k = 0; k < 2; ++k) \
;         acc[ai][bj][m][n] = __builtin_amdgcn_mfma_f32_16x16x32_bf16(Bt[n][k], At[m][k], acc[ai][bj][m][n], 0, 0, 0); __builtin_amdgcn_s_setprio(0); } while (0)
; #define PG8_WAIT_V(n) asm volatile("s_waitcnt vmcnt(" #n ")" ::: "memory")
; #define PG8_WAIT_L(n) asm volatile("s_waitcnt lgkmcnt(" #n ")" ::: "memory")
; #define PG8_BAR __builtin_amdgcn_s_barrier()
; #define PG8_SCHED __builtin_amdgcn_sched_barrier(0)
; template <class Epi, class Sched>
; __device__ __forceinline__ void gemm_phase(PG8_LAS unsigned char* lds, const Gemm g, const Sched& S, const Epi& E) {
;     ...
;             PG8_STAGE(PG8_SB(0, 1), b2 + hstep, voffB);
;             PG8_WAIT_V(6); PG8_BAR; PG8_MMA(1, 1, At, B1); PG8_BAR;
;             PG8_LDB(B0, 1, 0); PG8_SCHED; PG8_LDA(At, 1, 0); PG8_STAGE(PG8_SA(0, 1), a2 + hstep, voffA);
;             PG8_WAIT_L(8); PG8_BAR; PG8_WAIT_L(0); PG8_MMA(0, 0, At, B0); PG8_BAR; PG8_SCHED;
;             PG8_LDB(B1, 1, 1); PG8_STAGE(PG8_SB(1, 0), b3, voffB);
;             PG8_BAR; PG8_WAIT_L(0); PG8_MMA(0, 1, At, B1); PG8_BAR;
;             PG8_LDA(At, 1, 1); PG8_STAGE(PG8_SA(1, 0), a3, voffA);
;             PG8_BAR; PG8_WAIT_L(0); PG8_MMA(1, 0, At, B0); PG8_BAR; PG8_SCHED;
	s_setprio 1
	s_add_u32 s62, s30, 0x40000
	s_addc_u32 s63, s31, 0
	s_add_i32 s64, s64, s51
	v_lshl_add_u64 v[144:145], s[62:63], 0, v[134:135]
	s_mov_b32 m0, s64
	s_nop 0
	global_load_lds_dwordx4 v[144:145], off
	v_lshl_add_u64 v[144:145], s[62:63], 0, v[130:131]
	s_add_i32 m0, s64, 0x2000
	s_nop 0
	global_load_lds_dwordx4 v[144:145], off
	s_waitcnt vmcnt(6)
	s_barrier
	s_setprio 0
	v_mfma_f32_16x16x32_bf16 v[56:59], v[202:205], v[170:173], v[56:59]
	v_mfma_f32_16x16x32_bf16 v[48:51], v[212:215], v[170:173], v[48:51]
	v_mfma_f32_16x16x32_bf16 v[40:43], v[202:205], v[178:181], v[40:43]
	v_mfma_f32_16x16x32_bf16 v[32:35], v[212:215], v[178:181], v[32:35]
	v_mfma_f32_16x16x32_bf16 v[24:27], v[202:205], v[186:189], v[24:27]
	v_mfma_f32_16x16x32_bf16 v[16:19], v[212:215], v[186:189], v[16:19]
	v_mfma_f32_16x16x32_bf16 v[8:11], v[202:205], v[194:197], v[8:11]
	v_mfma_f32_16x16x32_bf16 v[0:3], v[212:215], v[194:197], v[0:3]
	v_mfma_f32_16x16x32_bf16 v[56:59], v[208:211], v[174:177], v[56:59]
	v_mfma_f32_16x16x32_bf16 v[48:51], v[216:219], v[174:177], v[48:51]
	v_mfma_f32_16x16x32_bf16 v[40:43], v[208:211], v[182:185], v[40:43]
	v_mfma_f32_16x16x32_bf16 v[32:35], v[216:219], v[182:185], v[32:35]
	v_mfma_f32_16x16x32_bf16 v[24:27], v[208:211], v[190:193], v[24:27]
	v_mfma_f32_16x16x32_bf16 v[16:19], v[216:219], v[190:193], v[16:19]
	v_mfma_f32_16x16x32_bf16 v[8:11], v[208:211], v[198:201], v[8:11]
	v_mfma_f32_16x16x32_bf16 v[0:3], v[216:219], v[198:201], v[0:3]
	s_add_i32 s62, 0, 0x18000
	v_add_u32_e32 v96, s62, v162
	s_barrier
	s_setprio 1
	ds_read_b128 v[144:147], v96
	ds_read_b128 v[148:151], v96 offset:1024
	ds_read_b128 v[152:155], v96 offset:2048
	ds_read_b128 v[156:159], v96 offset:3072
	s_add_u32 s48, s48, 0x40000
	s_addc_u32 s49, s49, 0
	s_mov_b32 m0, s54
	v_lshl_add_u64 v[202:203], s[48:49], 0, v[136:137]
	ds_read_b128 v[170:173], v168 offset:32768
	ds_read_b128 v[174:177], v168 offset:33792
	ds_read_b128 v[178:181], v168 offset:34816
	ds_read_b128 v[182:185], v168 offset:35840
	ds_read_b128 v[186:189], v168 offset:36864
	ds_read_b128 v[190:193], v168 offset:37888
	ds_read_b128 v[194:197], v168 offset:38912
	ds_read_b128 v[198:201], v168 offset:39936
	global_load_lds_dwordx4 v[202:203], off
	v_lshl_add_u64 v[202:203], s[48:49], 0, v[132:133]
	s_mov_b32 m0, s96
	s_nop 0
	global_load_lds_dwordx4 v[202:203], off
	s_waitcnt lgkmcnt(8)
	s_barrier
	s_setprio 0
	s_waitcnt lgkmcnt(0)
	v_mfma_f32_16x16x32_bf16 v[126:129], v[144:147], v[170:173], v[126:129]
	v_mfma_f32_16x16x32_bf16 v[118:121], v[152:155], v[170:173], v[118:121]
	v_mfma_f32_16x16x32_bf16 v[110:113], v[144:147], v[178:181], v[110:113]
	v_mfma_f32_16x16x32_bf16 v[102:105], v[152:155], v[178:181], v[102:105]
	v_mfma_f32_16x16x32_bf16 v[92:95], v[144:147], v[186:189], v[92:95]
	v_mfma_f32_16x16x32_bf16 v[84:87], v[152:155], v[186:189], v[84:87]
	v_mfma_f32_16x16x32_bf16 v[76:79], v[144:147], v[194:197], v[76:79]
	v_mfma_f32_16x16x32_bf16 v[68:71], v[152:155], v[194:197], v[68:71]
	v_mfma_f32_16x16x32_bf16 v[126:129], v[148:151], v[174:177], v[126:129]
	v_mfma_f32_16x16x32_bf16 v[118:121], v[156:159], v[174:177], v[118:121]
	v_mfma_f32_16x16x32_bf16 v[110:113], v[148:151], v[182:185], v[110:113]
	v_mfma_f32_16x16x32_bf16 v[102:105], v[156:159], v[182:185], v[102:105]
	v_mfma_f32_16x16x32_bf16 v[92:95], v[148:151], v[190:193], v[92:95]
	v_mfma_f32_16x16x32_bf16 v[84:87], v[156:159], v[190:193], v[84:87]
	v_mfma_f32_16x16x32_bf16 v[76:79], v[148:151], v[198:201], v[76:79]
	v_mfma_f32_16x16x32_bf16 v[68:71], v[156:159], v[198:201], v[68:71]
	s_barrier
	s_setprio 1
	s_add_i32 s48, 0, 0x1c000
	s_add_i32 s49, s62, s51
	v_add_u32_e32 v96, s48, v162
	v_lshl_add_u64 v[160:161], v[160:161], 0, s[2:3]
	s_mov_b32 m0, s49
	ds_read_b128 v[202:205], v96
	ds_read_b128 v[208:211], v96 offset:1024
	ds_read_b128 v[212:215], v96 offset:2048
	ds_read_b128 v[216:219], v96 offset:3072
	global_load_lds_dwordx4 v[160:161], off
	v_lshl_add_u64 v[160:161], v[220:221], 0, s[2:3]
	s_add_i32 m0, s49, 0x2000
	s_nop 0
	global_load_lds_dwordx4 v[160:161], off
	s_barrier
	s_setprio 0
	s_waitcnt lgkmcnt(0)
	v_mfma_f32_16x16x32_bf16 v[122:125], v[202:205], v[170:173], v[122:125]
	v_mfma_f32_16x16x32_bf16 v[114:117], v[212:215], v[170:173], v[114:117]
	v_mfma_f32_16x16x32_bf16 v[106:109], v[202:205], v[178:181], v[106:109]
	v_mfma_f32_16x16x32_bf16 v[98:101], v[212:215], v[178:181], v[98:101]
	v_mfma_f32_16x16x32_bf16 v[88:91], v[202:205], v[186:189], v[88:91]
	v_mfma_f32_16x16x32_bf16 v[80:83], v[212:215], v[186:189], v[80:83]
	v_mfma_f32_16x16x32_bf16 v[72:75], v[202:205], v[194:197], v[72:75]
	v_mfma_f32_16x16x32_bf16 v[64:67], v[212:215], v[194:197], v[64:67]
	v_mfma_f32_16x16x32_bf16 v[122:125], v[208:211], v[174:177], v[122:125]
	v_mfma_f32_16x16x32_bf16 v[114:117], v[216:219], v[174:177], v[114:117]
	v_mfma_f32_16x16x32_bf16 v[106:109], v[208:211], v[182:185], v[106:109]
	v_mfma_f32_16x16x32_bf16 v[98:101], v[216:219], v[182:185], v[98:101]
	v_mfma_f32_16x16x32_bf16 v[88:91], v[208:211], v[190:193], v[88:91]
	v_mfma_f32_16x16x32_bf16 v[80:83], v[216:219], v[190:193], v[80:83]
	v_mfma_f32_16x16x32_bf16 v[72:75], v[208:211], v[198:201], v[72:75]
	v_mfma_f32_16x16x32_bf16 v[64:67], v[216:219], v[198:201], v[64:67]
	s_mov_b32 m0, s97
	v_lshl_add_u64 v[160:161], v[222:223], 0, s[2:3]
	s_barrier
; #define PG8_STAGE(bufoff, gbase, voff) do { _Pragma("unroll") for (int _i = 0; _i < 2; ++_i) \
;         __builtin_amdgcn_global_load_lds((const unsigned*)((const char*)(gbase) + (voff)[_i]), (PG8_LAS unsigned*)(lds + (bufoff) + ldsw + _i * 8192), 16, 0, 0); } while (0)
; #define PG8_MMA(ai, bj, At, Bt) do { __builtin_amdgcn_s_setprio(1); _Pragma("unroll") for (int m = 0; m < 4; ++m) _Pragma("unroll") for (int n = 0; n < 2; ++n) _Pragma("unroll") for (int k = 0; k < 2; ++k) \
;         acc[ai][bj][m][n] = __builtin_amdgcn_mfma_f32_16x16x32_bf16(Bt[n][k], At[m][k], acc[ai][bj][m][n], 0, 0, 0); __builtin_amdgcn_s_setprio(0); } while (0)
; #define PG8_WAIT_V(n) asm volatile("s_waitcnt vmcnt(" #n ")" ::: "memory")
; #define PG8_WAIT_L(n) asm volatile("s_waitcnt lgkmcnt(" #n ")" ::: "memory")
; #define PG8_BAR __builtin_amdgcn_s_barrier()
; #define PG8_SCHED __builtin_amdgcn_sched_barrier(0)
; template <class Epi, class Sched>
; __device__ __forceinline__ void gemm_phase(PG8_LAS unsigned char* lds, const Gemm g, const Sched& S, const Epi& E) {
;     ...
;             PG8_BAR; PG8_WAIT_L(0); PG8_MMA(1, 0, At, B0); PG8_BAR; PG8_SCHED;
;             PG8_STAGE(PG8_SB(1, 1), b3 + hstep, voffB);
;             PG8_WAIT_V(6); PG8_BAR; PG8_MMA(1, 1, At, B1); PG8_BAR;
;         }
;         if constexpr (!Epi::AFTER_DRAIN) { E(acc, cur, wr, wc, fr, fq); S.done(cur); }
;         if (!has_next) break;
;   DEV void operator()(const f32x4 (&acc)[2][2][4][2], const pg8::Unit& u, int wr, int wc, int fr, int fq) const {
;     ...
;     } else {
; #pragma unroll
;       for (int ai = 0; ai < 2; ++ai)
; #pragma unroll
;         for (int m = 0; m < 4; ++m) {
;           const int row = row0 + ai * 128 + m * 16;
; #pragma unroll
;           for (int bj = 0; bj < 2; ++bj) {
;             const int c = (pn - 10) * 256 + bj * 128 + cl;
;             if (c < 1920) {
;               u32x4 o;
;               o[0] = pk2(acc[ai][bj][m][0][0], acc[ai][bj][m][0][1]); o[1] = pk2(acc[ai][bj][m][0][2], acc[ai][bj][m][0][3]);
;               o[2] = pk2(acc[ai][bj][m][1][0], acc[ai][bj][m][1][1]); o[3] = pk2(acc[ai][bj][m][1][2], acc[ai][bj][m][1][3]);
;               *(u32x4*)(ZRW + (size_t)row * 1920 + c) = o;
;             }
	s_setprio 1
	ds_read_b128 v[170:173], v168 offset:49152
	ds_read_b128 v[174:177], v168 offset:50176
	ds_read_b128 v[178:181], v168 offset:51200
	ds_read_b128 v[182:185], v168 offset:52224
	ds_read_b128 v[186:189], v168 offset:53248
	ds_read_b128 v[190:193], v168 offset:54272
	ds_read_b128 v[194:197], v168 offset:55296
	ds_read_b128 v[198:201], v168 offset:56320
	global_load_lds_dwordx4 v[160:161], off
	v_lshl_add_u64 v[160:161], v[224:225], 0, s[2:3]
	s_mov_b32 m0, s50
	s_nop 0
	global_load_lds_dwordx4 v[160:161], off
	s_barrier
	s_setprio 0
	s_waitcnt lgkmcnt(0)
	v_mfma_f32_16x16x32_bf16 v[60:63], v[144:147], v[170:173], v[60:63]
	v_mfma_f32_16x16x32_bf16 v[52:55], v[152:155], v[170:173], v[52:55]
	v_mfma_f32_16x16x32_bf16 v[44:47], v[144:147], v[178:181], v[44:47]
	v_mfma_f32_16x16x32_bf16 v[36:39], v[152:155], v[178:181], v[36:39]
	v_mfma_f32_16x16x32_bf16 v[28:31], v[144:147], v[186:189], v[28:31]
	v_mfma_f32_16x16x32_bf16 v[20:23], v[152:155], v[186:189], v[20:23]
	v_mfma_f32_16x16x32_bf16 v[12:15], v[144:147], v[194:197], v[12:15]
	v_mfma_f32_16x16x32_bf16 v[4:7], v[152:155], v[194:197], v[4:7]
	v_mfma_f32_16x16x32_bf16 v[60:63], v[148:151], v[174:177], v[60:63]
	v_mfma_f32_16x16x32_bf16 v[52:55], v[156:159], v[174:177], v[52:55]
	v_mfma_f32_16x16x32_bf16 v[44:47], v[148:151], v[182:185], v[44:47]
	v_mfma_f32_16x16x32_bf16 v[36:39], v[156:159], v[182:185], v[36:39]
	v_mfma_f32_16x16x32_bf16 v[28:31], v[148:151], v[190:193], v[28:31]
	v_mfma_f32_16x16x32_bf16 v[20:23], v[156:159], v[190:193], v[20:23]
	v_mfma_f32_16x16x32_bf16 v[12:15], v[148:151], v[198:201], v[12:15]
	v_mfma_f32_16x16x32_bf16 v[4:7], v[156:159], v[198:201], v[4:7]
	s_barrier
	s_setprio 1
	s_add_u32 s30, s30, 0x40080
	s_addc_u32 s31, s31, 0
	s_add_i32 s48, s48, s51
	v_lshl_add_u64 v[144:145], s[30:31], 0, v[134:135]
	s_mov_b32 m0, s48
	s_nop 0
	global_load_lds_dwordx4 v[144:145], off
	v_lshl_add_u64 v[144:145], s[30:31], 0, v[130:131]
	s_add_i32 m0, s48, 0x2000
	s_nop 0
	global_load_lds_dwordx4 v[144:145], off
	s_waitcnt vmcnt(6)
	s_barrier
	s_setprio 0
	v_mfma_f32_16x16x32_bf16 v[56:59], v[202:205], v[170:173], v[56:59]
	v_mfma_f32_16x16x32_bf16 v[48:51], v[212:215], v[170:173], v[48:51]
	v_mfma_f32_16x16x32_bf16 v[40:43], v[202:205], v[178:181], v[40:43]
	v_mfma_f32_16x16x32_bf16 v[32:35], v[212:215], v[178:181], v[32:35]
	v_mfma_f32_16x16x32_bf16 v[24:27], v[202:205], v[186:189], v[24:27]
	v_mfma_f32_16x16x32_bf16 v[16:19], v[212:215], v[186:189], v[16:19]
	v_mfma_f32_16x16x32_bf16 v[8:11], v[202:205], v[194:197], v[8:11]
	v_mfma_f32_16x16x32_bf16 v[0:3], v[212:215], v[194:197], v[0:3]
	v_mfma_f32_16x16x32_bf16 v[56:59], v[208:211], v[174:177], v[56:59]
	v_mfma_f32_16x16x32_bf16 v[48:51], v[216:219], v[174:177], v[48:51]
	v_mfma_f32_16x16x32_bf16 v[40:43], v[208:211], v[182:185], v[40:43]
	v_mfma_f32_16x16x32_bf16 v[32:35], v[216:219], v[182:185], v[32:35]
	v_mfma_f32_16x16x32_bf16 v[24:27], v[208:211], v[190:193], v[24:27]
	v_mfma_f32_16x16x32_bf16 v[16:19], v[216:219], v[190:193], v[16:19]
	v_mfma_f32_16x16x32_bf16 v[8:11], v[208:211], v[198:201], v[8:11]
	v_mfma_f32_16x16x32_bf16 v[0:3], v[216:219], v[198:201], v[0:3]
	s_add_i32 s61, s61, 2
	s_add_u32 s0, s0, 0x100
	s_addc_u32 s1, s1, 0
	s_add_u32 s59, s59, 0x100
	s_addc_u32 s60, s60, 0
	s_cmp_gt_u32 s61, 13
	s_barrier
	s_cbranch_scc0 .LBB0_654
	s_lshl_b32 s41, s56, 8
	s_add_i32 s41, s41, s79
	v_readlane_b32 s60, v255, 32
	v_readlane_b32 s64, v255, 38
	v_or_b32_e32 v144, s41, v139
	s_cmp_gt_i32 s37, 3
	s_mov_b64 s[0:1], -1
	v_readlane_b32 s61, v255, 33
	v_readlane_b32 s65, v255, 39
	s_movk_i32 s56, 0x2000
	s_cbranch_scc0 .LBB0_729
	s_cmp_gt_u32 s37, 7
	s_cbranch_scc0 .LBB0_694
	s_lshl_b32 s43, s37, 8
	s_cmp_lt_u32 s37, 10
	s_cbranch_scc1 .LBB0_691
	s_movk_i32 s0, 0xf00
	v_mad_i64_i32 v[146:147], s[0:1], v144, s0, 0
	v_add_u32_e32 v96, s43, v163
	s_movk_i32 s0, 0x780
	v_cmp_gt_i32_e32 vcc, s0, v96
	v_readlane_b32 s0, v251, 49
	v_readlane_b32 s1, v251, 50
	s_nop 1
	v_lshl_add_u64 v[146:147], s[0:1], 0, v[146:147]
	s_and_saveexec_b64 s[0:1], vcc
	s_cbranch_execz .LBB0_660
	v_cvt_pk_bf16_f32 v148, v126, v127
	v_cvt_pk_bf16_f32 v149, v128, v129
	v_cvt_pk_bf16_f32 v150, v118, v119
	v_cvt_pk_bf16_f32 v151, v120, v121
	v_lshl_add_u64 v[152:153], v[96:97], 1, v[146:147]
	global_store_dwordx4 v[152:153], v[148:151], off
